# peeled first k-iteration of every tile with srcC=0, accumulator clearing (128 v_mov per tile) removed; on top of race fix + S5 fmac chains + gates sqrt
# speedup vs baseline: 1.0241x; 1.0059x over previous
; #define PG8_STAGE(bufoff, gbase, voff) do { _Pragma("unroll") for (int _i = 0; _i < 2; ++_i) \
;         __builtin_amdgcn_global_load_lds((const unsigned*)((const char*)(gbase) + (voff)[_i]), (LAS unsigned*)(lds + (bufoff) + ldsw + _i * 8192), 16, 0, 0); } while (0)
; #define PG8_LDA(dst, b, h) do { _Pragma("unroll") for (int m = 0; m < 4; ++m) _Pragma("unroll") for (int k = 0; k < 2; ++k) dst[m][k] = *(const LAS bf16x8*)(lds + PG8_SA(b, h) + aoff + m * 2048 + k * 1024); } while (0)
; #define PG8_LDB(dst, b, h) do { _Pragma("unroll") for (int n = 0; n < 2; ++n) _Pragma("unroll") for (int k = 0; k < 2; ++k) dst[n][k] = *(const LAS bf16x8*)(lds + PG8_SB(b, h) + boff + n * 2048 + k * 1024); } while (0)
; #define PG8_WAIT_V(n) asm volatile("s_waitcnt vmcnt(" #n ")" ::: "memory")
; #define PG8_WAIT_L(n) asm volatile("s_waitcnt lgkmcnt(" #n ")" ::: "memory")
; #define PG8_BAR __builtin_amdgcn_s_barrier()
; #define PG8_SCHED __builtin_amdgcn_sched_barrier(0)
; template <class Epi>
; __device__ __forceinline__ void gemm_phase(LAS unsigned char* lds, const Gemm g, const StaticOrder& S, const Epi& E) {
;     ...
;         const bool has_next = S.next(ui + 1, nxt);
;         const char* nA = has_next ? (const char*)g.A + (size_t)nxt.pm * tstepA + (size_t)(nxt.pn >> g.a_shift) * g.a_step : cA; const char* nB = has_next ? (const char*)g.Bt + (size_t)nxt.pn * tstepB : cB;
;         for (int t = 0; t < nt; t += 2) {
;             const bool last = (t == nt - 2);
;             const char* a1 = cA + (size_t)(t + 1) * kstep;
;             const char* a2 = last ? nA : cA + (size_t)(t + 2) * kstep; const char* b2 = last ? nB : cB + (size_t)(t + 2) * kstep;
;             const char* a3 = a2 + kstep; const char* b3 = b2 + kstep;
;             PG8_LDB(B0, 0, 0); PG8_SCHED; PG8_LDA(At, 0, 0); PG8_STAGE(PG8_SA(1, 1), a1 + hstepA, voffA);
;             PG8_WAIT_L(8); PG8_BAR; PG8_WAIT_L(0); PG8_MMA(0, 0, At, B0); PG8_BAR; PG8_SCHED;
;             PG8_LDB(B1, 0, 1); PG8_STAGE(PG8_SB(0, 0), b2, voffB);
;             PG8_BAR; PG8_WAIT_L(0); PG8_MMA(0, 1, At, B1); PG8_BAR;
;             PG8_LDA(At, 0, 1); PG8_STAGE(PG8_SA(0, 0), a2, voffA);
;             PG8_BAR; PG8_WAIT_L(0); PG8_MMA(1, 0, At, B0); PG8_BAR; PG8_SCHED;
;             PG8_STAGE(PG8_SB(0, 1), b2 + hstepB, voffB);
;             PG8_WAIT_V(6); PG8_BAR; PG8_MMA(1, 1, At, B1); PG8_BAR;
.LBB0_308:
	s_ashr_i32 s27, s26, 31
	v_cmp_lt_i64_e32 vcc, s[28:29], v[228:229]
	s_lshl_b64 s[28:29], s[26:27], 19
	s_add_u32 s28, s66, s28
	s_addc_u32 s29, s67, s29
	s_and_b64 s[30:31], vcc, exec
	s_cselect_b32 s27, s29, s37
	s_cselect_b32 s75, s28, s36
	s_ashr_i32 s25, s24, 31
	s_lshl_b64 s[30:31], s[24:25], 19
	s_add_u32 s30, s4, s30
	s_addc_u32 s31, s5, s31
	s_and_b64 s[40:41], vcc, exec
	s_cselect_b32 s25, s31, s39
	s_cselect_b32 s76, s30, s38
	s_add_u32 s77, s38, 0x100
	s_addc_u32 s78, s39, 0
	s_mov_b32 s79, -2
	ds_read_b128 v[96:99], v243
	ds_read_b128 v[100:103], v243 offset:1024
	ds_read_b128 v[104:107], v243 offset:2048
	ds_read_b128 v[108:111], v243 offset:3072
	s_add_u32 s38, s36, 0x100
	s_addc_u32 s39, s37, 0
	s_cmp_eq_u32 s79, 12
	s_cselect_b32 s43, s27, s39
	s_cselect_b32 s42, s75, s38
	s_cselect_b32 s41, s25, s78
	s_cselect_b32 s40, s76, s77
	v_lshl_add_u64 v[176:177], s[36:37], 0, v[224:225]
	s_add_i32 m0, s45, 0xc000
	ds_read_b128 v[112:115], v244
	ds_read_b128 v[116:119], v244 offset:1024
	ds_read_b128 v[120:123], v244 offset:2048
	ds_read_b128 v[124:127], v244 offset:3072
	ds_read_b128 v[160:163], v244 offset:4096
	ds_read_b128 v[164:167], v244 offset:5120
	ds_read_b128 v[168:171], v244 offset:6144
	ds_read_b128 v[172:175], v244 offset:7168
	global_load_lds_dwordx4 v[176:177], off
	v_lshl_add_u64 v[176:177], s[36:37], 0, v[226:227]
	s_add_i32 m0, s45, 0xe000
	s_nop 0
	global_load_lds_dwordx4 v[176:177], off
	ds_read_b128 v[176:179], v245
	ds_read_b128 v[180:183], v245 offset:1024
	ds_read_b128 v[184:187], v245 offset:2048
	ds_read_b128 v[188:191], v245 offset:3072
	s_waitcnt lgkmcnt(0)
	s_barrier
	s_setprio 1
	v_mfma_f32_16x16x32_bf16 v[156:159], v[96:99], v[112:115], 0
	v_mfma_f32_16x16x32_bf16 v[60:63], v[104:107], v[112:115], 0
	v_mfma_f32_16x16x32_bf16 v[144:147], v[96:99], v[120:123], 0
	v_mfma_f32_16x16x32_bf16 v[48:51], v[104:107], v[120:123], 0
	v_mfma_f32_16x16x32_bf16 v[136:139], v[96:99], v[160:163], 0
	v_mfma_f32_16x16x32_bf16 v[40:43], v[104:107], v[160:163], 0
	v_mfma_f32_16x16x32_bf16 v[148:151], v[96:99], v[168:171], 0
	v_mfma_f32_16x16x32_bf16 v[52:55], v[104:107], v[168:171], 0
	v_mfma_f32_16x16x32_bf16 v[156:159], v[100:103], v[116:119], v[156:159]
	v_mfma_f32_16x16x32_bf16 v[60:63], v[108:111], v[116:119], v[60:63]
	v_mfma_f32_16x16x32_bf16 v[144:147], v[100:103], v[124:127], v[144:147]
	v_mfma_f32_16x16x32_bf16 v[48:51], v[108:111], v[124:127], v[48:51]
	v_mfma_f32_16x16x32_bf16 v[136:139], v[100:103], v[164:167], v[136:139]
	v_mfma_f32_16x16x32_bf16 v[40:43], v[108:111], v[164:167], v[40:43]
	v_mfma_f32_16x16x32_bf16 v[148:151], v[100:103], v[172:175], v[148:151]
	v_mfma_f32_16x16x32_bf16 v[52:55], v[108:111], v[172:175], v[52:55]
	v_mfma_f32_16x16x32_bf16 v[152:155], v[176:179], v[112:115], 0
	v_mfma_f32_16x16x32_bf16 v[56:59], v[184:187], v[112:115], 0
	v_mfma_f32_16x16x32_bf16 v[36:39], v[184:187], v[120:123], 0
	v_mfma_f32_16x16x32_bf16 v[32:35], v[184:187], v[160:163], 0
	v_mfma_f32_16x16x32_bf16 v[44:47], v[184:187], v[168:171], 0
	v_mfma_f32_16x16x32_bf16 v[152:155], v[180:183], v[116:119], v[152:155]
	v_mfma_f32_16x16x32_bf16 v[56:59], v[188:191], v[116:119], v[56:59]
	v_mfma_f32_16x16x32_bf16 v[112:115], v[176:179], v[120:123], 0
	v_mfma_f32_16x16x32_bf16 v[36:39], v[188:191], v[124:127], v[36:39]
	v_mfma_f32_16x16x32_bf16 v[116:119], v[176:179], v[160:163], 0
	v_mfma_f32_16x16x32_bf16 v[32:35], v[188:191], v[164:167], v[32:35]
	v_mfma_f32_16x16x32_bf16 v[120:123], v[176:179], v[168:171], 0
	v_mfma_f32_16x16x32_bf16 v[44:47], v[188:191], v[172:175], v[44:47]
	v_mfma_f32_16x16x32_bf16 v[112:115], v[180:183], v[124:127], v[112:115]
	v_mfma_f32_16x16x32_bf16 v[116:119], v[180:183], v[164:167], v[116:119]
	v_mfma_f32_16x16x32_bf16 v[120:123], v[180:183], v[172:175], v[120:123]
	s_setprio 0
	s_barrier
	s_nop 1
	ds_read_b128 v[124:127], v244 offset:16384
	ds_read_b128 v[128:131], v244 offset:17408
	ds_read_b128 v[132:135], v244 offset:18432
	ds_read_b128 v[140:143], v244 offset:19456
	ds_read_b128 v[160:163], v244 offset:20480
	ds_read_b128 v[164:167], v244 offset:21504
	ds_read_b128 v[168:171], v244 offset:22528
	ds_read_b128 v[172:175], v244 offset:23552
	s_add_i32 s36, s72, s6
	v_lshl_add_u64 v[196:197], s[40:41], 0, v[214:215]
	s_mov_b32 m0, s36
	s_nop 0
	global_load_lds_dwordx4 v[196:197], off
	v_lshl_add_u64 v[198:199], s[40:41], 0, v[210:211]
	s_add_i32 m0, s36, 0x2000
	s_nop 0
	global_load_lds_dwordx4 v[198:199], off
	s_mov_b32 m0, s45
	v_lshl_add_u64 v[200:201], s[42:43], 0, v[216:217]
	global_load_lds_dwordx4 v[200:201], off
	v_lshl_add_u64 v[202:203], s[42:43], 0, v[212:213]
	s_mov_b32 m0, s46
	s_nop 0
	global_load_lds_dwordx4 v[202:203], off
	s_add_u32 s36, s40, 0x40000
	s_addc_u32 s37, s41, 0
	s_add_i32 s80, s73, s6
	v_lshl_add_u64 v[254:255], s[36:37], 0, v[214:215]
	s_mov_b32 m0, s80
	s_nop 0
	global_load_lds_dwordx4 v[254:255], off
	v_lshl_add_u64 v[254:255], s[36:37], 0, v[210:211]
	s_add_i32 m0, s80, 0x2000
	s_nop 0
	global_load_lds_dwordx4 v[254:255], off
	s_waitcnt vmcnt(6)
	s_waitcnt lgkmcnt(0)
	s_barrier
; #define PG8_STAGE(bufoff, gbase, voff) do { _Pragma("unroll") for (int _i = 0; _i < 2; ++_i) \
;         __builtin_amdgcn_global_load_lds((const unsigned*)((const char*)(gbase) + (voff)[_i]), (LAS unsigned*)(lds + (bufoff) + ldsw + _i * 8192), 16, 0, 0); } while (0)
; #define PG8_LDA(dst, b, h) do { _Pragma("unroll") for (int m = 0; m < 4; ++m) _Pragma("unroll") for (int k = 0; k < 2; ++k) dst[m][k] = *(const LAS bf16x8*)(lds + PG8_SA(b, h) + aoff + m * 2048 + k * 1024); } while (0)
; #define PG8_LDB(dst, b, h) do { _Pragma("unroll") for (int n = 0; n < 2; ++n) _Pragma("unroll") for (int k = 0; k < 2; ++k) dst[n][k] = *(const LAS bf16x8*)(lds + PG8_SB(b, h) + boff + n * 2048 + k * 1024); } while (0)
; #define PG8_MMA(ai, bj, At, Bt) do { __builtin_amdgcn_s_setprio(1); _Pragma("unroll") for (int m = 0; m < 4; ++m) _Pragma("unroll") for (int n = 0; n < 2; ++n) _Pragma("unroll") for (int k = 0; k < 2; ++k) \
;         acc[ai][bj][m][n] = __builtin_amdgcn_mfma_f32_16x16x32_bf16(Bt[n][k], At[m][k], acc[ai][bj][m][n], 0, 0, 0); __builtin_amdgcn_s_setprio(0); } while (0)
; #define PG8_WAIT_V(n) asm volatile("s_waitcnt vmcnt(" #n ")" ::: "memory")
; #define PG8_WAIT_L(n) asm volatile("s_waitcnt lgkmcnt(" #n ")" ::: "memory")
; #define PG8_BAR __builtin_amdgcn_s_barrier()
; #define PG8_SCHED __builtin_amdgcn_sched_barrier(0)
; template <class Epi>
; __device__ __forceinline__ void gemm_phase(LAS unsigned char* lds, const Gemm g, const StaticOrder& S, const Epi& E) {
;     ...
;             PG8_BAR; PG8_WAIT_L(0); PG8_MMA(1, 0, At, B0); PG8_BAR; PG8_SCHED;
;             PG8_STAGE(PG8_SB(0, 1), b2 + hstepB, voffB);
;             PG8_WAIT_V(6); PG8_BAR; PG8_MMA(1, 1, At, B1); PG8_BAR;
;             PG8_LDB(B0, 1, 0); PG8_SCHED; PG8_LDA(At, 1, 0); PG8_STAGE(PG8_SA(0, 1), a2 + hstepA, voffA);
;             PG8_WAIT_L(8); PG8_BAR; PG8_WAIT_L(0); PG8_MMA(0, 0, At, B0); PG8_BAR; PG8_SCHED;
;             PG8_LDB(B1, 1, 1); PG8_STAGE(PG8_SB(1, 0), b3, voffB);
;             PG8_BAR; PG8_WAIT_L(0); PG8_MMA(0, 1, At, B1); PG8_BAR;
	s_setprio 1
	v_mfma_f32_16x16x32_bf16 v[92:95], v[96:99], v[124:127], 0
	v_mfma_f32_16x16x32_bf16 v[28:31], v[104:107], v[124:127], 0
	v_mfma_f32_16x16x32_bf16 v[80:83], v[96:99], v[132:135], 0
	v_mfma_f32_16x16x32_bf16 v[16:19], v[104:107], v[132:135], 0
	v_mfma_f32_16x16x32_bf16 v[76:79], v[96:99], v[160:163], 0
	v_mfma_f32_16x16x32_bf16 v[12:15], v[104:107], v[160:163], 0
	v_mfma_f32_16x16x32_bf16 v[84:87], v[96:99], v[168:171], 0
	v_mfma_f32_16x16x32_bf16 v[20:23], v[104:107], v[168:171], 0
	v_mfma_f32_16x16x32_bf16 v[92:95], v[100:103], v[128:131], v[92:95]
	v_mfma_f32_16x16x32_bf16 v[28:31], v[108:111], v[128:131], v[28:31]
	v_mfma_f32_16x16x32_bf16 v[80:83], v[100:103], v[140:143], v[80:83]
	v_mfma_f32_16x16x32_bf16 v[16:19], v[108:111], v[140:143], v[16:19]
	v_mfma_f32_16x16x32_bf16 v[76:79], v[100:103], v[164:167], v[76:79]
	v_mfma_f32_16x16x32_bf16 v[12:15], v[108:111], v[164:167], v[12:15]
	v_mfma_f32_16x16x32_bf16 v[84:87], v[100:103], v[172:175], v[84:87]
	v_mfma_f32_16x16x32_bf16 v[20:23], v[108:111], v[172:175], v[20:23]
	v_mfma_f32_16x16x32_bf16 v[88:91], v[176:179], v[124:127], 0
	v_mfma_f32_16x16x32_bf16 v[24:27], v[184:187], v[124:127], 0
	v_mfma_f32_16x16x32_bf16 v[68:71], v[176:179], v[132:135], 0
	v_mfma_f32_16x16x32_bf16 v[4:7], v[184:187], v[132:135], 0
	v_mfma_f32_16x16x32_bf16 v[64:67], v[176:179], v[160:163], 0
	v_mfma_f32_16x16x32_bf16 v[0:3], v[184:187], v[160:163], 0
	v_mfma_f32_16x16x32_bf16 v[72:75], v[176:179], v[168:171], 0
	v_mfma_f32_16x16x32_bf16 v[8:11], v[184:187], v[168:171], 0
	v_mfma_f32_16x16x32_bf16 v[88:91], v[180:183], v[128:131], v[88:91]
	v_mfma_f32_16x16x32_bf16 v[24:27], v[188:191], v[128:131], v[24:27]
	v_mfma_f32_16x16x32_bf16 v[68:71], v[180:183], v[140:143], v[68:71]
	v_mfma_f32_16x16x32_bf16 v[4:7], v[188:191], v[140:143], v[4:7]
	v_mfma_f32_16x16x32_bf16 v[64:67], v[180:183], v[164:167], v[64:67]
	v_mfma_f32_16x16x32_bf16 v[0:3], v[188:191], v[164:167], v[0:3]
	v_mfma_f32_16x16x32_bf16 v[72:75], v[180:183], v[172:175], v[72:75]
	v_mfma_f32_16x16x32_bf16 v[8:11], v[188:191], v[172:175], v[8:11]
	s_setprio 0
	s_add_i32 s80, 0, 0x18000
	v_add_u32_e32 v108, s80, v235
	s_barrier
	ds_read_b128 v[96:99], v108
	ds_read_b128 v[100:103], v108 offset:1024
	ds_read_b128 v[104:107], v108 offset:2048
	ds_read_b128 v[108:111], v108 offset:3072
	s_add_u32 s36, s42, 0x40000
	s_addc_u32 s37, s43, 0
	s_mov_b32 m0, s47
	v_lshl_add_u64 v[132:133], s[36:37], 0, v[216:217]
	ds_read_b128 v[124:127], v244 offset:32768
	ds_read_b128 v[128:131], v244 offset:33792
	ds_read_b128 v[140:143], v244 offset:34816
	ds_read_b128 v[160:163], v244 offset:35840
	ds_read_b128 v[164:167], v244 offset:36864
	ds_read_b128 v[168:171], v244 offset:37888
	ds_read_b128 v[172:175], v244 offset:38912
	ds_read_b128 v[176:179], v244 offset:39936
	global_load_lds_dwordx4 v[132:133], off
	v_lshl_add_u64 v[132:133], s[36:37], 0, v[212:213]
	s_mov_b32 m0, s48
	s_nop 0
	global_load_lds_dwordx4 v[132:133], off
	s_add_i32 s42, 0, 0x1c000
	v_add_u32_e32 v132, s42, v235
	ds_read_b128 v[180:183], v132
	ds_read_b128 v[184:187], v132 offset:1024
	ds_read_b128 v[188:191], v132 offset:2048
	ds_read_b128 v[192:195], v132 offset:3072
	s_waitcnt lgkmcnt(0)
	s_barrier
	s_setprio 1
	v_mfma_f32_16x16x32_bf16 v[132:135], v[96:99], v[124:127], v[156:159]
	v_mfma_f32_16x16x32_bf16 v[156:159], v[100:103], v[128:131], v[132:135]
	v_mfma_f32_16x16x32_bf16 v[132:135], v[96:99], v[140:143], v[144:147]
	v_mfma_f32_16x16x32_bf16 v[144:147], v[100:103], v[160:163], v[132:135]
	v_mfma_f32_16x16x32_bf16 v[132:135], v[96:99], v[164:167], v[136:139]
	v_mfma_f32_16x16x32_bf16 v[60:63], v[104:107], v[124:127], v[60:63]
	v_mfma_f32_16x16x32_bf16 v[48:51], v[104:107], v[140:143], v[48:51]
	v_mfma_f32_16x16x32_bf16 v[136:139], v[100:103], v[168:171], v[132:135]
	v_mfma_f32_16x16x32_bf16 v[40:43], v[104:107], v[164:167], v[40:43]
	v_mfma_f32_16x16x32_bf16 v[132:135], v[96:99], v[172:175], v[148:151]
	v_mfma_f32_16x16x32_bf16 v[52:55], v[104:107], v[172:175], v[52:55]
	v_mfma_f32_16x16x32_bf16 v[60:63], v[108:111], v[128:131], v[60:63]
	v_mfma_f32_16x16x32_bf16 v[48:51], v[108:111], v[160:163], v[48:51]
	v_mfma_f32_16x16x32_bf16 v[40:43], v[108:111], v[168:171], v[40:43]
	v_mfma_f32_16x16x32_bf16 v[148:151], v[100:103], v[176:179], v[132:135]
	v_mfma_f32_16x16x32_bf16 v[52:55], v[108:111], v[176:179], v[52:55]
	v_mfma_f32_16x16x32_bf16 v[132:135], v[180:183], v[124:127], v[152:155]
	v_mfma_f32_16x16x32_bf16 v[112:115], v[180:183], v[140:143], v[112:115]
	v_mfma_f32_16x16x32_bf16 v[152:155], v[184:187], v[128:131], v[132:135]
	v_mfma_f32_16x16x32_bf16 v[56:59], v[188:191], v[124:127], v[56:59]
	v_mfma_f32_16x16x32_bf16 v[132:135], v[184:187], v[160:163], v[112:115]
	v_mfma_f32_16x16x32_bf16 v[112:115], v[180:183], v[164:167], v[116:119]
	v_mfma_f32_16x16x32_bf16 v[56:59], v[192:195], v[128:131], v[56:59]
	v_mfma_f32_16x16x32_bf16 v[36:39], v[188:191], v[140:143], v[36:39]
	v_mfma_f32_16x16x32_bf16 v[128:131], v[184:187], v[168:171], v[112:115]
	v_mfma_f32_16x16x32_bf16 v[32:35], v[188:191], v[164:167], v[32:35]
	v_mfma_f32_16x16x32_bf16 v[112:115], v[180:183], v[172:175], v[120:123]
	v_mfma_f32_16x16x32_bf16 v[44:47], v[188:191], v[172:175], v[44:47]
	v_mfma_f32_16x16x32_bf16 v[36:39], v[192:195], v[160:163], v[36:39]
	v_mfma_f32_16x16x32_bf16 v[32:35], v[192:195], v[168:171], v[32:35]
	v_mfma_f32_16x16x32_bf16 v[140:143], v[184:187], v[176:179], v[112:115]
	v_mfma_f32_16x16x32_bf16 v[44:47], v[192:195], v[176:179], v[44:47]
	s_setprio 0
	s_barrier
; #define PG8_STAGE(bufoff, gbase, voff) do { _Pragma("unroll") for (int _i = 0; _i < 2; ++_i) \
;         __builtin_amdgcn_global_load_lds((const unsigned*)((const char*)(gbase) + (voff)[_i]), (LAS unsigned*)(lds + (bufoff) + ldsw + _i * 8192), 16, 0, 0); } while (0)
; #define PG8_LDA(dst, b, h) do { _Pragma("unroll") for (int m = 0; m < 4; ++m) _Pragma("unroll") for (int k = 0; k < 2; ++k) dst[m][k] = *(const LAS bf16x8*)(lds + PG8_SA(b, h) + aoff + m * 2048 + k * 1024); } while (0)
; #define PG8_LDB(dst, b, h) do { _Pragma("unroll") for (int n = 0; n < 2; ++n) _Pragma("unroll") for (int k = 0; k < 2; ++k) dst[n][k] = *(const LAS bf16x8*)(lds + PG8_SB(b, h) + boff + n * 2048 + k * 1024); } while (0)
; #define PG8_MMA(ai, bj, At, Bt) do { __builtin_amdgcn_s_setprio(1); _Pragma("unroll") for (int m = 0; m < 4; ++m) _Pragma("unroll") for (int n = 0; n < 2; ++n) _Pragma("unroll") for (int k = 0; k < 2; ++k) \
;         acc[ai][bj][m][n] = __builtin_amdgcn_mfma_f32_16x16x32_bf16(Bt[n][k], At[m][k], acc[ai][bj][m][n], 0, 0, 0); __builtin_amdgcn_s_setprio(0); } while (0)
; #define PG8_WAIT_V(n) asm volatile("s_waitcnt vmcnt(" #n ")" ::: "memory")
; #define PG8_WAIT_L(n) asm volatile("s_waitcnt lgkmcnt(" #n ")" ::: "memory")
; #define PG8_BAR __builtin_amdgcn_s_barrier()
; #define PG8_SCHED __builtin_amdgcn_sched_barrier(0)
; template <class Epi>
; __device__ __forceinline__ void gemm_phase(LAS unsigned char* lds, const Gemm g, const StaticOrder& S, const Epi& E) {
;     ...
;             PG8_LDB(B1, 1, 1); PG8_STAGE(PG8_SB(1, 0), b3, voffB);
;             PG8_BAR; PG8_WAIT_L(0); PG8_MMA(0, 1, At, B1); PG8_BAR;
;             PG8_LDA(At, 1, 1); PG8_STAGE(PG8_SA(1, 0), a3, voffA);
;             PG8_BAR; PG8_WAIT_L(0); PG8_MMA(1, 0, At, B0); PG8_BAR; PG8_SCHED;
;             PG8_STAGE(PG8_SB(1, 1), b3 + hstepB, voffB);
;             PG8_WAIT_V(6); PG8_BAR; PG8_MMA(1, 1, At, B1); PG8_BAR;
	s_nop 1
	ds_read_b128 v[112:115], v244 offset:49152
	ds_read_b128 v[116:119], v244 offset:50176
	ds_read_b128 v[120:123], v244 offset:51200
	ds_read_b128 v[124:127], v244 offset:52224
	ds_read_b128 v[160:163], v244 offset:53248
	ds_read_b128 v[164:167], v244 offset:54272
	ds_read_b128 v[168:171], v244 offset:55296
	ds_read_b128 v[172:175], v244 offset:56320
	s_add_i32 s36, s80, s6
	v_lshl_add_u64 v[254:255], v[196:197], 0, s[14:15]
	s_mov_b32 m0, s36
	s_nop 0
	global_load_lds_dwordx4 v[254:255], off
	v_lshl_add_u64 v[254:255], v[198:199], 0, s[14:15]
	s_add_i32 m0, s36, 0x2000
	s_nop 0
	global_load_lds_dwordx4 v[254:255], off
	s_mov_b32 m0, s68
	v_lshl_add_u64 v[254:255], v[200:201], 0, s[14:15]
	global_load_lds_dwordx4 v[254:255], off
	v_lshl_add_u64 v[254:255], v[202:203], 0, s[14:15]
	s_mov_b32 m0, s69
	s_nop 0
	global_load_lds_dwordx4 v[254:255], off
	s_add_u32 s36, s40, 0x40080
	s_addc_u32 s37, s41, 0
	s_add_i32 s40, s42, s6
	v_lshl_add_u64 v[254:255], s[36:37], 0, v[214:215]
	s_mov_b32 m0, s40
	s_nop 0
	global_load_lds_dwordx4 v[254:255], off
	v_lshl_add_u64 v[254:255], s[36:37], 0, v[210:211]
	s_add_i32 m0, s40, 0x2000
	s_nop 0
	global_load_lds_dwordx4 v[254:255], off
	s_waitcnt vmcnt(6)
	s_waitcnt lgkmcnt(0)
	s_barrier
	s_setprio 1
	v_mfma_f32_16x16x32_bf16 v[92:95], v[96:99], v[112:115], v[92:95]
	v_mfma_f32_16x16x32_bf16 v[28:31], v[104:107], v[112:115], v[28:31]
	v_mfma_f32_16x16x32_bf16 v[80:83], v[96:99], v[120:123], v[80:83]
	v_mfma_f32_16x16x32_bf16 v[16:19], v[104:107], v[120:123], v[16:19]
	v_mfma_f32_16x16x32_bf16 v[76:79], v[96:99], v[160:163], v[76:79]
	v_mfma_f32_16x16x32_bf16 v[12:15], v[104:107], v[160:163], v[12:15]
	v_mfma_f32_16x16x32_bf16 v[84:87], v[96:99], v[168:171], v[84:87]
	v_mfma_f32_16x16x32_bf16 v[20:23], v[104:107], v[168:171], v[20:23]
	v_mfma_f32_16x16x32_bf16 v[92:95], v[100:103], v[116:119], v[92:95]
	v_mfma_f32_16x16x32_bf16 v[28:31], v[108:111], v[116:119], v[28:31]
	v_mfma_f32_16x16x32_bf16 v[80:83], v[100:103], v[124:127], v[80:83]
	v_mfma_f32_16x16x32_bf16 v[16:19], v[108:111], v[124:127], v[16:19]
	v_mfma_f32_16x16x32_bf16 v[76:79], v[100:103], v[164:167], v[76:79]
	v_mfma_f32_16x16x32_bf16 v[12:15], v[108:111], v[164:167], v[12:15]
	v_mfma_f32_16x16x32_bf16 v[84:87], v[100:103], v[172:175], v[84:87]
	v_mfma_f32_16x16x32_bf16 v[20:23], v[108:111], v[172:175], v[20:23]
	v_mfma_f32_16x16x32_bf16 v[88:91], v[180:183], v[112:115], v[88:91]
	v_mfma_f32_16x16x32_bf16 v[24:27], v[188:191], v[112:115], v[24:27]
	v_mfma_f32_16x16x32_bf16 v[68:71], v[180:183], v[120:123], v[68:71]
	v_mfma_f32_16x16x32_bf16 v[4:7], v[188:191], v[120:123], v[4:7]
	v_mfma_f32_16x16x32_bf16 v[64:67], v[180:183], v[160:163], v[64:67]
	v_mfma_f32_16x16x32_bf16 v[0:3], v[188:191], v[160:163], v[0:3]
	v_mfma_f32_16x16x32_bf16 v[72:75], v[180:183], v[168:171], v[72:75]
	v_mfma_f32_16x16x32_bf16 v[8:11], v[188:191], v[168:171], v[8:11]
	v_mfma_f32_16x16x32_bf16 v[88:91], v[184:187], v[116:119], v[88:91]
	v_mfma_f32_16x16x32_bf16 v[24:27], v[192:195], v[116:119], v[24:27]
	v_mfma_f32_16x16x32_bf16 v[68:71], v[184:187], v[124:127], v[68:71]
	v_mfma_f32_16x16x32_bf16 v[4:7], v[192:195], v[124:127], v[4:7]
	v_mfma_f32_16x16x32_bf16 v[64:67], v[184:187], v[164:167], v[64:67]
	v_mfma_f32_16x16x32_bf16 v[0:3], v[192:195], v[164:167], v[0:3]
	v_mfma_f32_16x16x32_bf16 v[72:75], v[184:187], v[172:175], v[72:75]
	v_mfma_f32_16x16x32_bf16 v[8:11], v[192:195], v[172:175], v[8:11]
	s_setprio 0
	s_add_i32 s79, s79, 2
	s_add_u32 s77, s77, 0x100
	s_addc_u32 s78, s78, 0
	s_cmp_gt_u32 s79, 13
	s_mov_b64 s[36:37], s[38:39]
	s_barrier

; #define PG8_STAGE(bufoff, gbase, voff) do { _Pragma("unroll") for (int _i = 0; _i < 2; ++_i) \
;         __builtin_amdgcn_global_load_lds((const unsigned*)((const char*)(gbase) + (voff)[_i]), (LAS unsigned*)(lds + (bufoff) + ldsw + _i * 8192), 16, 0, 0); } while (0)
; #define PG8_LDA(dst, b, h) do { _Pragma("unroll") for (int m = 0; m < 4; ++m) _Pragma("unroll") for (int k = 0; k < 2; ++k) dst[m][k] = *(const LAS bf16x8*)(lds + PG8_SA(b, h) + aoff + m * 2048 + k * 1024); } while (0)
; #define PG8_LDB(dst, b, h) do { _Pragma("unroll") for (int n = 0; n < 2; ++n) _Pragma("unroll") for (int k = 0; k < 2; ++k) dst[n][k] = *(const LAS bf16x8*)(lds + PG8_SB(b, h) + boff + n * 2048 + k * 1024); } while (0)
; #define PG8_MMA(ai, bj, At, Bt) do { __builtin_amdgcn_s_setprio(1); _Pragma("unroll") for (int m = 0; m < 4; ++m) _Pragma("unroll") for (int n = 0; n < 2; ++n) _Pragma("unroll") for (int k = 0; k < 2; ++k) \
;         acc[ai][bj][m][n] = __builtin_amdgcn_mfma_f32_16x16x32_bf16(Bt[n][k], At[m][k], acc[ai][bj][m][n], 0, 0, 0); __builtin_amdgcn_s_setprio(0); } while (0)
; #define PG8_WAIT_V(n) asm volatile("s_waitcnt vmcnt(" #n ")" ::: "memory")
; #define PG8_WAIT_L(n) asm volatile("s_waitcnt lgkmcnt(" #n ")" ::: "memory")
; template <class Epi>
; __device__ __forceinline__ void gemm_phase(LAS unsigned char* lds, const Gemm g, const StaticOrder& S, const Epi& E) {
;     ...
;         for (int t = 0; t < nt; t += 2) {
;             const bool last = (t == nt - 2);
;             const char* a1 = cA + (size_t)(t + 1) * kstep;
;             const char* a2 = last ? nA : cA + (size_t)(t + 2) * kstep; const char* b2 = last ? nB : cB + (size_t)(t + 2) * kstep;
;             const char* a3 = a2 + kstep; const char* b3 = b2 + kstep;
;             PG8_LDB(B0, 0, 0); PG8_SCHED; PG8_LDA(At, 0, 0); PG8_STAGE(PG8_SA(1, 1), a1 + hstepA, voffA);
;             PG8_WAIT_L(8); PG8_BAR; PG8_WAIT_L(0); PG8_MMA(0, 0, At, B0); PG8_BAR; PG8_SCHED;
;             PG8_LDB(B1, 0, 1); PG8_STAGE(PG8_SB(0, 0), b2, voffB);
;             PG8_BAR; PG8_WAIT_L(0); PG8_MMA(0, 1, At, B1); PG8_BAR;
;             PG8_LDA(At, 0, 1); PG8_STAGE(PG8_SA(0, 0), a2, voffA);
;             PG8_BAR; PG8_WAIT_L(0); PG8_MMA(1, 0, At, B0); PG8_BAR; PG8_SCHED;
;             PG8_STAGE(PG8_SB(0, 1), b2 + hstepB, voffB);
;             PG8_WAIT_V(6); PG8_BAR; PG8_MMA(1, 1, At, B1); PG8_BAR;
.LBB0_410:
	s_add_u32 s49, s28, 0x100
	s_addc_u32 s63, s29, 0
	s_mov_b32 s68, -2
	ds_read_b128 v[140:143], v149
	ds_read_b128 v[152:155], v149 offset:1024
	ds_read_b128 v[156:159], v149 offset:2048
	ds_read_b128 v[160:163], v149 offset:3072
	s_add_u32 s28, s26, 0x100
	s_addc_u32 s29, s27, 0
	s_cmp_eq_u32 s68, 40
	s_cselect_b32 s35, s11, s29
	s_cselect_b32 s34, s10, s28
	s_cselect_b32 s31, s13, s63
	s_cselect_b32 s30, s12, s49
	v_lshl_add_u64 v[144:145], s[26:27], 0, v[132:133]
	s_add_i32 m0, s36, 0xc000
	ds_read_b128 v[164:167], v150
	ds_read_b128 v[168:171], v150 offset:1024
	ds_read_b128 v[172:175], v150 offset:2048
	ds_read_b128 v[176:179], v150 offset:3072
	ds_read_b128 v[180:183], v150 offset:4096
	ds_read_b128 v[184:187], v150 offset:5120
	ds_read_b128 v[188:191], v150 offset:6144
	ds_read_b128 v[192:195], v150 offset:7168
	global_load_lds_dwordx4 v[144:145], off
	v_lshl_add_u64 v[144:145], s[26:27], 0, v[134:135]
	s_add_i32 m0, s36, 0xe000
	s_nop 0
	global_load_lds_dwordx4 v[144:145], off
	ds_read_b128 v[196:199], v151
	ds_read_b128 v[200:203], v151 offset:1024
	ds_read_b128 v[204:207], v151 offset:2048
	ds_read_b128 v[208:211], v151 offset:3072
	s_waitcnt lgkmcnt(0)
	s_barrier
	s_setprio 1
	v_mfma_f32_16x16x32_bf16 v[124:127], v[140:143], v[164:167], 0
	v_mfma_f32_16x16x32_bf16 v[120:123], v[156:159], v[164:167], 0
	v_mfma_f32_16x16x32_bf16 v[112:115], v[140:143], v[172:175], 0
	v_mfma_f32_16x16x32_bf16 v[104:107], v[156:159], v[172:175], 0
	v_mfma_f32_16x16x32_bf16 v[92:95], v[140:143], v[180:183], 0
	v_mfma_f32_16x16x32_bf16 v[88:91], v[156:159], v[180:183], 0
	v_mfma_f32_16x16x32_bf16 v[80:83], v[140:143], v[188:191], 0
	v_mfma_f32_16x16x32_bf16 v[72:75], v[156:159], v[188:191], 0
	v_mfma_f32_16x16x32_bf16 v[124:127], v[152:155], v[168:171], v[124:127]
	v_mfma_f32_16x16x32_bf16 v[120:123], v[160:163], v[168:171], v[120:123]
	v_mfma_f32_16x16x32_bf16 v[112:115], v[152:155], v[176:179], v[112:115]
	v_mfma_f32_16x16x32_bf16 v[104:107], v[160:163], v[176:179], v[104:107]
	v_mfma_f32_16x16x32_bf16 v[92:95], v[152:155], v[184:187], v[92:95]
	v_mfma_f32_16x16x32_bf16 v[88:91], v[160:163], v[184:187], v[88:91]
	v_mfma_f32_16x16x32_bf16 v[80:83], v[152:155], v[192:195], v[80:83]
	v_mfma_f32_16x16x32_bf16 v[72:75], v[160:163], v[192:195], v[72:75]
	v_mfma_f32_16x16x32_bf16 v[116:119], v[196:199], v[164:167], 0
	v_mfma_f32_16x16x32_bf16 v[108:111], v[204:207], v[164:167], 0
	v_mfma_f32_16x16x32_bf16 v[100:103], v[196:199], v[172:175], 0
	v_mfma_f32_16x16x32_bf16 v[96:99], v[204:207], v[172:175], 0
	v_mfma_f32_16x16x32_bf16 v[84:87], v[196:199], v[180:183], 0
	v_mfma_f32_16x16x32_bf16 v[76:79], v[204:207], v[180:183], 0
	v_mfma_f32_16x16x32_bf16 v[68:71], v[196:199], v[188:191], 0
	v_mfma_f32_16x16x32_bf16 v[64:67], v[204:207], v[188:191], 0
	v_mfma_f32_16x16x32_bf16 v[116:119], v[200:203], v[168:171], v[116:119]
	v_mfma_f32_16x16x32_bf16 v[108:111], v[208:211], v[168:171], v[108:111]
	v_mfma_f32_16x16x32_bf16 v[100:103], v[200:203], v[176:179], v[100:103]
	v_mfma_f32_16x16x32_bf16 v[96:99], v[208:211], v[176:179], v[96:99]
	v_mfma_f32_16x16x32_bf16 v[84:87], v[200:203], v[184:187], v[84:87]
	v_mfma_f32_16x16x32_bf16 v[76:79], v[208:211], v[184:187], v[76:79]
	v_mfma_f32_16x16x32_bf16 v[68:71], v[200:203], v[192:195], v[68:71]
	v_mfma_f32_16x16x32_bf16 v[64:67], v[208:211], v[192:195], v[64:67]
	s_setprio 0
	s_barrier
	s_nop 1
	ds_read_b128 v[164:167], v150 offset:16384
	ds_read_b128 v[168:171], v150 offset:17408
	ds_read_b128 v[172:175], v150 offset:18432
	ds_read_b128 v[176:179], v150 offset:19456
	ds_read_b128 v[180:183], v150 offset:20480
	ds_read_b128 v[184:187], v150 offset:21504
	ds_read_b128 v[188:191], v150 offset:22528
	ds_read_b128 v[192:195], v150 offset:23552
	s_add_i32 s26, s43, s7
	v_lshl_add_u64 v[144:145], s[30:31], 0, v[128:129]
	s_mov_b32 m0, s26
	s_nop 0
	global_load_lds_dwordx4 v[144:145], off
	v_lshl_add_u64 v[212:213], s[30:31], 0, v[130:131]
	s_add_i32 m0, s26, 0x2000
	s_nop 0
	global_load_lds_dwordx4 v[212:213], off
	s_mov_b32 m0, s36
	v_lshl_add_u64 v[214:215], s[34:35], 0, v[128:129]
	global_load_lds_dwordx4 v[214:215], off
	v_lshl_add_u64 v[216:217], s[34:35], 0, v[130:131]
	s_mov_b32 m0, s37
	s_nop 0
	global_load_lds_dwordx4 v[216:217], off
	s_add_u32 s26, s30, 0xb0000
	s_addc_u32 s27, s31, 0
	s_add_i32 s69, s44, s7
	v_lshl_add_u64 v[254:255], s[26:27], 0, v[128:129]
	s_mov_b32 m0, s69
	s_nop 0
	global_load_lds_dwordx4 v[254:255], off
	v_lshl_add_u64 v[254:255], s[26:27], 0, v[130:131]
	s_add_i32 m0, s69, 0x2000
	s_nop 0
	global_load_lds_dwordx4 v[254:255], off
	s_waitcnt vmcnt(6)
	s_waitcnt lgkmcnt(0)
	s_barrier
; #define PG8_STAGE(bufoff, gbase, voff) do { _Pragma("unroll") for (int _i = 0; _i < 2; ++_i) \
;         __builtin_amdgcn_global_load_lds((const unsigned*)((const char*)(gbase) + (voff)[_i]), (LAS unsigned*)(lds + (bufoff) + ldsw + _i * 8192), 16, 0, 0); } while (0)
; #define PG8_LDA(dst, b, h) do { _Pragma("unroll") for (int m = 0; m < 4; ++m) _Pragma("unroll") for (int k = 0; k < 2; ++k) dst[m][k] = *(const LAS bf16x8*)(lds + PG8_SA(b, h) + aoff + m * 2048 + k * 1024); } while (0)
; #define PG8_LDB(dst, b, h) do { _Pragma("unroll") for (int n = 0; n < 2; ++n) _Pragma("unroll") for (int k = 0; k < 2; ++k) dst[n][k] = *(const LAS bf16x8*)(lds + PG8_SB(b, h) + boff + n * 2048 + k * 1024); } while (0)
; #define PG8_MMA(ai, bj, At, Bt) do { __builtin_amdgcn_s_setprio(1); _Pragma("unroll") for (int m = 0; m < 4; ++m) _Pragma("unroll") for (int n = 0; n < 2; ++n) _Pragma("unroll") for (int k = 0; k < 2; ++k) \
;         acc[ai][bj][m][n] = __builtin_amdgcn_mfma_f32_16x16x32_bf16(Bt[n][k], At[m][k], acc[ai][bj][m][n], 0, 0, 0); __builtin_amdgcn_s_setprio(0); } while (0)
; #define PG8_WAIT_V(n) asm volatile("s_waitcnt vmcnt(" #n ")" ::: "memory")
; #define PG8_WAIT_L(n) asm volatile("s_waitcnt lgkmcnt(" #n ")" ::: "memory")
; #define PG8_BAR __builtin_amdgcn_s_barrier()
; #define PG8_SCHED __builtin_amdgcn_sched_barrier(0)
; template <class Epi>
; __device__ __forceinline__ void gemm_phase(LAS unsigned char* lds, const Gemm g, const StaticOrder& S, const Epi& E) {
;     ...
;             PG8_BAR; PG8_WAIT_L(0); PG8_MMA(1, 0, At, B0); PG8_BAR; PG8_SCHED;
;             PG8_STAGE(PG8_SB(0, 1), b2 + hstepB, voffB);
;             PG8_WAIT_V(6); PG8_BAR; PG8_MMA(1, 1, At, B1); PG8_BAR;
;             PG8_LDB(B0, 1, 0); PG8_SCHED; PG8_LDA(At, 1, 0); PG8_STAGE(PG8_SA(0, 1), a2 + hstepA, voffA);
;             PG8_WAIT_L(8); PG8_BAR; PG8_WAIT_L(0); PG8_MMA(0, 0, At, B0); PG8_BAR; PG8_SCHED;
;             PG8_LDB(B1, 1, 1); PG8_STAGE(PG8_SB(1, 0), b3, voffB);
;             PG8_BAR; PG8_WAIT_L(0); PG8_MMA(0, 1, At, B1); PG8_BAR;
	s_setprio 1
	v_mfma_f32_16x16x32_bf16 v[60:63], v[140:143], v[164:167], 0
	v_mfma_f32_16x16x32_bf16 v[56:59], v[156:159], v[164:167], 0
	v_mfma_f32_16x16x32_bf16 v[48:51], v[140:143], v[172:175], 0
	v_mfma_f32_16x16x32_bf16 v[40:43], v[156:159], v[172:175], 0
	v_mfma_f32_16x16x32_bf16 v[28:31], v[140:143], v[180:183], 0
	v_mfma_f32_16x16x32_bf16 v[24:27], v[156:159], v[180:183], 0
	v_mfma_f32_16x16x32_bf16 v[16:19], v[140:143], v[188:191], 0
	v_mfma_f32_16x16x32_bf16 v[8:11], v[156:159], v[188:191], 0
	v_mfma_f32_16x16x32_bf16 v[60:63], v[152:155], v[168:171], v[60:63]
	v_mfma_f32_16x16x32_bf16 v[56:59], v[160:163], v[168:171], v[56:59]
	v_mfma_f32_16x16x32_bf16 v[48:51], v[152:155], v[176:179], v[48:51]
	v_mfma_f32_16x16x32_bf16 v[40:43], v[160:163], v[176:179], v[40:43]
	v_mfma_f32_16x16x32_bf16 v[28:31], v[152:155], v[184:187], v[28:31]
	v_mfma_f32_16x16x32_bf16 v[24:27], v[160:163], v[184:187], v[24:27]
	v_mfma_f32_16x16x32_bf16 v[16:19], v[152:155], v[192:195], v[16:19]
	v_mfma_f32_16x16x32_bf16 v[8:11], v[160:163], v[192:195], v[8:11]
	v_mfma_f32_16x16x32_bf16 v[52:55], v[196:199], v[164:167], 0
	v_mfma_f32_16x16x32_bf16 v[44:47], v[204:207], v[164:167], 0
	v_mfma_f32_16x16x32_bf16 v[36:39], v[196:199], v[172:175], 0
	v_mfma_f32_16x16x32_bf16 v[32:35], v[204:207], v[172:175], 0
	v_mfma_f32_16x16x32_bf16 v[20:23], v[196:199], v[180:183], 0
	v_mfma_f32_16x16x32_bf16 v[12:15], v[204:207], v[180:183], 0
	v_mfma_f32_16x16x32_bf16 v[4:7], v[196:199], v[188:191], 0
	v_mfma_f32_16x16x32_bf16 v[0:3], v[204:207], v[188:191], 0
	v_mfma_f32_16x16x32_bf16 v[52:55], v[200:203], v[168:171], v[52:55]
	v_mfma_f32_16x16x32_bf16 v[44:47], v[208:211], v[168:171], v[44:47]
	v_mfma_f32_16x16x32_bf16 v[36:39], v[200:203], v[176:179], v[36:39]
	v_mfma_f32_16x16x32_bf16 v[32:35], v[208:211], v[176:179], v[32:35]
	v_mfma_f32_16x16x32_bf16 v[20:23], v[200:203], v[184:187], v[20:23]
	v_mfma_f32_16x16x32_bf16 v[12:15], v[208:211], v[184:187], v[12:15]
	v_mfma_f32_16x16x32_bf16 v[4:7], v[200:203], v[192:195], v[4:7]
	v_mfma_f32_16x16x32_bf16 v[0:3], v[208:211], v[192:195], v[0:3]
	s_setprio 0
	s_add_i32 s69, 0, 0x18000
	v_add_u32_e32 v160, s69, v147
	s_barrier
	ds_read_b128 v[140:143], v160
	ds_read_b128 v[152:155], v160 offset:1024
	ds_read_b128 v[156:159], v160 offset:2048
	ds_read_b128 v[160:163], v160 offset:3072
	s_add_u32 s26, s34, 0xb0000
	s_addc_u32 s27, s35, 0
	s_mov_b32 m0, s38
	v_lshl_add_u64 v[196:197], s[26:27], 0, v[128:129]
	ds_read_b128 v[164:167], v150 offset:32768
	ds_read_b128 v[168:171], v150 offset:33792
	ds_read_b128 v[172:175], v150 offset:34816
	ds_read_b128 v[176:179], v150 offset:35840
	ds_read_b128 v[180:183], v150 offset:36864
	ds_read_b128 v[184:187], v150 offset:37888
	ds_read_b128 v[188:191], v150 offset:38912
	ds_read_b128 v[192:195], v150 offset:39936
	global_load_lds_dwordx4 v[196:197], off
	v_lshl_add_u64 v[196:197], s[26:27], 0, v[130:131]
	s_mov_b32 m0, s39
	s_nop 0
	global_load_lds_dwordx4 v[196:197], off
	s_add_i32 s34, 0, 0x1c000
	v_add_u32_e32 v208, s34, v147
	ds_read_b128 v[196:199], v208
	ds_read_b128 v[200:203], v208 offset:1024
	ds_read_b128 v[204:207], v208 offset:2048
	ds_read_b128 v[208:211], v208 offset:3072
	s_waitcnt lgkmcnt(0)
	s_barrier
	s_setprio 1
	v_mfma_f32_16x16x32_bf16 v[124:127], v[140:143], v[164:167], v[124:127]
	v_mfma_f32_16x16x32_bf16 v[120:123], v[156:159], v[164:167], v[120:123]
	v_mfma_f32_16x16x32_bf16 v[112:115], v[140:143], v[172:175], v[112:115]
	v_mfma_f32_16x16x32_bf16 v[104:107], v[156:159], v[172:175], v[104:107]
	v_mfma_f32_16x16x32_bf16 v[92:95], v[140:143], v[180:183], v[92:95]
	v_mfma_f32_16x16x32_bf16 v[88:91], v[156:159], v[180:183], v[88:91]
	v_mfma_f32_16x16x32_bf16 v[80:83], v[140:143], v[188:191], v[80:83]
	v_mfma_f32_16x16x32_bf16 v[72:75], v[156:159], v[188:191], v[72:75]
	v_mfma_f32_16x16x32_bf16 v[124:127], v[152:155], v[168:171], v[124:127]
	v_mfma_f32_16x16x32_bf16 v[120:123], v[160:163], v[168:171], v[120:123]
	v_mfma_f32_16x16x32_bf16 v[112:115], v[152:155], v[176:179], v[112:115]
	v_mfma_f32_16x16x32_bf16 v[104:107], v[160:163], v[176:179], v[104:107]
	v_mfma_f32_16x16x32_bf16 v[92:95], v[152:155], v[184:187], v[92:95]
	v_mfma_f32_16x16x32_bf16 v[88:91], v[160:163], v[184:187], v[88:91]
	v_mfma_f32_16x16x32_bf16 v[80:83], v[152:155], v[192:195], v[80:83]
	v_mfma_f32_16x16x32_bf16 v[72:75], v[160:163], v[192:195], v[72:75]
	v_mfma_f32_16x16x32_bf16 v[116:119], v[196:199], v[164:167], v[116:119]
	v_mfma_f32_16x16x32_bf16 v[108:111], v[204:207], v[164:167], v[108:111]
	v_mfma_f32_16x16x32_bf16 v[100:103], v[196:199], v[172:175], v[100:103]
	v_mfma_f32_16x16x32_bf16 v[96:99], v[204:207], v[172:175], v[96:99]
	v_mfma_f32_16x16x32_bf16 v[84:87], v[196:199], v[180:183], v[84:87]
	v_mfma_f32_16x16x32_bf16 v[76:79], v[204:207], v[180:183], v[76:79]
	v_mfma_f32_16x16x32_bf16 v[68:71], v[196:199], v[188:191], v[68:71]
	v_mfma_f32_16x16x32_bf16 v[64:67], v[204:207], v[188:191], v[64:67]
	v_mfma_f32_16x16x32_bf16 v[116:119], v[200:203], v[168:171], v[116:119]
	v_mfma_f32_16x16x32_bf16 v[108:111], v[208:211], v[168:171], v[108:111]
	v_mfma_f32_16x16x32_bf16 v[100:103], v[200:203], v[176:179], v[100:103]
	v_mfma_f32_16x16x32_bf16 v[96:99], v[208:211], v[176:179], v[96:99]
	v_mfma_f32_16x16x32_bf16 v[84:87], v[200:203], v[184:187], v[84:87]
	v_mfma_f32_16x16x32_bf16 v[76:79], v[208:211], v[184:187], v[76:79]
	v_mfma_f32_16x16x32_bf16 v[68:71], v[200:203], v[192:195], v[68:71]
	v_mfma_f32_16x16x32_bf16 v[64:67], v[208:211], v[192:195], v[64:67]
	s_setprio 0
	s_barrier
; #define PG8_STAGE(bufoff, gbase, voff) do { _Pragma("unroll") for (int _i = 0; _i < 2; ++_i) \
;         __builtin_amdgcn_global_load_lds((const unsigned*)((const char*)(gbase) + (voff)[_i]), (LAS unsigned*)(lds + (bufoff) + ldsw + _i * 8192), 16, 0, 0); } while (0)
; #define PG8_LDA(dst, b, h) do { _Pragma("unroll") for (int m = 0; m < 4; ++m) _Pragma("unroll") for (int k = 0; k < 2; ++k) dst[m][k] = *(const LAS bf16x8*)(lds + PG8_SA(b, h) + aoff + m * 2048 + k * 1024); } while (0)
; #define PG8_LDB(dst, b, h) do { _Pragma("unroll") for (int n = 0; n < 2; ++n) _Pragma("unroll") for (int k = 0; k < 2; ++k) dst[n][k] = *(const LAS bf16x8*)(lds + PG8_SB(b, h) + boff + n * 2048 + k * 1024); } while (0)
; #define PG8_MMA(ai, bj, At, Bt) do { __builtin_amdgcn_s_setprio(1); _Pragma("unroll") for (int m = 0; m < 4; ++m) _Pragma("unroll") for (int n = 0; n < 2; ++n) _Pragma("unroll") for (int k = 0; k < 2; ++k) \
;         acc[ai][bj][m][n] = __builtin_amdgcn_mfma_f32_16x16x32_bf16(Bt[n][k], At[m][k], acc[ai][bj][m][n], 0, 0, 0); __builtin_amdgcn_s_setprio(0); } while (0)
; #define PG8_WAIT_V(n) asm volatile("s_waitcnt vmcnt(" #n ")" ::: "memory")
; #define PG8_WAIT_L(n) asm volatile("s_waitcnt lgkmcnt(" #n ")" ::: "memory")
; #define PG8_BAR __builtin_amdgcn_s_barrier()
; #define PG8_SCHED __builtin_amdgcn_sched_barrier(0)
; template <class Epi>
; __device__ __forceinline__ void gemm_phase(LAS unsigned char* lds, const Gemm g, const StaticOrder& S, const Epi& E) {
;     ...
;             PG8_LDB(B1, 1, 1); PG8_STAGE(PG8_SB(1, 0), b3, voffB);
;             PG8_BAR; PG8_WAIT_L(0); PG8_MMA(0, 1, At, B1); PG8_BAR;
;             PG8_LDA(At, 1, 1); PG8_STAGE(PG8_SA(1, 0), a3, voffA);
;             PG8_BAR; PG8_WAIT_L(0); PG8_MMA(1, 0, At, B0); PG8_BAR; PG8_SCHED;
;             PG8_STAGE(PG8_SB(1, 1), b3 + hstepB, voffB);
;             PG8_WAIT_V(6); PG8_BAR; PG8_MMA(1, 1, At, B1); PG8_BAR;
	s_nop 1
	ds_read_b128 v[164:167], v150 offset:49152
	ds_read_b128 v[168:171], v150 offset:50176
	ds_read_b128 v[172:175], v150 offset:51200
	ds_read_b128 v[176:179], v150 offset:52224
	ds_read_b128 v[180:183], v150 offset:53248
	ds_read_b128 v[184:187], v150 offset:54272
	ds_read_b128 v[188:191], v150 offset:55296
	ds_read_b128 v[192:195], v150 offset:56320
	s_add_i32 s26, s69, s7
	v_lshl_add_u64 v[254:255], v[144:145], 0, s[16:17]
	s_mov_b32 m0, s26
	s_nop 0
	global_load_lds_dwordx4 v[254:255], off
	v_lshl_add_u64 v[254:255], v[212:213], 0, s[16:17]
	s_add_i32 m0, s26, 0x2000
	s_nop 0
	global_load_lds_dwordx4 v[254:255], off
	s_mov_b32 m0, s41
	v_lshl_add_u64 v[254:255], v[214:215], 0, s[16:17]
	global_load_lds_dwordx4 v[254:255], off
	v_lshl_add_u64 v[144:145], v[216:217], 0, s[16:17]
	s_mov_b32 m0, s42
	s_nop 0
	global_load_lds_dwordx4 v[144:145], off
	s_add_u32 s26, s30, 0xb0080
	s_addc_u32 s27, s31, 0
	s_add_i32 s30, s34, s7
	v_lshl_add_u64 v[254:255], s[26:27], 0, v[128:129]
	s_mov_b32 m0, s30
	s_nop 0
	global_load_lds_dwordx4 v[254:255], off
	v_lshl_add_u64 v[254:255], s[26:27], 0, v[130:131]
	s_add_i32 m0, s30, 0x2000
	s_nop 0
	global_load_lds_dwordx4 v[254:255], off
	s_waitcnt vmcnt(6)
	s_waitcnt lgkmcnt(0)
	s_barrier
	s_setprio 1
	v_mfma_f32_16x16x32_bf16 v[60:63], v[140:143], v[164:167], v[60:63]
	v_mfma_f32_16x16x32_bf16 v[56:59], v[156:159], v[164:167], v[56:59]
	v_mfma_f32_16x16x32_bf16 v[48:51], v[140:143], v[172:175], v[48:51]
	v_mfma_f32_16x16x32_bf16 v[40:43], v[156:159], v[172:175], v[40:43]
	v_mfma_f32_16x16x32_bf16 v[28:31], v[140:143], v[180:183], v[28:31]
	v_mfma_f32_16x16x32_bf16 v[24:27], v[156:159], v[180:183], v[24:27]
	v_mfma_f32_16x16x32_bf16 v[16:19], v[140:143], v[188:191], v[16:19]
	v_mfma_f32_16x16x32_bf16 v[8:11], v[156:159], v[188:191], v[8:11]
	v_mfma_f32_16x16x32_bf16 v[60:63], v[152:155], v[168:171], v[60:63]
	v_mfma_f32_16x16x32_bf16 v[56:59], v[160:163], v[168:171], v[56:59]
	v_mfma_f32_16x16x32_bf16 v[48:51], v[152:155], v[176:179], v[48:51]
	v_mfma_f32_16x16x32_bf16 v[40:43], v[160:163], v[176:179], v[40:43]
	v_mfma_f32_16x16x32_bf16 v[28:31], v[152:155], v[184:187], v[28:31]
	v_mfma_f32_16x16x32_bf16 v[24:27], v[160:163], v[184:187], v[24:27]
	v_mfma_f32_16x16x32_bf16 v[16:19], v[152:155], v[192:195], v[16:19]
	v_mfma_f32_16x16x32_bf16 v[8:11], v[160:163], v[192:195], v[8:11]
	v_mfma_f32_16x16x32_bf16 v[52:55], v[196:199], v[164:167], v[52:55]
	v_mfma_f32_16x16x32_bf16 v[44:47], v[204:207], v[164:167], v[44:47]
	v_mfma_f32_16x16x32_bf16 v[36:39], v[196:199], v[172:175], v[36:39]
	v_mfma_f32_16x16x32_bf16 v[32:35], v[204:207], v[172:175], v[32:35]
	v_mfma_f32_16x16x32_bf16 v[20:23], v[196:199], v[180:183], v[20:23]
	v_mfma_f32_16x16x32_bf16 v[12:15], v[204:207], v[180:183], v[12:15]
	v_mfma_f32_16x16x32_bf16 v[4:7], v[196:199], v[188:191], v[4:7]
	v_mfma_f32_16x16x32_bf16 v[0:3], v[204:207], v[188:191], v[0:3]
	v_mfma_f32_16x16x32_bf16 v[52:55], v[200:203], v[168:171], v[52:55]
	v_mfma_f32_16x16x32_bf16 v[44:47], v[208:211], v[168:171], v[44:47]
	v_mfma_f32_16x16x32_bf16 v[36:39], v[200:203], v[176:179], v[36:39]
	v_mfma_f32_16x16x32_bf16 v[32:35], v[208:211], v[176:179], v[32:35]
	v_mfma_f32_16x16x32_bf16 v[20:23], v[200:203], v[184:187], v[20:23]
	v_mfma_f32_16x16x32_bf16 v[12:15], v[208:211], v[184:187], v[12:15]
	v_mfma_f32_16x16x32_bf16 v[4:7], v[200:203], v[192:195], v[4:7]
	v_mfma_f32_16x16x32_bf16 v[0:3], v[208:211], v[192:195], v[0:3]
	s_setprio 0
	s_add_i32 s68, s68, 2
	s_add_u32 s49, s49, 0x100
	s_addc_u32 s63, s63, 0
	s_cmp_gt_u32 s68, 41
	s_mov_b64 s[26:27], s[28:29]
	s_barrier

; #define PG8_STAGE(bufoff, gbase, voff) do { _Pragma("unroll") for (int _i = 0; _i < 2; ++_i) \
;         __builtin_amdgcn_global_load_lds((const unsigned*)((const char*)(gbase) + (voff)[_i]), (LAS unsigned*)(lds + (bufoff) + ldsw + _i * 8192), 16, 0, 0); } while (0)
; #define PG8_LDA(dst, b, h) do { _Pragma("unroll") for (int m = 0; m < 4; ++m) _Pragma("unroll") for (int k = 0; k < 2; ++k) dst[m][k] = *(const LAS bf16x8*)(lds + PG8_SA(b, h) + aoff + m * 2048 + k * 1024); } while (0)
; #define PG8_LDB(dst, b, h) do { _Pragma("unroll") for (int n = 0; n < 2; ++n) _Pragma("unroll") for (int k = 0; k < 2; ++k) dst[n][k] = *(const LAS bf16x8*)(lds + PG8_SB(b, h) + boff + n * 2048 + k * 1024); } while (0)
; #define PG8_WAIT_V(n) asm volatile("s_waitcnt vmcnt(" #n ")" ::: "memory")
; #define PG8_WAIT_L(n) asm volatile("s_waitcnt lgkmcnt(" #n ")" ::: "memory")
; #define PG8_BAR __builtin_amdgcn_s_barrier()
; #define PG8_SCHED __builtin_amdgcn_sched_barrier(0)
; template <class Epi>
; __device__ __forceinline__ void gemm_phase(LAS unsigned char* lds, const Gemm g, const StaticOrder& S, const Epi& E) {
;     ...
;         const bool has_next = S.next(ui + 1, nxt);
;         const char* nA = has_next ? (const char*)g.A + (size_t)nxt.pm * tstepA + (size_t)(nxt.pn >> g.a_shift) * g.a_step : cA; const char* nB = has_next ? (const char*)g.Bt + (size_t)nxt.pn * tstepB : cB;
;         for (int t = 0; t < nt; t += 2) {
;             const bool last = (t == nt - 2);
;             const char* a1 = cA + (size_t)(t + 1) * kstep;
;             const char* a2 = last ? nA : cA + (size_t)(t + 2) * kstep; const char* b2 = last ? nB : cB + (size_t)(t + 2) * kstep;
;             const char* a3 = a2 + kstep; const char* b3 = b2 + kstep;
;             PG8_LDB(B0, 0, 0); PG8_SCHED; PG8_LDA(At, 0, 0); PG8_STAGE(PG8_SA(1, 1), a1 + hstepA, voffA);
;             PG8_WAIT_L(8); PG8_BAR; PG8_WAIT_L(0); PG8_MMA(0, 0, At, B0); PG8_BAR; PG8_SCHED;
;             PG8_LDB(B1, 0, 1); PG8_STAGE(PG8_SB(0, 0), b2, voffB);
;             PG8_BAR; PG8_WAIT_L(0); PG8_MMA(0, 1, At, B1); PG8_BAR;
;             PG8_LDA(At, 0, 1); PG8_STAGE(PG8_SA(0, 0), a2, voffA);
;             PG8_BAR; PG8_WAIT_L(0); PG8_MMA(1, 0, At, B0); PG8_BAR; PG8_SCHED;
;             PG8_STAGE(PG8_SB(0, 1), b2 + hstepB, voffB);
;             PG8_WAIT_V(6); PG8_BAR; PG8_MMA(1, 1, At, B1); PG8_BAR;
.LBB0_637:
	s_ashr_i32 s31, s30, 31
	v_cmp_lt_i64_e32 vcc, s[34:35], v[168:169]
	s_lshl_b64 s[34:35], s[30:31], 19
	s_add_u32 s34, s60, s34
	s_addc_u32 s35, s61, s35
	s_and_b64 s[36:37], vcc, exec
	s_cselect_b32 s31, s35, s41
	s_cselect_b32 s72, s34, s40
	s_ashr_i32 s29, s28, 31
	s_lshl_b64 s[36:37], s[28:29], 19
	s_add_u32 s36, s5, s36
	s_addc_u32 s37, s6, s37
	s_and_b64 s[44:45], vcc, exec
	s_cselect_b32 s29, s37, s43
	s_cselect_b32 s73, s36, s42
	s_add_u32 s40, s40, 0x40080
	s_addc_u32 s41, s41, 0
	s_add_u32 s74, s42, 0x100
	s_addc_u32 s75, s43, 0
	s_mov_b32 s76, -2
	ds_read_b128 v[128:131], v185
	ds_read_b128 v[132:135], v185 offset:1024
	ds_read_b128 v[136:139], v185 offset:2048
	ds_read_b128 v[140:143], v185 offset:3072
	s_add_u32 s42, s40, 0xfffc0080
	s_addc_u32 s43, s41, -1
	s_cmp_eq_u32 s76, 12
	s_cselect_b32 s45, s31, s43
	s_cselect_b32 s44, s72, s42
	s_cselect_b32 s43, s29, s75
	s_cselect_b32 s42, s73, s74
	v_lshl_add_u64 v[180:181], s[40:41], 0, v[164:165]
	s_add_i32 m0, s39, 0xc000
	ds_read_b128 v[144:147], v186
	ds_read_b128 v[148:151], v186 offset:1024
	ds_read_b128 v[152:155], v186 offset:2048
	ds_read_b128 v[172:175], v186 offset:3072
	ds_read_b128 v[176:179], v186 offset:4096
	ds_read_b128 v[188:191], v186 offset:5120
	ds_read_b128 v[192:195], v186 offset:6144
	ds_read_b128 v[196:199], v186 offset:7168
	global_load_lds_dwordx4 v[180:181], off
	v_lshl_add_u64 v[180:181], s[40:41], 0, v[166:167]
	s_add_i32 m0, s39, 0xe000
	s_nop 0
	global_load_lds_dwordx4 v[180:181], off
	ds_read_b128 v[200:203], v187
	ds_read_b128 v[204:207], v187 offset:1024
	ds_read_b128 v[208:211], v187 offset:2048
	ds_read_b128 v[212:215], v187 offset:3072
	s_waitcnt lgkmcnt(0)
	s_barrier
	s_setprio 1
	v_mfma_f32_16x16x32_bf16 v[124:127], v[128:131], v[144:147], 0
	v_mfma_f32_16x16x32_bf16 v[116:119], v[136:139], v[144:147], 0
	v_mfma_f32_16x16x32_bf16 v[108:111], v[128:131], v[152:155], 0
	v_mfma_f32_16x16x32_bf16 v[100:103], v[136:139], v[152:155], 0
	v_mfma_f32_16x16x32_bf16 v[92:95], v[128:131], v[176:179], 0
	v_mfma_f32_16x16x32_bf16 v[84:87], v[136:139], v[176:179], 0
	v_mfma_f32_16x16x32_bf16 v[76:79], v[128:131], v[192:195], 0
	v_mfma_f32_16x16x32_bf16 v[68:71], v[136:139], v[192:195], 0
	v_mfma_f32_16x16x32_bf16 v[124:127], v[132:135], v[148:151], v[124:127]
	v_mfma_f32_16x16x32_bf16 v[116:119], v[140:143], v[148:151], v[116:119]
	v_mfma_f32_16x16x32_bf16 v[108:111], v[132:135], v[172:175], v[108:111]
	v_mfma_f32_16x16x32_bf16 v[100:103], v[140:143], v[172:175], v[100:103]
	v_mfma_f32_16x16x32_bf16 v[92:95], v[132:135], v[188:191], v[92:95]
	v_mfma_f32_16x16x32_bf16 v[84:87], v[140:143], v[188:191], v[84:87]
	v_mfma_f32_16x16x32_bf16 v[76:79], v[132:135], v[196:199], v[76:79]
	v_mfma_f32_16x16x32_bf16 v[68:71], v[140:143], v[196:199], v[68:71]
	v_mfma_f32_16x16x32_bf16 v[120:123], v[200:203], v[144:147], 0
	v_mfma_f32_16x16x32_bf16 v[112:115], v[208:211], v[144:147], 0
	v_mfma_f32_16x16x32_bf16 v[104:107], v[200:203], v[152:155], 0
	v_mfma_f32_16x16x32_bf16 v[96:99], v[208:211], v[152:155], 0
	v_mfma_f32_16x16x32_bf16 v[88:91], v[200:203], v[176:179], 0
	v_mfma_f32_16x16x32_bf16 v[80:83], v[208:211], v[176:179], 0
	v_mfma_f32_16x16x32_bf16 v[72:75], v[200:203], v[192:195], 0
	v_mfma_f32_16x16x32_bf16 v[64:67], v[208:211], v[192:195], 0
	v_mfma_f32_16x16x32_bf16 v[120:123], v[204:207], v[148:151], v[120:123]
	v_mfma_f32_16x16x32_bf16 v[112:115], v[212:215], v[148:151], v[112:115]
	v_mfma_f32_16x16x32_bf16 v[104:107], v[204:207], v[172:175], v[104:107]
	v_mfma_f32_16x16x32_bf16 v[96:99], v[212:215], v[172:175], v[96:99]
	v_mfma_f32_16x16x32_bf16 v[88:91], v[204:207], v[188:191], v[88:91]
	v_mfma_f32_16x16x32_bf16 v[80:83], v[212:215], v[188:191], v[80:83]
	v_mfma_f32_16x16x32_bf16 v[72:75], v[204:207], v[196:199], v[72:75]
	v_mfma_f32_16x16x32_bf16 v[64:67], v[212:215], v[196:199], v[64:67]
	s_setprio 0
	s_barrier
	s_nop 1
	ds_read_b128 v[144:147], v186 offset:16384
	ds_read_b128 v[148:151], v186 offset:17408
	ds_read_b128 v[152:155], v186 offset:18432
	ds_read_b128 v[172:175], v186 offset:19456
	ds_read_b128 v[176:179], v186 offset:20480
	ds_read_b128 v[188:191], v186 offset:21504
	ds_read_b128 v[192:195], v186 offset:22528
	ds_read_b128 v[196:199], v186 offset:23552
	s_add_i32 s77, s69, s7
	v_lshl_add_u64 v[180:181], s[42:43], 0, v[158:159]
	s_mov_b32 m0, s77
	s_nop 0
	global_load_lds_dwordx4 v[180:181], off
	v_lshl_add_u64 v[216:217], s[42:43], 0, v[162:163]
	s_add_i32 m0, s77, 0x2000
	s_nop 0
	global_load_lds_dwordx4 v[216:217], off
	s_mov_b32 m0, s39
	v_lshl_add_u64 v[220:221], s[44:45], 0, v[156:157]
	global_load_lds_dwordx4 v[220:221], off
	v_lshl_add_u64 v[222:223], s[44:45], 0, v[160:161]
	s_mov_b32 m0, s46
	s_nop 0
	global_load_lds_dwordx4 v[222:223], off
	s_add_u32 s78, s42, 0x40000
	s_addc_u32 s79, s43, 0
	s_add_i32 s77, s70, s7
	v_lshl_add_u64 v[254:255], s[78:79], 0, v[158:159]
	s_mov_b32 m0, s77
	s_nop 0
	global_load_lds_dwordx4 v[254:255], off
	v_lshl_add_u64 v[254:255], s[78:79], 0, v[162:163]
	s_add_i32 m0, s77, 0x2000
	s_nop 0
	global_load_lds_dwordx4 v[254:255], off
	s_waitcnt vmcnt(6)
	s_waitcnt lgkmcnt(0)
	s_barrier
; #define PG8_STAGE(bufoff, gbase, voff) do { _Pragma("unroll") for (int _i = 0; _i < 2; ++_i) \
;         __builtin_amdgcn_global_load_lds((const unsigned*)((const char*)(gbase) + (voff)[_i]), (LAS unsigned*)(lds + (bufoff) + ldsw + _i * 8192), 16, 0, 0); } while (0)
; #define PG8_LDA(dst, b, h) do { _Pragma("unroll") for (int m = 0; m < 4; ++m) _Pragma("unroll") for (int k = 0; k < 2; ++k) dst[m][k] = *(const LAS bf16x8*)(lds + PG8_SA(b, h) + aoff + m * 2048 + k * 1024); } while (0)
; #define PG8_LDB(dst, b, h) do { _Pragma("unroll") for (int n = 0; n < 2; ++n) _Pragma("unroll") for (int k = 0; k < 2; ++k) dst[n][k] = *(const LAS bf16x8*)(lds + PG8_SB(b, h) + boff + n * 2048 + k * 1024); } while (0)
; #define PG8_MMA(ai, bj, At, Bt) do { __builtin_amdgcn_s_setprio(1); _Pragma("unroll") for (int m = 0; m < 4; ++m) _Pragma("unroll") for (int n = 0; n < 2; ++n) _Pragma("unroll") for (int k = 0; k < 2; ++k) \
;         acc[ai][bj][m][n] = __builtin_amdgcn_mfma_f32_16x16x32_bf16(Bt[n][k], At[m][k], acc[ai][bj][m][n], 0, 0, 0); __builtin_amdgcn_s_setprio(0); } while (0)
; #define PG8_WAIT_V(n) asm volatile("s_waitcnt vmcnt(" #n ")" ::: "memory")
; #define PG8_WAIT_L(n) asm volatile("s_waitcnt lgkmcnt(" #n ")" ::: "memory")
; #define PG8_BAR __builtin_amdgcn_s_barrier()
; #define PG8_SCHED __builtin_amdgcn_sched_barrier(0)
; template <class Epi>
; __device__ __forceinline__ void gemm_phase(LAS unsigned char* lds, const Gemm g, const StaticOrder& S, const Epi& E) {
;     ...
;             PG8_BAR; PG8_WAIT_L(0); PG8_MMA(1, 0, At, B0); PG8_BAR; PG8_SCHED;
;             PG8_STAGE(PG8_SB(0, 1), b2 + hstepB, voffB);
;             PG8_WAIT_V(6); PG8_BAR; PG8_MMA(1, 1, At, B1); PG8_BAR;
;             PG8_LDB(B0, 1, 0); PG8_SCHED; PG8_LDA(At, 1, 0); PG8_STAGE(PG8_SA(0, 1), a2 + hstepA, voffA);
;             PG8_WAIT_L(8); PG8_BAR; PG8_WAIT_L(0); PG8_MMA(0, 0, At, B0); PG8_BAR; PG8_SCHED;
;             PG8_LDB(B1, 1, 1); PG8_STAGE(PG8_SB(1, 0), b3, voffB);
;             PG8_BAR; PG8_WAIT_L(0); PG8_MMA(0, 1, At, B1); PG8_BAR;
	s_setprio 1
	v_mfma_f32_16x16x32_bf16 v[60:63], v[128:131], v[144:147], 0
	v_mfma_f32_16x16x32_bf16 v[52:55], v[136:139], v[144:147], 0
	v_mfma_f32_16x16x32_bf16 v[44:47], v[128:131], v[152:155], 0
	v_mfma_f32_16x16x32_bf16 v[36:39], v[136:139], v[152:155], 0
	v_mfma_f32_16x16x32_bf16 v[28:31], v[128:131], v[176:179], 0
	v_mfma_f32_16x16x32_bf16 v[20:23], v[136:139], v[176:179], 0
	v_mfma_f32_16x16x32_bf16 v[12:15], v[128:131], v[192:195], 0
	v_mfma_f32_16x16x32_bf16 v[4:7], v[136:139], v[192:195], 0
	v_mfma_f32_16x16x32_bf16 v[60:63], v[132:135], v[148:151], v[60:63]
	v_mfma_f32_16x16x32_bf16 v[52:55], v[140:143], v[148:151], v[52:55]
	v_mfma_f32_16x16x32_bf16 v[44:47], v[132:135], v[172:175], v[44:47]
	v_mfma_f32_16x16x32_bf16 v[36:39], v[140:143], v[172:175], v[36:39]
	v_mfma_f32_16x16x32_bf16 v[28:31], v[132:135], v[188:191], v[28:31]
	v_mfma_f32_16x16x32_bf16 v[20:23], v[140:143], v[188:191], v[20:23]
	v_mfma_f32_16x16x32_bf16 v[12:15], v[132:135], v[196:199], v[12:15]
	v_mfma_f32_16x16x32_bf16 v[4:7], v[140:143], v[196:199], v[4:7]
	v_mfma_f32_16x16x32_bf16 v[56:59], v[200:203], v[144:147], 0
	v_mfma_f32_16x16x32_bf16 v[48:51], v[208:211], v[144:147], 0
	v_mfma_f32_16x16x32_bf16 v[40:43], v[200:203], v[152:155], 0
	v_mfma_f32_16x16x32_bf16 v[32:35], v[208:211], v[152:155], 0
	v_mfma_f32_16x16x32_bf16 v[24:27], v[200:203], v[176:179], 0
	v_mfma_f32_16x16x32_bf16 v[16:19], v[208:211], v[176:179], 0
	v_mfma_f32_16x16x32_bf16 v[8:11], v[200:203], v[192:195], 0
	v_mfma_f32_16x16x32_bf16 v[0:3], v[208:211], v[192:195], 0
	v_mfma_f32_16x16x32_bf16 v[56:59], v[204:207], v[148:151], v[56:59]
	v_mfma_f32_16x16x32_bf16 v[48:51], v[212:215], v[148:151], v[48:51]
	v_mfma_f32_16x16x32_bf16 v[40:43], v[204:207], v[172:175], v[40:43]
	v_mfma_f32_16x16x32_bf16 v[32:35], v[212:215], v[172:175], v[32:35]
	v_mfma_f32_16x16x32_bf16 v[24:27], v[204:207], v[188:191], v[24:27]
	v_mfma_f32_16x16x32_bf16 v[16:19], v[212:215], v[188:191], v[16:19]
	v_mfma_f32_16x16x32_bf16 v[8:11], v[204:207], v[196:199], v[8:11]
	v_mfma_f32_16x16x32_bf16 v[0:3], v[212:215], v[196:199], v[0:3]
	s_setprio 0
	s_add_i32 s77, 0, 0x18000
	v_add_u32_e32 v140, s77, v183
	s_barrier
	ds_read_b128 v[128:131], v140
	ds_read_b128 v[132:135], v140 offset:1024
	ds_read_b128 v[136:139], v140 offset:2048
	ds_read_b128 v[140:143], v140 offset:3072
	s_add_u32 s44, s44, 0x40000
	s_addc_u32 s45, s45, 0
	s_mov_b32 m0, s47
	v_lshl_add_u64 v[200:201], s[44:45], 0, v[156:157]
	ds_read_b128 v[144:147], v186 offset:32768
	ds_read_b128 v[148:151], v186 offset:33792
	ds_read_b128 v[152:155], v186 offset:34816
	ds_read_b128 v[172:175], v186 offset:35840
	ds_read_b128 v[176:179], v186 offset:36864
	ds_read_b128 v[188:191], v186 offset:37888
	ds_read_b128 v[192:195], v186 offset:38912
	ds_read_b128 v[196:199], v186 offset:39936
	global_load_lds_dwordx4 v[200:201], off
	v_lshl_add_u64 v[200:201], s[44:45], 0, v[160:161]
	s_mov_b32 m0, s48
	s_nop 0
	global_load_lds_dwordx4 v[200:201], off
	s_add_i32 s44, 0, 0x1c000
	v_add_u32_e32 v212, s44, v183
	ds_read_b128 v[200:203], v212
	ds_read_b128 v[204:207], v212 offset:1024
	ds_read_b128 v[208:211], v212 offset:2048
	ds_read_b128 v[212:215], v212 offset:3072
	s_waitcnt lgkmcnt(0)
	s_barrier
	s_setprio 1
	v_mfma_f32_16x16x32_bf16 v[124:127], v[128:131], v[144:147], v[124:127]
	v_mfma_f32_16x16x32_bf16 v[116:119], v[136:139], v[144:147], v[116:119]
	v_mfma_f32_16x16x32_bf16 v[108:111], v[128:131], v[152:155], v[108:111]
	v_mfma_f32_16x16x32_bf16 v[100:103], v[136:139], v[152:155], v[100:103]
	v_mfma_f32_16x16x32_bf16 v[92:95], v[128:131], v[176:179], v[92:95]
	v_mfma_f32_16x16x32_bf16 v[84:87], v[136:139], v[176:179], v[84:87]
	v_mfma_f32_16x16x32_bf16 v[76:79], v[128:131], v[192:195], v[76:79]
	v_mfma_f32_16x16x32_bf16 v[68:71], v[136:139], v[192:195], v[68:71]
	v_mfma_f32_16x16x32_bf16 v[124:127], v[132:135], v[148:151], v[124:127]
	v_mfma_f32_16x16x32_bf16 v[116:119], v[140:143], v[148:151], v[116:119]
	v_mfma_f32_16x16x32_bf16 v[108:111], v[132:135], v[172:175], v[108:111]
	v_mfma_f32_16x16x32_bf16 v[100:103], v[140:143], v[172:175], v[100:103]
	v_mfma_f32_16x16x32_bf16 v[92:95], v[132:135], v[188:191], v[92:95]
	v_mfma_f32_16x16x32_bf16 v[84:87], v[140:143], v[188:191], v[84:87]
	v_mfma_f32_16x16x32_bf16 v[76:79], v[132:135], v[196:199], v[76:79]
	v_mfma_f32_16x16x32_bf16 v[68:71], v[140:143], v[196:199], v[68:71]
	v_mfma_f32_16x16x32_bf16 v[120:123], v[200:203], v[144:147], v[120:123]
	v_mfma_f32_16x16x32_bf16 v[112:115], v[208:211], v[144:147], v[112:115]
	v_mfma_f32_16x16x32_bf16 v[104:107], v[200:203], v[152:155], v[104:107]
	v_mfma_f32_16x16x32_bf16 v[96:99], v[208:211], v[152:155], v[96:99]
	v_mfma_f32_16x16x32_bf16 v[88:91], v[200:203], v[176:179], v[88:91]
	v_mfma_f32_16x16x32_bf16 v[80:83], v[208:211], v[176:179], v[80:83]
	v_mfma_f32_16x16x32_bf16 v[72:75], v[200:203], v[192:195], v[72:75]
	v_mfma_f32_16x16x32_bf16 v[64:67], v[208:211], v[192:195], v[64:67]
	v_mfma_f32_16x16x32_bf16 v[120:123], v[204:207], v[148:151], v[120:123]
	v_mfma_f32_16x16x32_bf16 v[112:115], v[212:215], v[148:151], v[112:115]
	v_mfma_f32_16x16x32_bf16 v[104:107], v[204:207], v[172:175], v[104:107]
	v_mfma_f32_16x16x32_bf16 v[96:99], v[212:215], v[172:175], v[96:99]
	v_mfma_f32_16x16x32_bf16 v[88:91], v[204:207], v[188:191], v[88:91]
	v_mfma_f32_16x16x32_bf16 v[80:83], v[212:215], v[188:191], v[80:83]
	v_mfma_f32_16x16x32_bf16 v[72:75], v[204:207], v[196:199], v[72:75]
	v_mfma_f32_16x16x32_bf16 v[64:67], v[212:215], v[196:199], v[64:67]
	s_setprio 0
	s_barrier
; #define PG8_STAGE(bufoff, gbase, voff) do { _Pragma("unroll") for (int _i = 0; _i < 2; ++_i) \
;         __builtin_amdgcn_global_load_lds((const unsigned*)((const char*)(gbase) + (voff)[_i]), (LAS unsigned*)(lds + (bufoff) + ldsw + _i * 8192), 16, 0, 0); } while (0)
; #define PG8_LDA(dst, b, h) do { _Pragma("unroll") for (int m = 0; m < 4; ++m) _Pragma("unroll") for (int k = 0; k < 2; ++k) dst[m][k] = *(const LAS bf16x8*)(lds + PG8_SA(b, h) + aoff + m * 2048 + k * 1024); } while (0)
; #define PG8_LDB(dst, b, h) do { _Pragma("unroll") for (int n = 0; n < 2; ++n) _Pragma("unroll") for (int k = 0; k < 2; ++k) dst[n][k] = *(const LAS bf16x8*)(lds + PG8_SB(b, h) + boff + n * 2048 + k * 1024); } while (0)
; #define PG8_MMA(ai, bj, At, Bt) do { __builtin_amdgcn_s_setprio(1); _Pragma("unroll") for (int m = 0; m < 4; ++m) _Pragma("unroll") for (int n = 0; n < 2; ++n) _Pragma("unroll") for (int k = 0; k < 2; ++k) \
;         acc[ai][bj][m][n] = __builtin_amdgcn_mfma_f32_16x16x32_bf16(Bt[n][k], At[m][k], acc[ai][bj][m][n], 0, 0, 0); __builtin_amdgcn_s_setprio(0); } while (0)
; #define PG8_WAIT_V(n) asm volatile("s_waitcnt vmcnt(" #n ")" ::: "memory")
; #define PG8_WAIT_L(n) asm volatile("s_waitcnt lgkmcnt(" #n ")" ::: "memory")
; #define PG8_BAR __builtin_amdgcn_s_barrier()
; #define PG8_SCHED __builtin_amdgcn_sched_barrier(0)
; template <class Epi>
; __device__ __forceinline__ void gemm_phase(LAS unsigned char* lds, const Gemm g, const StaticOrder& S, const Epi& E) {
;     ...
;             PG8_LDB(B1, 1, 1); PG8_STAGE(PG8_SB(1, 0), b3, voffB);
;             PG8_BAR; PG8_WAIT_L(0); PG8_MMA(0, 1, At, B1); PG8_BAR;
;             PG8_LDA(At, 1, 1); PG8_STAGE(PG8_SA(1, 0), a3, voffA);
;             PG8_BAR; PG8_WAIT_L(0); PG8_MMA(1, 0, At, B0); PG8_BAR; PG8_SCHED;
;             PG8_STAGE(PG8_SB(1, 1), b3 + hstepB, voffB);
;             PG8_WAIT_V(6); PG8_BAR; PG8_MMA(1, 1, At, B1); PG8_BAR;
	s_nop 1
	ds_read_b128 v[144:147], v186 offset:49152
	ds_read_b128 v[148:151], v186 offset:50176
	ds_read_b128 v[152:155], v186 offset:51200
	ds_read_b128 v[172:175], v186 offset:52224
	ds_read_b128 v[176:179], v186 offset:53248
	ds_read_b128 v[188:191], v186 offset:54272
	ds_read_b128 v[192:195], v186 offset:55296
	ds_read_b128 v[196:199], v186 offset:56320
	s_add_i32 s45, s77, s7
	v_lshl_add_u64 v[254:255], v[180:181], 0, s[12:13]
	s_mov_b32 m0, s45
	s_nop 0
	global_load_lds_dwordx4 v[254:255], off
	v_lshl_add_u64 v[254:255], v[216:217], 0, s[12:13]
	s_add_i32 m0, s45, 0x2000
	s_nop 0
	global_load_lds_dwordx4 v[254:255], off
	s_mov_b32 m0, s63
	v_lshl_add_u64 v[254:255], v[220:221], 0, s[12:13]
	global_load_lds_dwordx4 v[254:255], off
	v_lshl_add_u64 v[180:181], v[222:223], 0, s[12:13]
	s_mov_b32 m0, s68
	s_nop 0
	global_load_lds_dwordx4 v[180:181], off
	s_add_u32 s42, s42, 0x40080
	s_addc_u32 s43, s43, 0
	s_add_i32 s44, s44, s7
	v_lshl_add_u64 v[254:255], s[42:43], 0, v[158:159]
	s_mov_b32 m0, s44
	s_nop 0
	global_load_lds_dwordx4 v[254:255], off
	v_lshl_add_u64 v[254:255], s[42:43], 0, v[162:163]
	s_add_i32 m0, s44, 0x2000
	s_nop 0
	global_load_lds_dwordx4 v[254:255], off
	s_waitcnt vmcnt(6)
	s_waitcnt lgkmcnt(0)
	s_barrier
	s_setprio 1
	v_mfma_f32_16x16x32_bf16 v[60:63], v[128:131], v[144:147], v[60:63]
	v_mfma_f32_16x16x32_bf16 v[52:55], v[136:139], v[144:147], v[52:55]
	v_mfma_f32_16x16x32_bf16 v[44:47], v[128:131], v[152:155], v[44:47]
	v_mfma_f32_16x16x32_bf16 v[36:39], v[136:139], v[152:155], v[36:39]
	v_mfma_f32_16x16x32_bf16 v[28:31], v[128:131], v[176:179], v[28:31]
	v_mfma_f32_16x16x32_bf16 v[20:23], v[136:139], v[176:179], v[20:23]
	v_mfma_f32_16x16x32_bf16 v[12:15], v[128:131], v[192:195], v[12:15]
	v_mfma_f32_16x16x32_bf16 v[4:7], v[136:139], v[192:195], v[4:7]
	v_mfma_f32_16x16x32_bf16 v[60:63], v[132:135], v[148:151], v[60:63]
	v_mfma_f32_16x16x32_bf16 v[52:55], v[140:143], v[148:151], v[52:55]
	v_mfma_f32_16x16x32_bf16 v[44:47], v[132:135], v[172:175], v[44:47]
	v_mfma_f32_16x16x32_bf16 v[36:39], v[140:143], v[172:175], v[36:39]
	v_mfma_f32_16x16x32_bf16 v[28:31], v[132:135], v[188:191], v[28:31]
	v_mfma_f32_16x16x32_bf16 v[20:23], v[140:143], v[188:191], v[20:23]
	v_mfma_f32_16x16x32_bf16 v[12:15], v[132:135], v[196:199], v[12:15]
	v_mfma_f32_16x16x32_bf16 v[4:7], v[140:143], v[196:199], v[4:7]
	v_mfma_f32_16x16x32_bf16 v[56:59], v[200:203], v[144:147], v[56:59]
	v_mfma_f32_16x16x32_bf16 v[48:51], v[208:211], v[144:147], v[48:51]
	v_mfma_f32_16x16x32_bf16 v[40:43], v[200:203], v[152:155], v[40:43]
	v_mfma_f32_16x16x32_bf16 v[32:35], v[208:211], v[152:155], v[32:35]
	v_mfma_f32_16x16x32_bf16 v[24:27], v[200:203], v[176:179], v[24:27]
	v_mfma_f32_16x16x32_bf16 v[16:19], v[208:211], v[176:179], v[16:19]
	v_mfma_f32_16x16x32_bf16 v[8:11], v[200:203], v[192:195], v[8:11]
	v_mfma_f32_16x16x32_bf16 v[0:3], v[208:211], v[192:195], v[0:3]
	v_mfma_f32_16x16x32_bf16 v[56:59], v[204:207], v[148:151], v[56:59]
	v_mfma_f32_16x16x32_bf16 v[48:51], v[212:215], v[148:151], v[48:51]
	v_mfma_f32_16x16x32_bf16 v[40:43], v[204:207], v[172:175], v[40:43]
	v_mfma_f32_16x16x32_bf16 v[32:35], v[212:215], v[172:175], v[32:35]
	v_mfma_f32_16x16x32_bf16 v[24:27], v[204:207], v[188:191], v[24:27]
	v_mfma_f32_16x16x32_bf16 v[16:19], v[212:215], v[188:191], v[16:19]
	v_mfma_f32_16x16x32_bf16 v[8:11], v[204:207], v[196:199], v[8:11]
	v_mfma_f32_16x16x32_bf16 v[0:3], v[212:215], v[196:199], v[0:3]
	s_setprio 0
	s_add_i32 s76, s76, 2
	s_add_u32 s40, s40, 0x100
	s_addc_u32 s41, s41, 0
	s_add_u32 s74, s74, 0x100
	s_addc_u32 s75, s75, 0
	s_cmp_gt_u32 s76, 13
	s_barrier

; #define PG8_STAGE(bufoff, gbase, voff) do { _Pragma("unroll") for (int _i = 0; _i < 2; ++_i) \
;         __builtin_amdgcn_global_load_lds((const unsigned*)((const char*)(gbase) + (voff)[_i]), (LAS unsigned*)(lds + (bufoff) + ldsw + _i * 8192), 16, 0, 0); } while (0)
; #define PG8_LDA(dst, b, h) do { _Pragma("unroll") for (int m = 0; m < 4; ++m) _Pragma("unroll") for (int k = 0; k < 2; ++k) dst[m][k] = *(const LAS bf16x8*)(lds + PG8_SA(b, h) + aoff + m * 2048 + k * 1024); } while (0)
; #define PG8_LDB(dst, b, h) do { _Pragma("unroll") for (int n = 0; n < 2; ++n) _Pragma("unroll") for (int k = 0; k < 2; ++k) dst[n][k] = *(const LAS bf16x8*)(lds + PG8_SB(b, h) + boff + n * 2048 + k * 1024); } while (0)
; #define PG8_WAIT_V(n) asm volatile("s_waitcnt vmcnt(" #n ")" ::: "memory")
; #define PG8_WAIT_L(n) asm volatile("s_waitcnt lgkmcnt(" #n ")" ::: "memory")
; #define PG8_BAR __builtin_amdgcn_s_barrier()
; #define PG8_SCHED __builtin_amdgcn_sched_barrier(0)
; template <class Epi>
; __device__ __forceinline__ void gemm_phase(LAS unsigned char* lds, const Gemm g, const StaticOrder& S, const Epi& E) {
;     ...
;         const bool has_next = S.next(ui + 1, nxt);
;         const char* nA = has_next ? (const char*)g.A + (size_t)nxt.pm * tstepA + (size_t)(nxt.pn >> g.a_shift) * g.a_step : cA; const char* nB = has_next ? (const char*)g.Bt + (size_t)nxt.pn * tstepB : cB;
;         for (int t = 0; t < nt; t += 2) {
;             const bool last = (t == nt - 2);
;             const char* a1 = cA + (size_t)(t + 1) * kstep;
;             const char* a2 = last ? nA : cA + (size_t)(t + 2) * kstep; const char* b2 = last ? nB : cB + (size_t)(t + 2) * kstep;
;             const char* a3 = a2 + kstep; const char* b3 = b2 + kstep;
;             PG8_LDB(B0, 0, 0); PG8_SCHED; PG8_LDA(At, 0, 0); PG8_STAGE(PG8_SA(1, 1), a1 + hstepA, voffA);
;             PG8_WAIT_L(8); PG8_BAR; PG8_WAIT_L(0); PG8_MMA(0, 0, At, B0); PG8_BAR; PG8_SCHED;
;             PG8_LDB(B1, 0, 1); PG8_STAGE(PG8_SB(0, 0), b2, voffB);
;             PG8_BAR; PG8_WAIT_L(0); PG8_MMA(0, 1, At, B1); PG8_BAR;
;             PG8_LDA(At, 0, 1); PG8_STAGE(PG8_SA(0, 0), a2, voffA);
;             PG8_BAR; PG8_WAIT_L(0); PG8_MMA(1, 0, At, B0); PG8_BAR; PG8_SCHED;
;             PG8_STAGE(PG8_SB(0, 1), b2 + hstepB, voffB);
;             PG8_WAIT_V(6); PG8_BAR; PG8_MMA(1, 1, At, B1); PG8_BAR;
.LBB0_757:
	s_ashr_i32 s35, s34, 31
	v_cmp_lt_i64_e32 vcc, s[36:37], v[228:229]
	s_lshl_b64 s[36:37], s[34:35], 19
	s_add_u32 s36, s66, s36
	s_addc_u32 s37, s67, s37
	s_and_b64 s[38:39], vcc, exec
	s_cselect_b32 s35, s37, s43
	s_cselect_b32 s77, s36, s42
	s_ashr_i32 s31, s30, 31
	s_lshl_b64 s[38:39], s[30:31], 19
	s_add_u32 s38, s5, s38
	s_addc_u32 s39, s6, s39
	s_and_b64 s[46:47], vcc, exec
	s_cselect_b32 s31, s39, s45
	s_cselect_b32 s78, s38, s44
	s_add_u32 s79, s44, 0x100
	s_addc_u32 s80, s45, 0
	s_mov_b32 s81, -2
	ds_read_b128 v[96:99], v243
	ds_read_b128 v[100:103], v243 offset:1024
	ds_read_b128 v[104:107], v243 offset:2048
	ds_read_b128 v[108:111], v243 offset:3072
	s_add_u32 s44, s42, 0x100
	s_addc_u32 s45, s43, 0
	s_cmp_eq_u32 s81, 12
	s_cselect_b32 s49, s35, s45
	s_cselect_b32 s48, s77, s44
	s_cselect_b32 s47, s31, s80
	s_cselect_b32 s46, s78, s79
	v_lshl_add_u64 v[176:177], s[42:43], 0, v[224:225]
	s_add_i32 m0, s9, 0xc000
	ds_read_b128 v[112:115], v244
	ds_read_b128 v[116:119], v244 offset:1024
	ds_read_b128 v[120:123], v244 offset:2048
	ds_read_b128 v[124:127], v244 offset:3072
	ds_read_b128 v[160:163], v244 offset:4096
	ds_read_b128 v[164:167], v244 offset:5120
	ds_read_b128 v[168:171], v244 offset:6144
	ds_read_b128 v[172:175], v244 offset:7168
	global_load_lds_dwordx4 v[176:177], off
	v_lshl_add_u64 v[176:177], s[42:43], 0, v[226:227]
	s_add_i32 m0, s9, 0xe000
	s_nop 0
	global_load_lds_dwordx4 v[176:177], off
	ds_read_b128 v[176:179], v245
	ds_read_b128 v[180:183], v245 offset:1024
	ds_read_b128 v[184:187], v245 offset:2048
	ds_read_b128 v[188:191], v245 offset:3072
	s_waitcnt lgkmcnt(0)
	s_barrier
	s_setprio 1
	v_mfma_f32_16x16x32_bf16 v[156:159], v[96:99], v[112:115], 0
	v_mfma_f32_16x16x32_bf16 v[60:63], v[104:107], v[112:115], 0
	v_mfma_f32_16x16x32_bf16 v[144:147], v[96:99], v[120:123], 0
	v_mfma_f32_16x16x32_bf16 v[48:51], v[104:107], v[120:123], 0
	v_mfma_f32_16x16x32_bf16 v[136:139], v[96:99], v[160:163], 0
	v_mfma_f32_16x16x32_bf16 v[40:43], v[104:107], v[160:163], 0
	v_mfma_f32_16x16x32_bf16 v[148:151], v[96:99], v[168:171], 0
	v_mfma_f32_16x16x32_bf16 v[52:55], v[104:107], v[168:171], 0
	v_mfma_f32_16x16x32_bf16 v[156:159], v[100:103], v[116:119], v[156:159]
	v_mfma_f32_16x16x32_bf16 v[60:63], v[108:111], v[116:119], v[60:63]
	v_mfma_f32_16x16x32_bf16 v[144:147], v[100:103], v[124:127], v[144:147]
	v_mfma_f32_16x16x32_bf16 v[48:51], v[108:111], v[124:127], v[48:51]
	v_mfma_f32_16x16x32_bf16 v[136:139], v[100:103], v[164:167], v[136:139]
	v_mfma_f32_16x16x32_bf16 v[40:43], v[108:111], v[164:167], v[40:43]
	v_mfma_f32_16x16x32_bf16 v[148:151], v[100:103], v[172:175], v[148:151]
	v_mfma_f32_16x16x32_bf16 v[52:55], v[108:111], v[172:175], v[52:55]
	v_mfma_f32_16x16x32_bf16 v[152:155], v[176:179], v[112:115], 0
	v_mfma_f32_16x16x32_bf16 v[56:59], v[184:187], v[112:115], 0
	v_mfma_f32_16x16x32_bf16 v[36:39], v[184:187], v[120:123], 0
	v_mfma_f32_16x16x32_bf16 v[32:35], v[184:187], v[160:163], 0
	v_mfma_f32_16x16x32_bf16 v[44:47], v[184:187], v[168:171], 0
	v_mfma_f32_16x16x32_bf16 v[152:155], v[180:183], v[116:119], v[152:155]
	v_mfma_f32_16x16x32_bf16 v[56:59], v[188:191], v[116:119], v[56:59]
	v_mfma_f32_16x16x32_bf16 v[112:115], v[176:179], v[120:123], 0
	v_mfma_f32_16x16x32_bf16 v[36:39], v[188:191], v[124:127], v[36:39]
	v_mfma_f32_16x16x32_bf16 v[116:119], v[176:179], v[160:163], 0
	v_mfma_f32_16x16x32_bf16 v[32:35], v[188:191], v[164:167], v[32:35]
	v_mfma_f32_16x16x32_bf16 v[120:123], v[176:179], v[168:171], 0
	v_mfma_f32_16x16x32_bf16 v[44:47], v[188:191], v[172:175], v[44:47]
	v_mfma_f32_16x16x32_bf16 v[112:115], v[180:183], v[124:127], v[112:115]
	v_mfma_f32_16x16x32_bf16 v[116:119], v[180:183], v[164:167], v[116:119]
	v_mfma_f32_16x16x32_bf16 v[120:123], v[180:183], v[172:175], v[120:123]
	s_setprio 0
	s_barrier
	s_nop 1
	ds_read_b128 v[124:127], v244 offset:16384
	ds_read_b128 v[128:131], v244 offset:17408
	ds_read_b128 v[132:135], v244 offset:18432
	ds_read_b128 v[140:143], v244 offset:19456
	ds_read_b128 v[160:163], v244 offset:20480
	ds_read_b128 v[164:167], v244 offset:21504
	ds_read_b128 v[168:171], v244 offset:22528
	ds_read_b128 v[172:175], v244 offset:23552
	s_add_i32 s42, s74, s7
	v_lshl_add_u64 v[196:197], s[46:47], 0, v[214:215]
	s_mov_b32 m0, s42
	s_nop 0
	global_load_lds_dwordx4 v[196:197], off
	v_lshl_add_u64 v[198:199], s[46:47], 0, v[210:211]
	s_add_i32 m0, s42, 0x2000
	s_nop 0
	global_load_lds_dwordx4 v[198:199], off
	s_mov_b32 m0, s9
	v_lshl_add_u64 v[200:201], s[48:49], 0, v[216:217]
	global_load_lds_dwordx4 v[200:201], off
	v_lshl_add_u64 v[202:203], s[48:49], 0, v[212:213]
	s_mov_b32 m0, s63
	s_nop 0
	global_load_lds_dwordx4 v[202:203], off
	s_add_u32 s42, s46, 0x40000
	s_addc_u32 s43, s47, 0
	s_add_i32 s82, s75, s7
	v_lshl_add_u64 v[254:255], s[42:43], 0, v[214:215]
	s_mov_b32 m0, s82
	s_nop 0
	global_load_lds_dwordx4 v[254:255], off
	v_lshl_add_u64 v[254:255], s[42:43], 0, v[210:211]
	s_add_i32 m0, s82, 0x2000
	s_nop 0
	global_load_lds_dwordx4 v[254:255], off
	s_waitcnt vmcnt(6)
	s_waitcnt lgkmcnt(0)
	s_barrier
; #define PG8_STAGE(bufoff, gbase, voff) do { _Pragma("unroll") for (int _i = 0; _i < 2; ++_i) \
;         __builtin_amdgcn_global_load_lds((const unsigned*)((const char*)(gbase) + (voff)[_i]), (LAS unsigned*)(lds + (bufoff) + ldsw + _i * 8192), 16, 0, 0); } while (0)
; #define PG8_LDA(dst, b, h) do { _Pragma("unroll") for (int m = 0; m < 4; ++m) _Pragma("unroll") for (int k = 0; k < 2; ++k) dst[m][k] = *(const LAS bf16x8*)(lds + PG8_SA(b, h) + aoff + m * 2048 + k * 1024); } while (0)
; #define PG8_LDB(dst, b, h) do { _Pragma("unroll") for (int n = 0; n < 2; ++n) _Pragma("unroll") for (int k = 0; k < 2; ++k) dst[n][k] = *(const LAS bf16x8*)(lds + PG8_SB(b, h) + boff + n * 2048 + k * 1024); } while (0)
; #define PG8_MMA(ai, bj, At, Bt) do { __builtin_amdgcn_s_setprio(1); _Pragma("unroll") for (int m = 0; m < 4; ++m) _Pragma("unroll") for (int n = 0; n < 2; ++n) _Pragma("unroll") for (int k = 0; k < 2; ++k) \
;         acc[ai][bj][m][n] = __builtin_amdgcn_mfma_f32_16x16x32_bf16(Bt[n][k], At[m][k], acc[ai][bj][m][n], 0, 0, 0); __builtin_amdgcn_s_setprio(0); } while (0)
; #define PG8_WAIT_V(n) asm volatile("s_waitcnt vmcnt(" #n ")" ::: "memory")
; #define PG8_WAIT_L(n) asm volatile("s_waitcnt lgkmcnt(" #n ")" ::: "memory")
; #define PG8_BAR __builtin_amdgcn_s_barrier()
; #define PG8_SCHED __builtin_amdgcn_sched_barrier(0)
; template <class Epi>
; __device__ __forceinline__ void gemm_phase(LAS unsigned char* lds, const Gemm g, const StaticOrder& S, const Epi& E) {
;     ...
;             PG8_BAR; PG8_WAIT_L(0); PG8_MMA(1, 0, At, B0); PG8_BAR; PG8_SCHED;
;             PG8_STAGE(PG8_SB(0, 1), b2 + hstepB, voffB);
;             PG8_WAIT_V(6); PG8_BAR; PG8_MMA(1, 1, At, B1); PG8_BAR;
;             PG8_LDB(B0, 1, 0); PG8_SCHED; PG8_LDA(At, 1, 0); PG8_STAGE(PG8_SA(0, 1), a2 + hstepA, voffA);
;             PG8_WAIT_L(8); PG8_BAR; PG8_WAIT_L(0); PG8_MMA(0, 0, At, B0); PG8_BAR; PG8_SCHED;
;             PG8_LDB(B1, 1, 1); PG8_STAGE(PG8_SB(1, 0), b3, voffB);
;             PG8_BAR; PG8_WAIT_L(0); PG8_MMA(0, 1, At, B1); PG8_BAR;
	s_setprio 1
	v_mfma_f32_16x16x32_bf16 v[92:95], v[96:99], v[124:127], 0
	v_mfma_f32_16x16x32_bf16 v[28:31], v[104:107], v[124:127], 0
	v_mfma_f32_16x16x32_bf16 v[80:83], v[96:99], v[132:135], 0
	v_mfma_f32_16x16x32_bf16 v[16:19], v[104:107], v[132:135], 0
	v_mfma_f32_16x16x32_bf16 v[76:79], v[96:99], v[160:163], 0
	v_mfma_f32_16x16x32_bf16 v[12:15], v[104:107], v[160:163], 0
	v_mfma_f32_16x16x32_bf16 v[84:87], v[96:99], v[168:171], 0
	v_mfma_f32_16x16x32_bf16 v[20:23], v[104:107], v[168:171], 0
	v_mfma_f32_16x16x32_bf16 v[92:95], v[100:103], v[128:131], v[92:95]
	v_mfma_f32_16x16x32_bf16 v[28:31], v[108:111], v[128:131], v[28:31]
	v_mfma_f32_16x16x32_bf16 v[80:83], v[100:103], v[140:143], v[80:83]
	v_mfma_f32_16x16x32_bf16 v[16:19], v[108:111], v[140:143], v[16:19]
	v_mfma_f32_16x16x32_bf16 v[76:79], v[100:103], v[164:167], v[76:79]
	v_mfma_f32_16x16x32_bf16 v[12:15], v[108:111], v[164:167], v[12:15]
	v_mfma_f32_16x16x32_bf16 v[84:87], v[100:103], v[172:175], v[84:87]
	v_mfma_f32_16x16x32_bf16 v[20:23], v[108:111], v[172:175], v[20:23]
	v_mfma_f32_16x16x32_bf16 v[88:91], v[176:179], v[124:127], 0
	v_mfma_f32_16x16x32_bf16 v[24:27], v[184:187], v[124:127], 0
	v_mfma_f32_16x16x32_bf16 v[68:71], v[176:179], v[132:135], 0
	v_mfma_f32_16x16x32_bf16 v[4:7], v[184:187], v[132:135], 0
	v_mfma_f32_16x16x32_bf16 v[64:67], v[176:179], v[160:163], 0
	v_mfma_f32_16x16x32_bf16 v[0:3], v[184:187], v[160:163], 0
	v_mfma_f32_16x16x32_bf16 v[72:75], v[176:179], v[168:171], 0
	v_mfma_f32_16x16x32_bf16 v[8:11], v[184:187], v[168:171], 0
	v_mfma_f32_16x16x32_bf16 v[88:91], v[180:183], v[128:131], v[88:91]
	v_mfma_f32_16x16x32_bf16 v[24:27], v[188:191], v[128:131], v[24:27]
	v_mfma_f32_16x16x32_bf16 v[68:71], v[180:183], v[140:143], v[68:71]
	v_mfma_f32_16x16x32_bf16 v[4:7], v[188:191], v[140:143], v[4:7]
	v_mfma_f32_16x16x32_bf16 v[64:67], v[180:183], v[164:167], v[64:67]
	v_mfma_f32_16x16x32_bf16 v[0:3], v[188:191], v[164:167], v[0:3]
	v_mfma_f32_16x16x32_bf16 v[72:75], v[180:183], v[172:175], v[72:75]
	v_mfma_f32_16x16x32_bf16 v[8:11], v[188:191], v[172:175], v[8:11]
	s_setprio 0
	s_add_i32 s82, 0, 0x18000
	v_add_u32_e32 v108, s82, v235
	s_barrier
	ds_read_b128 v[96:99], v108
	ds_read_b128 v[100:103], v108 offset:1024
	ds_read_b128 v[104:107], v108 offset:2048
	ds_read_b128 v[108:111], v108 offset:3072
	s_add_u32 s42, s48, 0x40000
	s_addc_u32 s43, s49, 0
	s_mov_b32 m0, s68
	v_lshl_add_u64 v[132:133], s[42:43], 0, v[216:217]
	ds_read_b128 v[124:127], v244 offset:32768
	ds_read_b128 v[128:131], v244 offset:33792
	ds_read_b128 v[140:143], v244 offset:34816
	ds_read_b128 v[160:163], v244 offset:35840
	ds_read_b128 v[164:167], v244 offset:36864
	ds_read_b128 v[168:171], v244 offset:37888
	ds_read_b128 v[172:175], v244 offset:38912
	ds_read_b128 v[176:179], v244 offset:39936
	global_load_lds_dwordx4 v[132:133], off
	v_lshl_add_u64 v[132:133], s[42:43], 0, v[212:213]
	s_mov_b32 m0, s69
	s_nop 0
	global_load_lds_dwordx4 v[132:133], off
	s_add_i32 s48, 0, 0x1c000
	v_add_u32_e32 v132, s48, v235
	ds_read_b128 v[180:183], v132
	ds_read_b128 v[184:187], v132 offset:1024
	ds_read_b128 v[188:191], v132 offset:2048
	ds_read_b128 v[192:195], v132 offset:3072
	s_waitcnt lgkmcnt(0)
	s_barrier
	s_setprio 1
	v_mfma_f32_16x16x32_bf16 v[132:135], v[96:99], v[124:127], v[156:159]
	v_mfma_f32_16x16x32_bf16 v[156:159], v[100:103], v[128:131], v[132:135]
	v_mfma_f32_16x16x32_bf16 v[132:135], v[96:99], v[140:143], v[144:147]
	v_mfma_f32_16x16x32_bf16 v[144:147], v[100:103], v[160:163], v[132:135]
	v_mfma_f32_16x16x32_bf16 v[132:135], v[96:99], v[164:167], v[136:139]
	v_mfma_f32_16x16x32_bf16 v[60:63], v[104:107], v[124:127], v[60:63]
	v_mfma_f32_16x16x32_bf16 v[48:51], v[104:107], v[140:143], v[48:51]
	v_mfma_f32_16x16x32_bf16 v[136:139], v[100:103], v[168:171], v[132:135]
	v_mfma_f32_16x16x32_bf16 v[40:43], v[104:107], v[164:167], v[40:43]
	v_mfma_f32_16x16x32_bf16 v[132:135], v[96:99], v[172:175], v[148:151]
	v_mfma_f32_16x16x32_bf16 v[52:55], v[104:107], v[172:175], v[52:55]
	v_mfma_f32_16x16x32_bf16 v[60:63], v[108:111], v[128:131], v[60:63]
	v_mfma_f32_16x16x32_bf16 v[48:51], v[108:111], v[160:163], v[48:51]
	v_mfma_f32_16x16x32_bf16 v[40:43], v[108:111], v[168:171], v[40:43]
	v_mfma_f32_16x16x32_bf16 v[148:151], v[100:103], v[176:179], v[132:135]
	v_mfma_f32_16x16x32_bf16 v[52:55], v[108:111], v[176:179], v[52:55]
	v_mfma_f32_16x16x32_bf16 v[132:135], v[180:183], v[124:127], v[152:155]
	v_mfma_f32_16x16x32_bf16 v[112:115], v[180:183], v[140:143], v[112:115]
	v_mfma_f32_16x16x32_bf16 v[152:155], v[184:187], v[128:131], v[132:135]
	v_mfma_f32_16x16x32_bf16 v[56:59], v[188:191], v[124:127], v[56:59]
	v_mfma_f32_16x16x32_bf16 v[132:135], v[184:187], v[160:163], v[112:115]
	v_mfma_f32_16x16x32_bf16 v[112:115], v[180:183], v[164:167], v[116:119]
	v_mfma_f32_16x16x32_bf16 v[56:59], v[192:195], v[128:131], v[56:59]
	v_mfma_f32_16x16x32_bf16 v[36:39], v[188:191], v[140:143], v[36:39]
	v_mfma_f32_16x16x32_bf16 v[128:131], v[184:187], v[168:171], v[112:115]
	v_mfma_f32_16x16x32_bf16 v[32:35], v[188:191], v[164:167], v[32:35]
	v_mfma_f32_16x16x32_bf16 v[112:115], v[180:183], v[172:175], v[120:123]
	v_mfma_f32_16x16x32_bf16 v[44:47], v[188:191], v[172:175], v[44:47]
	v_mfma_f32_16x16x32_bf16 v[36:39], v[192:195], v[160:163], v[36:39]
	v_mfma_f32_16x16x32_bf16 v[32:35], v[192:195], v[168:171], v[32:35]
	v_mfma_f32_16x16x32_bf16 v[140:143], v[184:187], v[176:179], v[112:115]
	v_mfma_f32_16x16x32_bf16 v[44:47], v[192:195], v[176:179], v[44:47]
	s_setprio 0
	s_barrier
; #define PG8_STAGE(bufoff, gbase, voff) do { _Pragma("unroll") for (int _i = 0; _i < 2; ++_i) \
;         __builtin_amdgcn_global_load_lds((const unsigned*)((const char*)(gbase) + (voff)[_i]), (LAS unsigned*)(lds + (bufoff) + ldsw + _i * 8192), 16, 0, 0); } while (0)
; #define PG8_LDA(dst, b, h) do { _Pragma("unroll") for (int m = 0; m < 4; ++m) _Pragma("unroll") for (int k = 0; k < 2; ++k) dst[m][k] = *(const LAS bf16x8*)(lds + PG8_SA(b, h) + aoff + m * 2048 + k * 1024); } while (0)
; #define PG8_LDB(dst, b, h) do { _Pragma("unroll") for (int n = 0; n < 2; ++n) _Pragma("unroll") for (int k = 0; k < 2; ++k) dst[n][k] = *(const LAS bf16x8*)(lds + PG8_SB(b, h) + boff + n * 2048 + k * 1024); } while (0)
; #define PG8_MMA(ai, bj, At, Bt) do { __builtin_amdgcn_s_setprio(1); _Pragma("unroll") for (int m = 0; m < 4; ++m) _Pragma("unroll") for (int n = 0; n < 2; ++n) _Pragma("unroll") for (int k = 0; k < 2; ++k) \
;         acc[ai][bj][m][n] = __builtin_amdgcn_mfma_f32_16x16x32_bf16(Bt[n][k], At[m][k], acc[ai][bj][m][n], 0, 0, 0); __builtin_amdgcn_s_setprio(0); } while (0)
; #define PG8_WAIT_V(n) asm volatile("s_waitcnt vmcnt(" #n ")" ::: "memory")
; #define PG8_WAIT_L(n) asm volatile("s_waitcnt lgkmcnt(" #n ")" ::: "memory")
; #define PG8_BAR __builtin_amdgcn_s_barrier()
; #define PG8_SCHED __builtin_amdgcn_sched_barrier(0)
; template <class Epi>
; __device__ __forceinline__ void gemm_phase(LAS unsigned char* lds, const Gemm g, const StaticOrder& S, const Epi& E) {
;     ...
;             PG8_LDB(B1, 1, 1); PG8_STAGE(PG8_SB(1, 0), b3, voffB);
;             PG8_BAR; PG8_WAIT_L(0); PG8_MMA(0, 1, At, B1); PG8_BAR;
;             PG8_LDA(At, 1, 1); PG8_STAGE(PG8_SA(1, 0), a3, voffA);
;             PG8_BAR; PG8_WAIT_L(0); PG8_MMA(1, 0, At, B0); PG8_BAR; PG8_SCHED;
;             PG8_STAGE(PG8_SB(1, 1), b3 + hstepB, voffB);
;             PG8_WAIT_V(6); PG8_BAR; PG8_MMA(1, 1, At, B1); PG8_BAR;
	s_nop 1
	ds_read_b128 v[112:115], v244 offset:49152
	ds_read_b128 v[116:119], v244 offset:50176
	ds_read_b128 v[120:123], v244 offset:51200
	ds_read_b128 v[124:127], v244 offset:52224
	ds_read_b128 v[160:163], v244 offset:53248
	ds_read_b128 v[164:167], v244 offset:54272
	ds_read_b128 v[168:171], v244 offset:55296
	ds_read_b128 v[172:175], v244 offset:56320
	s_add_i32 s42, s82, s7
	v_lshl_add_u64 v[254:255], v[196:197], 0, s[20:21]
	s_mov_b32 m0, s42
	s_nop 0
	global_load_lds_dwordx4 v[254:255], off
	v_lshl_add_u64 v[254:255], v[198:199], 0, s[20:21]
	s_add_i32 m0, s42, 0x2000
	s_nop 0
	global_load_lds_dwordx4 v[254:255], off
	s_mov_b32 m0, s72
	v_lshl_add_u64 v[254:255], v[200:201], 0, s[20:21]
	global_load_lds_dwordx4 v[254:255], off
	v_lshl_add_u64 v[254:255], v[202:203], 0, s[20:21]
	s_mov_b32 m0, s73
	s_nop 0
	global_load_lds_dwordx4 v[254:255], off
	s_add_u32 s42, s46, 0x40080
	s_addc_u32 s43, s47, 0
	s_add_i32 s46, s48, s7
	v_lshl_add_u64 v[254:255], s[42:43], 0, v[214:215]
	s_mov_b32 m0, s46
	s_nop 0
	global_load_lds_dwordx4 v[254:255], off
	v_lshl_add_u64 v[254:255], s[42:43], 0, v[210:211]
	s_add_i32 m0, s46, 0x2000
	s_nop 0
	global_load_lds_dwordx4 v[254:255], off
	s_waitcnt vmcnt(6)
	s_waitcnt lgkmcnt(0)
	s_barrier
	s_setprio 1
	v_mfma_f32_16x16x32_bf16 v[92:95], v[96:99], v[112:115], v[92:95]
	v_mfma_f32_16x16x32_bf16 v[28:31], v[104:107], v[112:115], v[28:31]
	v_mfma_f32_16x16x32_bf16 v[80:83], v[96:99], v[120:123], v[80:83]
	v_mfma_f32_16x16x32_bf16 v[16:19], v[104:107], v[120:123], v[16:19]
	v_mfma_f32_16x16x32_bf16 v[76:79], v[96:99], v[160:163], v[76:79]
	v_mfma_f32_16x16x32_bf16 v[12:15], v[104:107], v[160:163], v[12:15]
	v_mfma_f32_16x16x32_bf16 v[84:87], v[96:99], v[168:171], v[84:87]
	v_mfma_f32_16x16x32_bf16 v[20:23], v[104:107], v[168:171], v[20:23]
	v_mfma_f32_16x16x32_bf16 v[92:95], v[100:103], v[116:119], v[92:95]
	v_mfma_f32_16x16x32_bf16 v[28:31], v[108:111], v[116:119], v[28:31]
	v_mfma_f32_16x16x32_bf16 v[80:83], v[100:103], v[124:127], v[80:83]
	v_mfma_f32_16x16x32_bf16 v[16:19], v[108:111], v[124:127], v[16:19]
	v_mfma_f32_16x16x32_bf16 v[76:79], v[100:103], v[164:167], v[76:79]
	v_mfma_f32_16x16x32_bf16 v[12:15], v[108:111], v[164:167], v[12:15]
	v_mfma_f32_16x16x32_bf16 v[84:87], v[100:103], v[172:175], v[84:87]
	v_mfma_f32_16x16x32_bf16 v[20:23], v[108:111], v[172:175], v[20:23]
	v_mfma_f32_16x16x32_bf16 v[88:91], v[180:183], v[112:115], v[88:91]
	v_mfma_f32_16x16x32_bf16 v[24:27], v[188:191], v[112:115], v[24:27]
	v_mfma_f32_16x16x32_bf16 v[68:71], v[180:183], v[120:123], v[68:71]
	v_mfma_f32_16x16x32_bf16 v[4:7], v[188:191], v[120:123], v[4:7]
	v_mfma_f32_16x16x32_bf16 v[64:67], v[180:183], v[160:163], v[64:67]
	v_mfma_f32_16x16x32_bf16 v[0:3], v[188:191], v[160:163], v[0:3]
	v_mfma_f32_16x16x32_bf16 v[72:75], v[180:183], v[168:171], v[72:75]
	v_mfma_f32_16x16x32_bf16 v[8:11], v[188:191], v[168:171], v[8:11]
	v_mfma_f32_16x16x32_bf16 v[88:91], v[184:187], v[116:119], v[88:91]
	v_mfma_f32_16x16x32_bf16 v[24:27], v[192:195], v[116:119], v[24:27]
	v_mfma_f32_16x16x32_bf16 v[68:71], v[184:187], v[124:127], v[68:71]
	v_mfma_f32_16x16x32_bf16 v[4:7], v[192:195], v[124:127], v[4:7]
	v_mfma_f32_16x16x32_bf16 v[64:67], v[184:187], v[164:167], v[64:67]
	v_mfma_f32_16x16x32_bf16 v[0:3], v[192:195], v[164:167], v[0:3]
	v_mfma_f32_16x16x32_bf16 v[72:75], v[184:187], v[172:175], v[72:75]
	v_mfma_f32_16x16x32_bf16 v[8:11], v[192:195], v[172:175], v[8:11]
	s_setprio 0
	s_add_i32 s81, s81, 2
	s_add_u32 s79, s79, 0x100
	s_addc_u32 s80, s80, 0
	s_cmp_gt_u32 s81, 13
	s_mov_b64 s[42:43], s[44:45]
	s_barrier

; #define PG8_STAGE(bufoff, gbase, voff) do { _Pragma("unroll") for (int _i = 0; _i < 2; ++_i) \
;         __builtin_amdgcn_global_load_lds((const unsigned*)((const char*)(gbase) + (voff)[_i]), (LAS unsigned*)(lds + (bufoff) + ldsw + _i * 8192), 16, 0, 0); } while (0)
; #define PG8_LDA(dst, b, h) do { _Pragma("unroll") for (int m = 0; m < 4; ++m) _Pragma("unroll") for (int k = 0; k < 2; ++k) dst[m][k] = *(const LAS bf16x8*)(lds + PG8_SA(b, h) + aoff + m * 2048 + k * 1024); } while (0)
; #define PG8_LDB(dst, b, h) do { _Pragma("unroll") for (int n = 0; n < 2; ++n) _Pragma("unroll") for (int k = 0; k < 2; ++k) dst[n][k] = *(const LAS bf16x8*)(lds + PG8_SB(b, h) + boff + n * 2048 + k * 1024); } while (0)
; #define PG8_MMA(ai, bj, At, Bt) do { __builtin_amdgcn_s_setprio(1); _Pragma("unroll") for (int m = 0; m < 4; ++m) _Pragma("unroll") for (int n = 0; n < 2; ++n) _Pragma("unroll") for (int k = 0; k < 2; ++k) \
;         acc[ai][bj][m][n] = __builtin_amdgcn_mfma_f32_16x16x32_bf16(Bt[n][k], At[m][k], acc[ai][bj][m][n], 0, 0, 0); __builtin_amdgcn_s_setprio(0); } while (0)
; #define PG8_WAIT_V(n) asm volatile("s_waitcnt vmcnt(" #n ")" ::: "memory")
; #define PG8_WAIT_L(n) asm volatile("s_waitcnt lgkmcnt(" #n ")" ::: "memory")
; template <class Epi>
; __device__ __forceinline__ void gemm_phase(LAS unsigned char* lds, const Gemm g, const StaticOrder& S, const Epi& E) {
;     ...
;         for (int t = 0; t < nt; t += 2) {
;             const bool last = (t == nt - 2);
;             const char* a1 = cA + (size_t)(t + 1) * kstep;
;             const char* a2 = last ? nA : cA + (size_t)(t + 2) * kstep; const char* b2 = last ? nB : cB + (size_t)(t + 2) * kstep;
;             const char* a3 = a2 + kstep; const char* b3 = b2 + kstep;
;             PG8_LDB(B0, 0, 0); PG8_SCHED; PG8_LDA(At, 0, 0); PG8_STAGE(PG8_SA(1, 1), a1 + hstepA, voffA);
;             PG8_WAIT_L(8); PG8_BAR; PG8_WAIT_L(0); PG8_MMA(0, 0, At, B0); PG8_BAR; PG8_SCHED;
;             PG8_LDB(B1, 0, 1); PG8_STAGE(PG8_SB(0, 0), b2, voffB);
;             PG8_BAR; PG8_WAIT_L(0); PG8_MMA(0, 1, At, B1); PG8_BAR;
;             PG8_LDA(At, 0, 1); PG8_STAGE(PG8_SA(0, 0), a2, voffA);
;             PG8_BAR; PG8_WAIT_L(0); PG8_MMA(1, 0, At, B0); PG8_BAR; PG8_SCHED;
;             PG8_STAGE(PG8_SB(0, 1), b2 + hstepB, voffB);
;             PG8_WAIT_V(6); PG8_BAR; PG8_MMA(1, 1, At, B1); PG8_BAR;
.LBB0_859:
	s_add_u32 s49, s30, 0x100
	s_addc_u32 s63, s31, 0
	s_mov_b32 s68, -2
	ds_read_b128 v[140:143], v149
	ds_read_b128 v[152:155], v149 offset:1024
	ds_read_b128 v[156:159], v149 offset:2048
	ds_read_b128 v[160:163], v149 offset:3072
	s_add_u32 s30, s28, 0x100
	s_addc_u32 s31, s29, 0
	s_cmp_eq_u32 s68, 40
	s_cselect_b32 s37, s13, s31
	s_cselect_b32 s36, s12, s30
	s_cselect_b32 s35, s15, s63
	s_cselect_b32 s34, s14, s49
	v_lshl_add_u64 v[144:145], s[28:29], 0, v[132:133]
	s_add_i32 m0, s8, 0xc000
	ds_read_b128 v[164:167], v150
	ds_read_b128 v[168:171], v150 offset:1024
	ds_read_b128 v[172:175], v150 offset:2048
	ds_read_b128 v[176:179], v150 offset:3072
	ds_read_b128 v[180:183], v150 offset:4096
	ds_read_b128 v[184:187], v150 offset:5120
	ds_read_b128 v[188:191], v150 offset:6144
	ds_read_b128 v[192:195], v150 offset:7168
	global_load_lds_dwordx4 v[144:145], off
	v_lshl_add_u64 v[144:145], s[28:29], 0, v[134:135]
	s_add_i32 m0, s8, 0xe000
	s_nop 0
	global_load_lds_dwordx4 v[144:145], off
	ds_read_b128 v[196:199], v151
	ds_read_b128 v[200:203], v151 offset:1024
	ds_read_b128 v[204:207], v151 offset:2048
	ds_read_b128 v[208:211], v151 offset:3072
	s_waitcnt lgkmcnt(0)
	s_barrier
	s_setprio 1
	v_mfma_f32_16x16x32_bf16 v[124:127], v[140:143], v[164:167], 0
	v_mfma_f32_16x16x32_bf16 v[120:123], v[156:159], v[164:167], 0
	v_mfma_f32_16x16x32_bf16 v[112:115], v[140:143], v[172:175], 0
	v_mfma_f32_16x16x32_bf16 v[104:107], v[156:159], v[172:175], 0
	v_mfma_f32_16x16x32_bf16 v[92:95], v[140:143], v[180:183], 0
	v_mfma_f32_16x16x32_bf16 v[88:91], v[156:159], v[180:183], 0
	v_mfma_f32_16x16x32_bf16 v[80:83], v[140:143], v[188:191], 0
	v_mfma_f32_16x16x32_bf16 v[72:75], v[156:159], v[188:191], 0
	v_mfma_f32_16x16x32_bf16 v[124:127], v[152:155], v[168:171], v[124:127]
	v_mfma_f32_16x16x32_bf16 v[120:123], v[160:163], v[168:171], v[120:123]
	v_mfma_f32_16x16x32_bf16 v[112:115], v[152:155], v[176:179], v[112:115]
	v_mfma_f32_16x16x32_bf16 v[104:107], v[160:163], v[176:179], v[104:107]
	v_mfma_f32_16x16x32_bf16 v[92:95], v[152:155], v[184:187], v[92:95]
	v_mfma_f32_16x16x32_bf16 v[88:91], v[160:163], v[184:187], v[88:91]
	v_mfma_f32_16x16x32_bf16 v[80:83], v[152:155], v[192:195], v[80:83]
	v_mfma_f32_16x16x32_bf16 v[72:75], v[160:163], v[192:195], v[72:75]
	v_mfma_f32_16x16x32_bf16 v[116:119], v[196:199], v[164:167], 0
	v_mfma_f32_16x16x32_bf16 v[108:111], v[204:207], v[164:167], 0
	v_mfma_f32_16x16x32_bf16 v[100:103], v[196:199], v[172:175], 0
	v_mfma_f32_16x16x32_bf16 v[96:99], v[204:207], v[172:175], 0
	v_mfma_f32_16x16x32_bf16 v[84:87], v[196:199], v[180:183], 0
	v_mfma_f32_16x16x32_bf16 v[76:79], v[204:207], v[180:183], 0
	v_mfma_f32_16x16x32_bf16 v[68:71], v[196:199], v[188:191], 0
	v_mfma_f32_16x16x32_bf16 v[64:67], v[204:207], v[188:191], 0
	v_mfma_f32_16x16x32_bf16 v[116:119], v[200:203], v[168:171], v[116:119]
	v_mfma_f32_16x16x32_bf16 v[108:111], v[208:211], v[168:171], v[108:111]
	v_mfma_f32_16x16x32_bf16 v[100:103], v[200:203], v[176:179], v[100:103]
	v_mfma_f32_16x16x32_bf16 v[96:99], v[208:211], v[176:179], v[96:99]
	v_mfma_f32_16x16x32_bf16 v[84:87], v[200:203], v[184:187], v[84:87]
	v_mfma_f32_16x16x32_bf16 v[76:79], v[208:211], v[184:187], v[76:79]
	v_mfma_f32_16x16x32_bf16 v[68:71], v[200:203], v[192:195], v[68:71]
	v_mfma_f32_16x16x32_bf16 v[64:67], v[208:211], v[192:195], v[64:67]
	s_setprio 0
	s_barrier
	s_nop 1
	ds_read_b128 v[164:167], v150 offset:16384
	ds_read_b128 v[168:171], v150 offset:17408
	ds_read_b128 v[172:175], v150 offset:18432
	ds_read_b128 v[176:179], v150 offset:19456
	ds_read_b128 v[180:183], v150 offset:20480
	ds_read_b128 v[184:187], v150 offset:21504
	ds_read_b128 v[188:191], v150 offset:22528
	ds_read_b128 v[192:195], v150 offset:23552
	s_add_i32 s28, s43, s7
	v_lshl_add_u64 v[144:145], s[34:35], 0, v[128:129]
	s_mov_b32 m0, s28
	s_nop 0
	global_load_lds_dwordx4 v[144:145], off
	v_lshl_add_u64 v[212:213], s[34:35], 0, v[130:131]
	s_add_i32 m0, s28, 0x2000
	s_nop 0
	global_load_lds_dwordx4 v[212:213], off
	s_mov_b32 m0, s8
	v_lshl_add_u64 v[214:215], s[36:37], 0, v[128:129]
	global_load_lds_dwordx4 v[214:215], off
	v_lshl_add_u64 v[216:217], s[36:37], 0, v[130:131]
	s_mov_b32 m0, s9
	s_nop 0
	global_load_lds_dwordx4 v[216:217], off
	s_add_u32 s28, s34, 0xb0000
	s_addc_u32 s29, s35, 0
	s_add_i32 s69, s44, s7
	v_lshl_add_u64 v[254:255], s[28:29], 0, v[128:129]
	s_mov_b32 m0, s69
	s_nop 0
	global_load_lds_dwordx4 v[254:255], off
	v_lshl_add_u64 v[254:255], s[28:29], 0, v[130:131]
	s_add_i32 m0, s69, 0x2000
	s_nop 0
	global_load_lds_dwordx4 v[254:255], off
	s_waitcnt vmcnt(6)
	s_waitcnt lgkmcnt(0)
	s_barrier
; #define PG8_STAGE(bufoff, gbase, voff) do { _Pragma("unroll") for (int _i = 0; _i < 2; ++_i) \
;         __builtin_amdgcn_global_load_lds((const unsigned*)((const char*)(gbase) + (voff)[_i]), (LAS unsigned*)(lds + (bufoff) + ldsw + _i * 8192), 16, 0, 0); } while (0)
; #define PG8_LDA(dst, b, h) do { _Pragma("unroll") for (int m = 0; m < 4; ++m) _Pragma("unroll") for (int k = 0; k < 2; ++k) dst[m][k] = *(const LAS bf16x8*)(lds + PG8_SA(b, h) + aoff + m * 2048 + k * 1024); } while (0)
; #define PG8_LDB(dst, b, h) do { _Pragma("unroll") for (int n = 0; n < 2; ++n) _Pragma("unroll") for (int k = 0; k < 2; ++k) dst[n][k] = *(const LAS bf16x8*)(lds + PG8_SB(b, h) + boff + n * 2048 + k * 1024); } while (0)
; #define PG8_MMA(ai, bj, At, Bt) do { __builtin_amdgcn_s_setprio(1); _Pragma("unroll") for (int m = 0; m < 4; ++m) _Pragma("unroll") for (int n = 0; n < 2; ++n) _Pragma("unroll") for (int k = 0; k < 2; ++k) \
;         acc[ai][bj][m][n] = __builtin_amdgcn_mfma_f32_16x16x32_bf16(Bt[n][k], At[m][k], acc[ai][bj][m][n], 0, 0, 0); __builtin_amdgcn_s_setprio(0); } while (0)
; #define PG8_WAIT_V(n) asm volatile("s_waitcnt vmcnt(" #n ")" ::: "memory")
; #define PG8_WAIT_L(n) asm volatile("s_waitcnt lgkmcnt(" #n ")" ::: "memory")
; #define PG8_BAR __builtin_amdgcn_s_barrier()
; #define PG8_SCHED __builtin_amdgcn_sched_barrier(0)
; template <class Epi>
; __device__ __forceinline__ void gemm_phase(LAS unsigned char* lds, const Gemm g, const StaticOrder& S, const Epi& E) {
;     ...
;             PG8_BAR; PG8_WAIT_L(0); PG8_MMA(1, 0, At, B0); PG8_BAR; PG8_SCHED;
;             PG8_STAGE(PG8_SB(0, 1), b2 + hstepB, voffB);
;             PG8_WAIT_V(6); PG8_BAR; PG8_MMA(1, 1, At, B1); PG8_BAR;
;             PG8_LDB(B0, 1, 0); PG8_SCHED; PG8_LDA(At, 1, 0); PG8_STAGE(PG8_SA(0, 1), a2 + hstepA, voffA);
;             PG8_WAIT_L(8); PG8_BAR; PG8_WAIT_L(0); PG8_MMA(0, 0, At, B0); PG8_BAR; PG8_SCHED;
;             PG8_LDB(B1, 1, 1); PG8_STAGE(PG8_SB(1, 0), b3, voffB);
;             PG8_BAR; PG8_WAIT_L(0); PG8_MMA(0, 1, At, B1); PG8_BAR;
	s_setprio 1
	v_mfma_f32_16x16x32_bf16 v[60:63], v[140:143], v[164:167], 0
	v_mfma_f32_16x16x32_bf16 v[56:59], v[156:159], v[164:167], 0
	v_mfma_f32_16x16x32_bf16 v[48:51], v[140:143], v[172:175], 0
	v_mfma_f32_16x16x32_bf16 v[40:43], v[156:159], v[172:175], 0
	v_mfma_f32_16x16x32_bf16 v[28:31], v[140:143], v[180:183], 0
	v_mfma_f32_16x16x32_bf16 v[24:27], v[156:159], v[180:183], 0
	v_mfma_f32_16x16x32_bf16 v[16:19], v[140:143], v[188:191], 0
	v_mfma_f32_16x16x32_bf16 v[8:11], v[156:159], v[188:191], 0
	v_mfma_f32_16x16x32_bf16 v[60:63], v[152:155], v[168:171], v[60:63]
	v_mfma_f32_16x16x32_bf16 v[56:59], v[160:163], v[168:171], v[56:59]
	v_mfma_f32_16x16x32_bf16 v[48:51], v[152:155], v[176:179], v[48:51]
	v_mfma_f32_16x16x32_bf16 v[40:43], v[160:163], v[176:179], v[40:43]
	v_mfma_f32_16x16x32_bf16 v[28:31], v[152:155], v[184:187], v[28:31]
	v_mfma_f32_16x16x32_bf16 v[24:27], v[160:163], v[184:187], v[24:27]
	v_mfma_f32_16x16x32_bf16 v[16:19], v[152:155], v[192:195], v[16:19]
	v_mfma_f32_16x16x32_bf16 v[8:11], v[160:163], v[192:195], v[8:11]
	v_mfma_f32_16x16x32_bf16 v[52:55], v[196:199], v[164:167], 0
	v_mfma_f32_16x16x32_bf16 v[44:47], v[204:207], v[164:167], 0
	v_mfma_f32_16x16x32_bf16 v[36:39], v[196:199], v[172:175], 0
	v_mfma_f32_16x16x32_bf16 v[32:35], v[204:207], v[172:175], 0
	v_mfma_f32_16x16x32_bf16 v[20:23], v[196:199], v[180:183], 0
	v_mfma_f32_16x16x32_bf16 v[12:15], v[204:207], v[180:183], 0
	v_mfma_f32_16x16x32_bf16 v[4:7], v[196:199], v[188:191], 0
	v_mfma_f32_16x16x32_bf16 v[0:3], v[204:207], v[188:191], 0
	v_mfma_f32_16x16x32_bf16 v[52:55], v[200:203], v[168:171], v[52:55]
	v_mfma_f32_16x16x32_bf16 v[44:47], v[208:211], v[168:171], v[44:47]
	v_mfma_f32_16x16x32_bf16 v[36:39], v[200:203], v[176:179], v[36:39]
	v_mfma_f32_16x16x32_bf16 v[32:35], v[208:211], v[176:179], v[32:35]
	v_mfma_f32_16x16x32_bf16 v[20:23], v[200:203], v[184:187], v[20:23]
	v_mfma_f32_16x16x32_bf16 v[12:15], v[208:211], v[184:187], v[12:15]
	v_mfma_f32_16x16x32_bf16 v[4:7], v[200:203], v[192:195], v[4:7]
	v_mfma_f32_16x16x32_bf16 v[0:3], v[208:211], v[192:195], v[0:3]
	s_setprio 0
	s_add_i32 s69, 0, 0x18000
	v_add_u32_e32 v160, s69, v147
	s_barrier
	ds_read_b128 v[140:143], v160
	ds_read_b128 v[152:155], v160 offset:1024
	ds_read_b128 v[156:159], v160 offset:2048
	ds_read_b128 v[160:163], v160 offset:3072
	s_add_u32 s28, s36, 0xb0000
	s_addc_u32 s29, s37, 0
	s_mov_b32 m0, s38
	v_lshl_add_u64 v[196:197], s[28:29], 0, v[128:129]
	ds_read_b128 v[164:167], v150 offset:32768
	ds_read_b128 v[168:171], v150 offset:33792
	ds_read_b128 v[172:175], v150 offset:34816
	ds_read_b128 v[176:179], v150 offset:35840
	ds_read_b128 v[180:183], v150 offset:36864
	ds_read_b128 v[184:187], v150 offset:37888
	ds_read_b128 v[188:191], v150 offset:38912
	ds_read_b128 v[192:195], v150 offset:39936
	global_load_lds_dwordx4 v[196:197], off
	v_lshl_add_u64 v[196:197], s[28:29], 0, v[130:131]
	s_mov_b32 m0, s39
	s_nop 0
	global_load_lds_dwordx4 v[196:197], off
	s_add_i32 s36, 0, 0x1c000
	v_add_u32_e32 v208, s36, v147
	ds_read_b128 v[196:199], v208
	ds_read_b128 v[200:203], v208 offset:1024
	ds_read_b128 v[204:207], v208 offset:2048
	ds_read_b128 v[208:211], v208 offset:3072
	s_waitcnt lgkmcnt(0)
	s_barrier
	s_setprio 1
	v_mfma_f32_16x16x32_bf16 v[124:127], v[140:143], v[164:167], v[124:127]
	v_mfma_f32_16x16x32_bf16 v[120:123], v[156:159], v[164:167], v[120:123]
	v_mfma_f32_16x16x32_bf16 v[112:115], v[140:143], v[172:175], v[112:115]
	v_mfma_f32_16x16x32_bf16 v[104:107], v[156:159], v[172:175], v[104:107]
	v_mfma_f32_16x16x32_bf16 v[92:95], v[140:143], v[180:183], v[92:95]
	v_mfma_f32_16x16x32_bf16 v[88:91], v[156:159], v[180:183], v[88:91]
	v_mfma_f32_16x16x32_bf16 v[80:83], v[140:143], v[188:191], v[80:83]
	v_mfma_f32_16x16x32_bf16 v[72:75], v[156:159], v[188:191], v[72:75]
	v_mfma_f32_16x16x32_bf16 v[124:127], v[152:155], v[168:171], v[124:127]
	v_mfma_f32_16x16x32_bf16 v[120:123], v[160:163], v[168:171], v[120:123]
	v_mfma_f32_16x16x32_bf16 v[112:115], v[152:155], v[176:179], v[112:115]
	v_mfma_f32_16x16x32_bf16 v[104:107], v[160:163], v[176:179], v[104:107]
	v_mfma_f32_16x16x32_bf16 v[92:95], v[152:155], v[184:187], v[92:95]
	v_mfma_f32_16x16x32_bf16 v[88:91], v[160:163], v[184:187], v[88:91]
	v_mfma_f32_16x16x32_bf16 v[80:83], v[152:155], v[192:195], v[80:83]
	v_mfma_f32_16x16x32_bf16 v[72:75], v[160:163], v[192:195], v[72:75]
	v_mfma_f32_16x16x32_bf16 v[116:119], v[196:199], v[164:167], v[116:119]
	v_mfma_f32_16x16x32_bf16 v[108:111], v[204:207], v[164:167], v[108:111]
	v_mfma_f32_16x16x32_bf16 v[100:103], v[196:199], v[172:175], v[100:103]
	v_mfma_f32_16x16x32_bf16 v[96:99], v[204:207], v[172:175], v[96:99]
	v_mfma_f32_16x16x32_bf16 v[84:87], v[196:199], v[180:183], v[84:87]
	v_mfma_f32_16x16x32_bf16 v[76:79], v[204:207], v[180:183], v[76:79]
	v_mfma_f32_16x16x32_bf16 v[68:71], v[196:199], v[188:191], v[68:71]
	v_mfma_f32_16x16x32_bf16 v[64:67], v[204:207], v[188:191], v[64:67]
	v_mfma_f32_16x16x32_bf16 v[116:119], v[200:203], v[168:171], v[116:119]
	v_mfma_f32_16x16x32_bf16 v[108:111], v[208:211], v[168:171], v[108:111]
	v_mfma_f32_16x16x32_bf16 v[100:103], v[200:203], v[176:179], v[100:103]
	v_mfma_f32_16x16x32_bf16 v[96:99], v[208:211], v[176:179], v[96:99]
	v_mfma_f32_16x16x32_bf16 v[84:87], v[200:203], v[184:187], v[84:87]
	v_mfma_f32_16x16x32_bf16 v[76:79], v[208:211], v[184:187], v[76:79]
	v_mfma_f32_16x16x32_bf16 v[68:71], v[200:203], v[192:195], v[68:71]
	v_mfma_f32_16x16x32_bf16 v[64:67], v[208:211], v[192:195], v[64:67]
	s_setprio 0
	s_barrier
; #define PG8_STAGE(bufoff, gbase, voff) do { _Pragma("unroll") for (int _i = 0; _i < 2; ++_i) \
;         __builtin_amdgcn_global_load_lds((const unsigned*)((const char*)(gbase) + (voff)[_i]), (LAS unsigned*)(lds + (bufoff) + ldsw + _i * 8192), 16, 0, 0); } while (0)
; #define PG8_LDA(dst, b, h) do { _Pragma("unroll") for (int m = 0; m < 4; ++m) _Pragma("unroll") for (int k = 0; k < 2; ++k) dst[m][k] = *(const LAS bf16x8*)(lds + PG8_SA(b, h) + aoff + m * 2048 + k * 1024); } while (0)
; #define PG8_LDB(dst, b, h) do { _Pragma("unroll") for (int n = 0; n < 2; ++n) _Pragma("unroll") for (int k = 0; k < 2; ++k) dst[n][k] = *(const LAS bf16x8*)(lds + PG8_SB(b, h) + boff + n * 2048 + k * 1024); } while (0)
; #define PG8_MMA(ai, bj, At, Bt) do { __builtin_amdgcn_s_setprio(1); _Pragma("unroll") for (int m = 0; m < 4; ++m) _Pragma("unroll") for (int n = 0; n < 2; ++n) _Pragma("unroll") for (int k = 0; k < 2; ++k) \
;         acc[ai][bj][m][n] = __builtin_amdgcn_mfma_f32_16x16x32_bf16(Bt[n][k], At[m][k], acc[ai][bj][m][n], 0, 0, 0); __builtin_amdgcn_s_setprio(0); } while (0)
; #define PG8_WAIT_V(n) asm volatile("s_waitcnt vmcnt(" #n ")" ::: "memory")
; #define PG8_WAIT_L(n) asm volatile("s_waitcnt lgkmcnt(" #n ")" ::: "memory")
; #define PG8_BAR __builtin_amdgcn_s_barrier()
; #define PG8_SCHED __builtin_amdgcn_sched_barrier(0)
; template <class Epi>
; __device__ __forceinline__ void gemm_phase(LAS unsigned char* lds, const Gemm g, const StaticOrder& S, const Epi& E) {
;     ...
;             PG8_LDB(B1, 1, 1); PG8_STAGE(PG8_SB(1, 0), b3, voffB);
;             PG8_BAR; PG8_WAIT_L(0); PG8_MMA(0, 1, At, B1); PG8_BAR;
;             PG8_LDA(At, 1, 1); PG8_STAGE(PG8_SA(1, 0), a3, voffA);
;             PG8_BAR; PG8_WAIT_L(0); PG8_MMA(1, 0, At, B0); PG8_BAR; PG8_SCHED;
;             PG8_STAGE(PG8_SB(1, 1), b3 + hstepB, voffB);
;             PG8_WAIT_V(6); PG8_BAR; PG8_MMA(1, 1, At, B1); PG8_BAR;
	s_nop 1
	ds_read_b128 v[164:167], v150 offset:49152
	ds_read_b128 v[168:171], v150 offset:50176
	ds_read_b128 v[172:175], v150 offset:51200
	ds_read_b128 v[176:179], v150 offset:52224
	ds_read_b128 v[180:183], v150 offset:53248
	ds_read_b128 v[184:187], v150 offset:54272
	ds_read_b128 v[188:191], v150 offset:55296
	ds_read_b128 v[192:195], v150 offset:56320
	s_add_i32 s28, s69, s7
	v_lshl_add_u64 v[254:255], v[144:145], 0, s[20:21]
	s_mov_b32 m0, s28
	s_nop 0
	global_load_lds_dwordx4 v[254:255], off
	v_lshl_add_u64 v[254:255], v[212:213], 0, s[20:21]
	s_add_i32 m0, s28, 0x2000
	s_nop 0
	global_load_lds_dwordx4 v[254:255], off
	s_mov_b32 m0, s41
	v_lshl_add_u64 v[254:255], v[214:215], 0, s[20:21]
	global_load_lds_dwordx4 v[254:255], off
	v_lshl_add_u64 v[144:145], v[216:217], 0, s[20:21]
	s_mov_b32 m0, s42
	s_nop 0
	global_load_lds_dwordx4 v[144:145], off
	s_add_u32 s28, s34, 0xb0080
	s_addc_u32 s29, s35, 0
	s_add_i32 s34, s36, s7
	v_lshl_add_u64 v[254:255], s[28:29], 0, v[128:129]
	s_mov_b32 m0, s34
	s_nop 0
	global_load_lds_dwordx4 v[254:255], off
	v_lshl_add_u64 v[254:255], s[28:29], 0, v[130:131]
	s_add_i32 m0, s34, 0x2000
	s_nop 0
	global_load_lds_dwordx4 v[254:255], off
	s_waitcnt vmcnt(6)
	s_waitcnt lgkmcnt(0)
	s_barrier
	s_setprio 1
	v_mfma_f32_16x16x32_bf16 v[60:63], v[140:143], v[164:167], v[60:63]
	v_mfma_f32_16x16x32_bf16 v[56:59], v[156:159], v[164:167], v[56:59]
	v_mfma_f32_16x16x32_bf16 v[48:51], v[140:143], v[172:175], v[48:51]
	v_mfma_f32_16x16x32_bf16 v[40:43], v[156:159], v[172:175], v[40:43]
	v_mfma_f32_16x16x32_bf16 v[28:31], v[140:143], v[180:183], v[28:31]
	v_mfma_f32_16x16x32_bf16 v[24:27], v[156:159], v[180:183], v[24:27]
	v_mfma_f32_16x16x32_bf16 v[16:19], v[140:143], v[188:191], v[16:19]
	v_mfma_f32_16x16x32_bf16 v[8:11], v[156:159], v[188:191], v[8:11]
	v_mfma_f32_16x16x32_bf16 v[60:63], v[152:155], v[168:171], v[60:63]
	v_mfma_f32_16x16x32_bf16 v[56:59], v[160:163], v[168:171], v[56:59]
	v_mfma_f32_16x16x32_bf16 v[48:51], v[152:155], v[176:179], v[48:51]
	v_mfma_f32_16x16x32_bf16 v[40:43], v[160:163], v[176:179], v[40:43]
	v_mfma_f32_16x16x32_bf16 v[28:31], v[152:155], v[184:187], v[28:31]
	v_mfma_f32_16x16x32_bf16 v[24:27], v[160:163], v[184:187], v[24:27]
	v_mfma_f32_16x16x32_bf16 v[16:19], v[152:155], v[192:195], v[16:19]
	v_mfma_f32_16x16x32_bf16 v[8:11], v[160:163], v[192:195], v[8:11]
	v_mfma_f32_16x16x32_bf16 v[52:55], v[196:199], v[164:167], v[52:55]
	v_mfma_f32_16x16x32_bf16 v[44:47], v[204:207], v[164:167], v[44:47]
	v_mfma_f32_16x16x32_bf16 v[36:39], v[196:199], v[172:175], v[36:39]
	v_mfma_f32_16x16x32_bf16 v[32:35], v[204:207], v[172:175], v[32:35]
	v_mfma_f32_16x16x32_bf16 v[20:23], v[196:199], v[180:183], v[20:23]
	v_mfma_f32_16x16x32_bf16 v[12:15], v[204:207], v[180:183], v[12:15]
	v_mfma_f32_16x16x32_bf16 v[4:7], v[196:199], v[188:191], v[4:7]
	v_mfma_f32_16x16x32_bf16 v[0:3], v[204:207], v[188:191], v[0:3]
	v_mfma_f32_16x16x32_bf16 v[52:55], v[200:203], v[168:171], v[52:55]
	v_mfma_f32_16x16x32_bf16 v[44:47], v[208:211], v[168:171], v[44:47]
	v_mfma_f32_16x16x32_bf16 v[36:39], v[200:203], v[176:179], v[36:39]
	v_mfma_f32_16x16x32_bf16 v[32:35], v[208:211], v[176:179], v[32:35]
	v_mfma_f32_16x16x32_bf16 v[20:23], v[200:203], v[184:187], v[20:23]
	v_mfma_f32_16x16x32_bf16 v[12:15], v[208:211], v[184:187], v[12:15]
	v_mfma_f32_16x16x32_bf16 v[4:7], v[200:203], v[192:195], v[4:7]
	v_mfma_f32_16x16x32_bf16 v[0:3], v[208:211], v[192:195], v[0:3]
	s_setprio 0
	s_add_i32 s68, s68, 2
	s_add_u32 s49, s49, 0x100
	s_addc_u32 s63, s63, 0
	s_cmp_gt_u32 s68, 41
	s_mov_b64 s[28:29], s[30:31]
	s_barrier

; #define PG8_STAGE(bufoff, gbase, voff) do { _Pragma("unroll") for (int _i = 0; _i < 2; ++_i) \
;         __builtin_amdgcn_global_load_lds((const unsigned*)((const char*)(gbase) + (voff)[_i]), (LAS unsigned*)(lds + (bufoff) + ldsw + _i * 8192), 16, 0, 0); } while (0)
; #define PG8_LDA(dst, b, h) do { _Pragma("unroll") for (int m = 0; m < 4; ++m) _Pragma("unroll") for (int k = 0; k < 2; ++k) dst[m][k] = *(const LAS bf16x8*)(lds + PG8_SA(b, h) + aoff + m * 2048 + k * 1024); } while (0)
; #define PG8_LDB(dst, b, h) do { _Pragma("unroll") for (int n = 0; n < 2; ++n) _Pragma("unroll") for (int k = 0; k < 2; ++k) dst[n][k] = *(const LAS bf16x8*)(lds + PG8_SB(b, h) + boff + n * 2048 + k * 1024); } while (0)
; #define PG8_WAIT_V(n) asm volatile("s_waitcnt vmcnt(" #n ")" ::: "memory")
; #define PG8_WAIT_L(n) asm volatile("s_waitcnt lgkmcnt(" #n ")" ::: "memory")
; #define PG8_BAR __builtin_amdgcn_s_barrier()
; #define PG8_SCHED __builtin_amdgcn_sched_barrier(0)
; template <class Epi>
; __device__ __forceinline__ void gemm_phase(LAS unsigned char* lds, const Gemm g, const StaticOrder& S, const Epi& E) {
;     ...
;         const bool has_next = S.next(ui + 1, nxt);
;         const char* nA = has_next ? (const char*)g.A + (size_t)nxt.pm * tstepA + (size_t)(nxt.pn >> g.a_shift) * g.a_step : cA; const char* nB = has_next ? (const char*)g.Bt + (size_t)nxt.pn * tstepB : cB;
;         for (int t = 0; t < nt; t += 2) {
;             const bool last = (t == nt - 2);
;             const char* a1 = cA + (size_t)(t + 1) * kstep;
;             const char* a2 = last ? nA : cA + (size_t)(t + 2) * kstep; const char* b2 = last ? nB : cB + (size_t)(t + 2) * kstep;
;             const char* a3 = a2 + kstep; const char* b3 = b2 + kstep;
;             PG8_LDB(B0, 0, 0); PG8_SCHED; PG8_LDA(At, 0, 0); PG8_STAGE(PG8_SA(1, 1), a1 + hstepA, voffA);
;             PG8_WAIT_L(8); PG8_BAR; PG8_WAIT_L(0); PG8_MMA(0, 0, At, B0); PG8_BAR; PG8_SCHED;
;             PG8_LDB(B1, 0, 1); PG8_STAGE(PG8_SB(0, 0), b2, voffB);
;             PG8_BAR; PG8_WAIT_L(0); PG8_MMA(0, 1, At, B1); PG8_BAR;
;             PG8_LDA(At, 0, 1); PG8_STAGE(PG8_SA(0, 0), a2, voffA);
;             PG8_BAR; PG8_WAIT_L(0); PG8_MMA(1, 0, At, B0); PG8_BAR; PG8_SCHED;
;             PG8_STAGE(PG8_SB(0, 1), b2 + hstepB, voffB);
;             PG8_WAIT_V(6); PG8_BAR; PG8_MMA(1, 1, At, B1); PG8_BAR;
.LBB0_989:
	s_ashr_i32 s71, s70, 31
	s_lshl_b64 s[10:11], s[70:71], 19
	v_cmp_lt_i64_e32 vcc, s[72:73], v[178:179]
	s_add_u32 s72, s66, s10
	s_addc_u32 s73, s67, s11
	s_and_b64 s[10:11], vcc, exec
	s_cselect_b32 s71, s73, s81
	s_cselect_b32 s77, s72, s80
	s_ashr_i32 s69, s68, 31
	s_lshl_b64 s[10:11], s[68:69], 19
	s_add_u32 s74, s88, s10
	s_addc_u32 s75, s89, s11
	s_and_b64 s[10:11], vcc, exec
	s_cselect_b32 s69, s75, s83
	s_cselect_b32 s79, s74, s82
	s_add_u32 vcc_lo, s82, 0x100
	s_addc_u32 vcc_hi, s83, 0
	s_mov_b32 s10, -2
	ds_read_b128 v[128:131], v214
	ds_read_b128 v[132:135], v214 offset:1024
	ds_read_b128 v[136:139], v214 offset:2048
	ds_read_b128 v[140:143], v214 offset:3072
	s_add_u32 s82, s80, 0x100
	s_addc_u32 s83, s81, 0
	s_cmp_eq_u32 s10, 12
	s_cselect_b32 s87, s71, s83
	s_cselect_b32 s86, s77, s82
	s_cselect_b32 s85, s69, vcc_hi
	s_cselect_b32 s84, s79, vcc_lo
	v_lshl_add_u64 v[160:161], s[80:81], 0, v[174:175]
	s_add_i32 m0, s91, 0xc000
	ds_read_b128 v[144:147], v215
	ds_read_b128 v[148:151], v215 offset:1024
	ds_read_b128 v[152:155], v215 offset:2048
	ds_read_b128 v[156:159], v215 offset:3072
	ds_read_b128 v[182:185], v215 offset:4096
	ds_read_b128 v[186:189], v215 offset:5120
	ds_read_b128 v[190:193], v215 offset:6144
	ds_read_b128 v[194:197], v215 offset:7168
	global_load_lds_dwordx4 v[160:161], off
	v_lshl_add_u64 v[160:161], s[80:81], 0, v[176:177]
	s_add_i32 m0, s91, 0xe000
	s_nop 0
	global_load_lds_dwordx4 v[160:161], off
	ds_read_b128 v[198:201], v216
	ds_read_b128 v[220:223], v216 offset:1024
	ds_read_b128 v[224:227], v216 offset:2048
	ds_read_b128 v[228:231], v216 offset:3072
	s_waitcnt lgkmcnt(0)
	s_barrier
	s_setprio 1
	v_mfma_f32_16x16x32_bf16 v[124:127], v[128:131], v[144:147], 0
	v_mfma_f32_16x16x32_bf16 v[120:123], v[136:139], v[144:147], 0
	v_mfma_f32_16x16x32_bf16 v[108:111], v[128:131], v[152:155], 0
	v_mfma_f32_16x16x32_bf16 v[104:107], v[136:139], v[152:155], 0
	v_mfma_f32_16x16x32_bf16 v[92:95], v[128:131], v[182:185], 0
	v_mfma_f32_16x16x32_bf16 v[88:91], v[136:139], v[182:185], 0
	v_mfma_f32_16x16x32_bf16 v[76:79], v[128:131], v[190:193], 0
	v_mfma_f32_16x16x32_bf16 v[72:75], v[136:139], v[190:193], 0
	v_mfma_f32_16x16x32_bf16 v[124:127], v[132:135], v[148:151], v[124:127]
	v_mfma_f32_16x16x32_bf16 v[120:123], v[140:143], v[148:151], v[120:123]
	v_mfma_f32_16x16x32_bf16 v[108:111], v[132:135], v[156:159], v[108:111]
	v_mfma_f32_16x16x32_bf16 v[104:107], v[140:143], v[156:159], v[104:107]
	v_mfma_f32_16x16x32_bf16 v[92:95], v[132:135], v[186:189], v[92:95]
	v_mfma_f32_16x16x32_bf16 v[88:91], v[140:143], v[186:189], v[88:91]
	v_mfma_f32_16x16x32_bf16 v[76:79], v[132:135], v[194:197], v[76:79]
	v_mfma_f32_16x16x32_bf16 v[72:75], v[140:143], v[194:197], v[72:75]
	v_mfma_f32_16x16x32_bf16 v[116:119], v[198:201], v[144:147], 0
	v_mfma_f32_16x16x32_bf16 v[112:115], v[224:227], v[144:147], 0
	v_mfma_f32_16x16x32_bf16 v[100:103], v[198:201], v[152:155], 0
	v_mfma_f32_16x16x32_bf16 v[96:99], v[224:227], v[152:155], 0
	v_mfma_f32_16x16x32_bf16 v[84:87], v[198:201], v[182:185], 0
	v_mfma_f32_16x16x32_bf16 v[80:83], v[224:227], v[182:185], 0
	v_mfma_f32_16x16x32_bf16 v[68:71], v[198:201], v[190:193], 0
	v_mfma_f32_16x16x32_bf16 v[64:67], v[224:227], v[190:193], 0
	v_mfma_f32_16x16x32_bf16 v[116:119], v[220:223], v[148:151], v[116:119]
	v_mfma_f32_16x16x32_bf16 v[112:115], v[228:231], v[148:151], v[112:115]
	v_mfma_f32_16x16x32_bf16 v[100:103], v[220:223], v[156:159], v[100:103]
	v_mfma_f32_16x16x32_bf16 v[96:99], v[228:231], v[156:159], v[96:99]
	v_mfma_f32_16x16x32_bf16 v[84:87], v[220:223], v[186:189], v[84:87]
	v_mfma_f32_16x16x32_bf16 v[80:83], v[228:231], v[186:189], v[80:83]
	v_mfma_f32_16x16x32_bf16 v[68:71], v[220:223], v[194:197], v[68:71]
	v_mfma_f32_16x16x32_bf16 v[64:67], v[228:231], v[194:197], v[64:67]
	s_setprio 0
	s_barrier
	s_nop 1
	ds_read_b128 v[144:147], v215 offset:16384
	ds_read_b128 v[148:151], v215 offset:17408
	ds_read_b128 v[152:155], v215 offset:18432
	ds_read_b128 v[156:159], v215 offset:19456
	ds_read_b128 v[182:185], v215 offset:20480
	ds_read_b128 v[186:189], v215 offset:21504
	ds_read_b128 v[190:193], v215 offset:22528
	ds_read_b128 v[194:197], v215 offset:23552
	s_add_i32 s11, s93, s90
	v_lshl_add_u64 v[160:161], s[84:85], 0, v[164:165]
	s_mov_b32 m0, s11
	s_nop 0
	global_load_lds_dwordx4 v[160:161], off
	v_lshl_add_u64 v[202:203], s[84:85], 0, v[168:169]
	s_add_i32 m0, s11, 0x2000
	s_nop 0
	global_load_lds_dwordx4 v[202:203], off
	s_mov_b32 m0, s91
	v_lshl_add_u64 v[232:233], s[86:87], 0, v[162:163]
	global_load_lds_dwordx4 v[232:233], off
	v_lshl_add_u64 v[236:237], s[86:87], 0, v[166:167]
	s_mov_b32 m0, s97
	s_nop 0
	global_load_lds_dwordx4 v[236:237], off
	s_add_u32 s80, s84, 0x40000
	s_addc_u32 s81, s85, 0
	s_add_i32 s11, s96, s90
	v_lshl_add_u64 v[254:255], s[80:81], 0, v[164:165]
	s_mov_b32 m0, s11
	s_nop 0
	global_load_lds_dwordx4 v[254:255], off
	v_lshl_add_u64 v[254:255], s[80:81], 0, v[168:169]
	s_add_i32 m0, s11, 0x2000
	s_nop 0
	global_load_lds_dwordx4 v[254:255], off
	s_waitcnt vmcnt(6)
	s_waitcnt lgkmcnt(0)
	s_barrier
; #define PG8_STAGE(bufoff, gbase, voff) do { _Pragma("unroll") for (int _i = 0; _i < 2; ++_i) \
;         __builtin_amdgcn_global_load_lds((const unsigned*)((const char*)(gbase) + (voff)[_i]), (LAS unsigned*)(lds + (bufoff) + ldsw + _i * 8192), 16, 0, 0); } while (0)
; #define PG8_LDA(dst, b, h) do { _Pragma("unroll") for (int m = 0; m < 4; ++m) _Pragma("unroll") for (int k = 0; k < 2; ++k) dst[m][k] = *(const LAS bf16x8*)(lds + PG8_SA(b, h) + aoff + m * 2048 + k * 1024); } while (0)
; #define PG8_LDB(dst, b, h) do { _Pragma("unroll") for (int n = 0; n < 2; ++n) _Pragma("unroll") for (int k = 0; k < 2; ++k) dst[n][k] = *(const LAS bf16x8*)(lds + PG8_SB(b, h) + boff + n * 2048 + k * 1024); } while (0)
; #define PG8_MMA(ai, bj, At, Bt) do { __builtin_amdgcn_s_setprio(1); _Pragma("unroll") for (int m = 0; m < 4; ++m) _Pragma("unroll") for (int n = 0; n < 2; ++n) _Pragma("unroll") for (int k = 0; k < 2; ++k) \
;         acc[ai][bj][m][n] = __builtin_amdgcn_mfma_f32_16x16x32_bf16(Bt[n][k], At[m][k], acc[ai][bj][m][n], 0, 0, 0); __builtin_amdgcn_s_setprio(0); } while (0)
; #define PG8_WAIT_V(n) asm volatile("s_waitcnt vmcnt(" #n ")" ::: "memory")
; #define PG8_WAIT_L(n) asm volatile("s_waitcnt lgkmcnt(" #n ")" ::: "memory")
; #define PG8_BAR __builtin_amdgcn_s_barrier()
; #define PG8_SCHED __builtin_amdgcn_sched_barrier(0)
; template <class Epi>
; __device__ __forceinline__ void gemm_phase(LAS unsigned char* lds, const Gemm g, const StaticOrder& S, const Epi& E) {
;     ...
;             PG8_BAR; PG8_WAIT_L(0); PG8_MMA(1, 0, At, B0); PG8_BAR; PG8_SCHED;
;             PG8_STAGE(PG8_SB(0, 1), b2 + hstepB, voffB);
;             PG8_WAIT_V(6); PG8_BAR; PG8_MMA(1, 1, At, B1); PG8_BAR;
;             PG8_LDB(B0, 1, 0); PG8_SCHED; PG8_LDA(At, 1, 0); PG8_STAGE(PG8_SA(0, 1), a2 + hstepA, voffA);
;             PG8_WAIT_L(8); PG8_BAR; PG8_WAIT_L(0); PG8_MMA(0, 0, At, B0); PG8_BAR; PG8_SCHED;
;             PG8_LDB(B1, 1, 1); PG8_STAGE(PG8_SB(1, 0), b3, voffB);
;             PG8_BAR; PG8_WAIT_L(0); PG8_MMA(0, 1, At, B1); PG8_BAR;
	s_setprio 1
	v_mfma_f32_16x16x32_bf16 v[60:63], v[128:131], v[144:147], 0
	v_mfma_f32_16x16x32_bf16 v[56:59], v[136:139], v[144:147], 0
	v_mfma_f32_16x16x32_bf16 v[44:47], v[128:131], v[152:155], 0
	v_mfma_f32_16x16x32_bf16 v[40:43], v[136:139], v[152:155], 0
	v_mfma_f32_16x16x32_bf16 v[28:31], v[128:131], v[182:185], 0
	v_mfma_f32_16x16x32_bf16 v[24:27], v[136:139], v[182:185], 0
	v_mfma_f32_16x16x32_bf16 v[12:15], v[128:131], v[190:193], 0
	v_mfma_f32_16x16x32_bf16 v[8:11], v[136:139], v[190:193], 0
	v_mfma_f32_16x16x32_bf16 v[60:63], v[132:135], v[148:151], v[60:63]
	v_mfma_f32_16x16x32_bf16 v[56:59], v[140:143], v[148:151], v[56:59]
	v_mfma_f32_16x16x32_bf16 v[44:47], v[132:135], v[156:159], v[44:47]
	v_mfma_f32_16x16x32_bf16 v[40:43], v[140:143], v[156:159], v[40:43]
	v_mfma_f32_16x16x32_bf16 v[28:31], v[132:135], v[186:189], v[28:31]
	v_mfma_f32_16x16x32_bf16 v[24:27], v[140:143], v[186:189], v[24:27]
	v_mfma_f32_16x16x32_bf16 v[12:15], v[132:135], v[194:197], v[12:15]
	v_mfma_f32_16x16x32_bf16 v[8:11], v[140:143], v[194:197], v[8:11]
	v_mfma_f32_16x16x32_bf16 v[52:55], v[198:201], v[144:147], 0
	v_mfma_f32_16x16x32_bf16 v[48:51], v[224:227], v[144:147], 0
	v_mfma_f32_16x16x32_bf16 v[36:39], v[198:201], v[152:155], 0
	v_mfma_f32_16x16x32_bf16 v[32:35], v[224:227], v[152:155], 0
	v_mfma_f32_16x16x32_bf16 v[20:23], v[198:201], v[182:185], 0
	v_mfma_f32_16x16x32_bf16 v[16:19], v[224:227], v[182:185], 0
	v_mfma_f32_16x16x32_bf16 v[4:7], v[198:201], v[190:193], 0
	v_mfma_f32_16x16x32_bf16 v[0:3], v[224:227], v[190:193], 0
	v_mfma_f32_16x16x32_bf16 v[52:55], v[220:223], v[148:151], v[52:55]
	v_mfma_f32_16x16x32_bf16 v[48:51], v[228:231], v[148:151], v[48:51]
	v_mfma_f32_16x16x32_bf16 v[36:39], v[220:223], v[156:159], v[36:39]
	v_mfma_f32_16x16x32_bf16 v[32:35], v[228:231], v[156:159], v[32:35]
	v_mfma_f32_16x16x32_bf16 v[20:23], v[220:223], v[186:189], v[20:23]
	v_mfma_f32_16x16x32_bf16 v[16:19], v[228:231], v[186:189], v[16:19]
	v_mfma_f32_16x16x32_bf16 v[4:7], v[220:223], v[194:197], v[4:7]
	v_mfma_f32_16x16x32_bf16 v[0:3], v[228:231], v[194:197], v[0:3]
	s_setprio 0
	s_add_i32 s11, 0, 0x18000
	v_add_u32_e32 v140, s11, v173
	s_barrier
	ds_read_b128 v[128:131], v140
	ds_read_b128 v[132:135], v140 offset:1024
	ds_read_b128 v[136:139], v140 offset:2048
	ds_read_b128 v[140:143], v140 offset:3072
	s_add_u32 s80, s86, 0x40000
	s_addc_u32 s81, s87, 0
	s_mov_b32 m0, s8
	v_lshl_add_u64 v[198:199], s[80:81], 0, v[162:163]
	ds_read_b128 v[144:147], v215 offset:32768
	ds_read_b128 v[148:151], v215 offset:33792
	ds_read_b128 v[152:155], v215 offset:34816
	ds_read_b128 v[156:159], v215 offset:35840
	ds_read_b128 v[182:185], v215 offset:36864
	ds_read_b128 v[186:189], v215 offset:37888
	ds_read_b128 v[190:193], v215 offset:38912
	ds_read_b128 v[194:197], v215 offset:39936
	global_load_lds_dwordx4 v[198:199], off
	v_lshl_add_u64 v[198:199], s[80:81], 0, v[166:167]
	s_mov_b32 m0, s9
	s_nop 0
	global_load_lds_dwordx4 v[198:199], off
	s_add_i32 s86, 0, 0x1c000
	v_add_u32_e32 v170, s86, v173
	ds_read_b128 v[198:201], v170
	ds_read_b128 v[220:223], v170 offset:1024
	ds_read_b128 v[224:227], v170 offset:2048
	ds_read_b128 v[228:231], v170 offset:3072
	s_waitcnt lgkmcnt(0)
	s_barrier
	s_setprio 1
	v_mfma_f32_16x16x32_bf16 v[124:127], v[128:131], v[144:147], v[124:127]
	v_mfma_f32_16x16x32_bf16 v[120:123], v[136:139], v[144:147], v[120:123]
	v_mfma_f32_16x16x32_bf16 v[108:111], v[128:131], v[152:155], v[108:111]
	v_mfma_f32_16x16x32_bf16 v[104:107], v[136:139], v[152:155], v[104:107]
	v_mfma_f32_16x16x32_bf16 v[92:95], v[128:131], v[182:185], v[92:95]
	v_mfma_f32_16x16x32_bf16 v[88:91], v[136:139], v[182:185], v[88:91]
	v_mfma_f32_16x16x32_bf16 v[76:79], v[128:131], v[190:193], v[76:79]
	v_mfma_f32_16x16x32_bf16 v[72:75], v[136:139], v[190:193], v[72:75]
	v_mfma_f32_16x16x32_bf16 v[124:127], v[132:135], v[148:151], v[124:127]
	v_mfma_f32_16x16x32_bf16 v[120:123], v[140:143], v[148:151], v[120:123]
	v_mfma_f32_16x16x32_bf16 v[108:111], v[132:135], v[156:159], v[108:111]
	v_mfma_f32_16x16x32_bf16 v[104:107], v[140:143], v[156:159], v[104:107]
	v_mfma_f32_16x16x32_bf16 v[92:95], v[132:135], v[186:189], v[92:95]
	v_mfma_f32_16x16x32_bf16 v[88:91], v[140:143], v[186:189], v[88:91]
	v_mfma_f32_16x16x32_bf16 v[76:79], v[132:135], v[194:197], v[76:79]
	v_mfma_f32_16x16x32_bf16 v[72:75], v[140:143], v[194:197], v[72:75]
	v_mfma_f32_16x16x32_bf16 v[116:119], v[198:201], v[144:147], v[116:119]
	v_mfma_f32_16x16x32_bf16 v[112:115], v[224:227], v[144:147], v[112:115]
	v_mfma_f32_16x16x32_bf16 v[100:103], v[198:201], v[152:155], v[100:103]
	v_mfma_f32_16x16x32_bf16 v[96:99], v[224:227], v[152:155], v[96:99]
	v_mfma_f32_16x16x32_bf16 v[84:87], v[198:201], v[182:185], v[84:87]
	v_mfma_f32_16x16x32_bf16 v[80:83], v[224:227], v[182:185], v[80:83]
	v_mfma_f32_16x16x32_bf16 v[68:71], v[198:201], v[190:193], v[68:71]
	v_mfma_f32_16x16x32_bf16 v[64:67], v[224:227], v[190:193], v[64:67]
	v_mfma_f32_16x16x32_bf16 v[116:119], v[220:223], v[148:151], v[116:119]
	v_mfma_f32_16x16x32_bf16 v[112:115], v[228:231], v[148:151], v[112:115]
	v_mfma_f32_16x16x32_bf16 v[100:103], v[220:223], v[156:159], v[100:103]
	v_mfma_f32_16x16x32_bf16 v[96:99], v[228:231], v[156:159], v[96:99]
	v_mfma_f32_16x16x32_bf16 v[84:87], v[220:223], v[186:189], v[84:87]
	v_mfma_f32_16x16x32_bf16 v[80:83], v[228:231], v[186:189], v[80:83]
	v_mfma_f32_16x16x32_bf16 v[68:71], v[220:223], v[194:197], v[68:71]
	v_mfma_f32_16x16x32_bf16 v[64:67], v[228:231], v[194:197], v[64:67]
	s_setprio 0
	s_barrier
; #define PG8_STAGE(bufoff, gbase, voff) do { _Pragma("unroll") for (int _i = 0; _i < 2; ++_i) \
;         __builtin_amdgcn_global_load_lds((const unsigned*)((const char*)(gbase) + (voff)[_i]), (LAS unsigned*)(lds + (bufoff) + ldsw + _i * 8192), 16, 0, 0); } while (0)
; #define PG8_LDA(dst, b, h) do { _Pragma("unroll") for (int m = 0; m < 4; ++m) _Pragma("unroll") for (int k = 0; k < 2; ++k) dst[m][k] = *(const LAS bf16x8*)(lds + PG8_SA(b, h) + aoff + m * 2048 + k * 1024); } while (0)
; #define PG8_LDB(dst, b, h) do { _Pragma("unroll") for (int n = 0; n < 2; ++n) _Pragma("unroll") for (int k = 0; k < 2; ++k) dst[n][k] = *(const LAS bf16x8*)(lds + PG8_SB(b, h) + boff + n * 2048 + k * 1024); } while (0)
; #define PG8_MMA(ai, bj, At, Bt) do { __builtin_amdgcn_s_setprio(1); _Pragma("unroll") for (int m = 0; m < 4; ++m) _Pragma("unroll") for (int n = 0; n < 2; ++n) _Pragma("unroll") for (int k = 0; k < 2; ++k) \
;         acc[ai][bj][m][n] = __builtin_amdgcn_mfma_f32_16x16x32_bf16(Bt[n][k], At[m][k], acc[ai][bj][m][n], 0, 0, 0); __builtin_amdgcn_s_setprio(0); } while (0)
; #define PG8_WAIT_V(n) asm volatile("s_waitcnt vmcnt(" #n ")" ::: "memory")
; #define PG8_WAIT_L(n) asm volatile("s_waitcnt lgkmcnt(" #n ")" ::: "memory")
; #define PG8_BAR __builtin_amdgcn_s_barrier()
; #define PG8_SCHED __builtin_amdgcn_sched_barrier(0)
; template <class Epi>
; __device__ __forceinline__ void gemm_phase(LAS unsigned char* lds, const Gemm g, const StaticOrder& S, const Epi& E) {
;     ...
;             PG8_LDB(B1, 1, 1); PG8_STAGE(PG8_SB(1, 0), b3, voffB);
;             PG8_BAR; PG8_WAIT_L(0); PG8_MMA(0, 1, At, B1); PG8_BAR;
;             PG8_LDA(At, 1, 1); PG8_STAGE(PG8_SA(1, 0), a3, voffA);
;             PG8_BAR; PG8_WAIT_L(0); PG8_MMA(1, 0, At, B0); PG8_BAR; PG8_SCHED;
;             PG8_STAGE(PG8_SB(1, 1), b3 + hstepB, voffB);
;             PG8_WAIT_V(6); PG8_BAR; PG8_MMA(1, 1, At, B1); PG8_BAR;
	s_nop 1
	ds_read_b128 v[144:147], v215 offset:49152
	ds_read_b128 v[148:151], v215 offset:50176
	ds_read_b128 v[152:155], v215 offset:51200
	ds_read_b128 v[156:159], v215 offset:52224
	ds_read_b128 v[182:185], v215 offset:53248
	ds_read_b128 v[186:189], v215 offset:54272
	ds_read_b128 v[190:193], v215 offset:55296
	ds_read_b128 v[194:197], v215 offset:56320
	s_add_i32 s11, s11, s90
	v_lshl_add_u64 v[254:255], v[160:161], 0, s[28:29]
	s_mov_b32 m0, s11
	s_nop 0
	global_load_lds_dwordx4 v[254:255], off
	v_lshl_add_u64 v[254:255], v[202:203], 0, s[28:29]
	s_add_i32 m0, s11, 0x2000
	s_nop 0
	global_load_lds_dwordx4 v[254:255], off
	s_mov_b32 m0, s4
	v_lshl_add_u64 v[254:255], v[232:233], 0, s[28:29]
	global_load_lds_dwordx4 v[254:255], off
	v_lshl_add_u64 v[160:161], v[236:237], 0, s[28:29]
	s_mov_b32 m0, s5
	s_nop 0
	global_load_lds_dwordx4 v[160:161], off
	s_add_u32 s80, s84, 0x40080
	s_addc_u32 s81, s85, 0
	s_add_i32 s11, s86, s90
	v_lshl_add_u64 v[254:255], s[80:81], 0, v[164:165]
	s_mov_b32 m0, s11
	s_nop 0
	global_load_lds_dwordx4 v[254:255], off
	v_lshl_add_u64 v[254:255], s[80:81], 0, v[168:169]
	s_add_i32 m0, s11, 0x2000
	s_nop 0
	global_load_lds_dwordx4 v[254:255], off
	s_waitcnt vmcnt(6)
	s_waitcnt lgkmcnt(0)
	s_barrier
	s_setprio 1
	v_mfma_f32_16x16x32_bf16 v[60:63], v[128:131], v[144:147], v[60:63]
	v_mfma_f32_16x16x32_bf16 v[56:59], v[136:139], v[144:147], v[56:59]
	v_mfma_f32_16x16x32_bf16 v[44:47], v[128:131], v[152:155], v[44:47]
	v_mfma_f32_16x16x32_bf16 v[40:43], v[136:139], v[152:155], v[40:43]
	v_mfma_f32_16x16x32_bf16 v[28:31], v[128:131], v[182:185], v[28:31]
	v_mfma_f32_16x16x32_bf16 v[24:27], v[136:139], v[182:185], v[24:27]
	v_mfma_f32_16x16x32_bf16 v[12:15], v[128:131], v[190:193], v[12:15]
	v_mfma_f32_16x16x32_bf16 v[8:11], v[136:139], v[190:193], v[8:11]
	v_mfma_f32_16x16x32_bf16 v[60:63], v[132:135], v[148:151], v[60:63]
	v_mfma_f32_16x16x32_bf16 v[56:59], v[140:143], v[148:151], v[56:59]
	v_mfma_f32_16x16x32_bf16 v[44:47], v[132:135], v[156:159], v[44:47]
	v_mfma_f32_16x16x32_bf16 v[40:43], v[140:143], v[156:159], v[40:43]
	v_mfma_f32_16x16x32_bf16 v[28:31], v[132:135], v[186:189], v[28:31]
	v_mfma_f32_16x16x32_bf16 v[24:27], v[140:143], v[186:189], v[24:27]
	v_mfma_f32_16x16x32_bf16 v[12:15], v[132:135], v[194:197], v[12:15]
	v_mfma_f32_16x16x32_bf16 v[8:11], v[140:143], v[194:197], v[8:11]
	v_mfma_f32_16x16x32_bf16 v[52:55], v[198:201], v[144:147], v[52:55]
	v_mfma_f32_16x16x32_bf16 v[48:51], v[224:227], v[144:147], v[48:51]
	v_mfma_f32_16x16x32_bf16 v[36:39], v[198:201], v[152:155], v[36:39]
	v_mfma_f32_16x16x32_bf16 v[32:35], v[224:227], v[152:155], v[32:35]
	v_mfma_f32_16x16x32_bf16 v[20:23], v[198:201], v[182:185], v[20:23]
	v_mfma_f32_16x16x32_bf16 v[16:19], v[224:227], v[182:185], v[16:19]
	v_mfma_f32_16x16x32_bf16 v[4:7], v[198:201], v[190:193], v[4:7]
	v_mfma_f32_16x16x32_bf16 v[0:3], v[224:227], v[190:193], v[0:3]
	v_mfma_f32_16x16x32_bf16 v[52:55], v[220:223], v[148:151], v[52:55]
	v_mfma_f32_16x16x32_bf16 v[48:51], v[228:231], v[148:151], v[48:51]
	v_mfma_f32_16x16x32_bf16 v[36:39], v[220:223], v[156:159], v[36:39]
	v_mfma_f32_16x16x32_bf16 v[32:35], v[228:231], v[156:159], v[32:35]
	v_mfma_f32_16x16x32_bf16 v[20:23], v[220:223], v[186:189], v[20:23]
	v_mfma_f32_16x16x32_bf16 v[16:19], v[228:231], v[186:189], v[16:19]
	v_mfma_f32_16x16x32_bf16 v[4:7], v[220:223], v[194:197], v[4:7]
	v_mfma_f32_16x16x32_bf16 v[0:3], v[228:231], v[194:197], v[0:3]
	s_setprio 0
	s_add_i32 s10, s10, 2
	s_add_u32 vcc_lo, vcc_lo, 0x100
	s_addc_u32 vcc_hi, vcc_hi, 0
	s_cmp_gt_u32 s10, 13
	s_mov_b64 s[80:81], s[82:83]
	s_barrier

; #define PG8_STAGE(bufoff, gbase, voff) do { _Pragma("unroll") for (int _i = 0; _i < 2; ++_i) \
;         __builtin_amdgcn_global_load_lds((const unsigned*)((const char*)(gbase) + (voff)[_i]), (LAS unsigned*)(lds + (bufoff) + ldsw + _i * 8192), 16, 0, 0); } while (0)
; #define PG8_LDA(dst, b, h) do { _Pragma("unroll") for (int m = 0; m < 4; ++m) _Pragma("unroll") for (int k = 0; k < 2; ++k) dst[m][k] = *(const LAS bf16x8*)(lds + PG8_SA(b, h) + aoff + m * 2048 + k * 1024); } while (0)
; #define PG8_LDB(dst, b, h) do { _Pragma("unroll") for (int n = 0; n < 2; ++n) _Pragma("unroll") for (int k = 0; k < 2; ++k) dst[n][k] = *(const LAS bf16x8*)(lds + PG8_SB(b, h) + boff + n * 2048 + k * 1024); } while (0)
; #define PG8_WAIT_V(n) asm volatile("s_waitcnt vmcnt(" #n ")" ::: "memory")
; #define PG8_WAIT_L(n) asm volatile("s_waitcnt lgkmcnt(" #n ")" ::: "memory")
; #define PG8_BAR __builtin_amdgcn_s_barrier()
; #define PG8_SCHED __builtin_amdgcn_sched_barrier(0)
; template <class Epi>
; __device__ __forceinline__ void gemm_phase(LAS unsigned char* lds, const Gemm g, const StaticOrder& S, const Epi& E) {
;     ...
;         const bool has_next = S.next(ui + 1, nxt);
;         const char* nA = has_next ? (const char*)g.A + (size_t)nxt.pm * tstepA + (size_t)(nxt.pn >> g.a_shift) * g.a_step : cA; const char* nB = has_next ? (const char*)g.Bt + (size_t)nxt.pn * tstepB : cB;
;         for (int t = 0; t < nt; t += 2) {
;             const bool last = (t == nt - 2);
;             const char* a1 = cA + (size_t)(t + 1) * kstep;
;             const char* a2 = last ? nA : cA + (size_t)(t + 2) * kstep; const char* b2 = last ? nB : cB + (size_t)(t + 2) * kstep;
;             const char* a3 = a2 + kstep; const char* b3 = b2 + kstep;
;             PG8_LDB(B0, 0, 0); PG8_SCHED; PG8_LDA(At, 0, 0); PG8_STAGE(PG8_SA(1, 1), a1 + hstepA, voffA);
;             PG8_WAIT_L(8); PG8_BAR; PG8_WAIT_L(0); PG8_MMA(0, 0, At, B0); PG8_BAR; PG8_SCHED;
;             PG8_LDB(B1, 0, 1); PG8_STAGE(PG8_SB(0, 0), b2, voffB);
;             PG8_BAR; PG8_WAIT_L(0); PG8_MMA(0, 1, At, B1); PG8_BAR;
;             PG8_LDA(At, 0, 1); PG8_STAGE(PG8_SA(0, 0), a2, voffA);
;             PG8_BAR; PG8_WAIT_L(0); PG8_MMA(1, 0, At, B0); PG8_BAR; PG8_SCHED;
;             PG8_STAGE(PG8_SB(0, 1), b2 + hstepB, voffB);
;             PG8_WAIT_V(6); PG8_BAR; PG8_MMA(1, 1, At, B1); PG8_BAR;
.LBB0_1238:
	s_ashr_i32 s29, s28, 31
	v_cmp_lt_i64_e32 vcc, s[30:31], v[136:137]
	s_lshl_b64 s[30:31], s[28:29], 19
	s_add_u32 s30, s60, s30
	s_addc_u32 s31, s61, s31
	s_and_b64 s[34:35], vcc, exec
	s_cselect_b32 s29, s31, s39
	s_cselect_b32 s72, s30, s38
	s_ashr_i32 s27, s26, 31
	s_lshl_b64 s[34:35], s[26:27], 19
	s_add_u32 s34, s5, s34
	s_addc_u32 s35, s6, s35
	s_and_b64 s[42:43], vcc, exec
	s_cselect_b32 s27, s35, s41
	s_cselect_b32 s73, s34, s40
	s_add_u32 s38, s38, 0x40080
	s_addc_u32 s39, s39, 0
	s_add_u32 s74, s40, 0x100
	s_addc_u32 s75, s41, 0
	s_mov_b32 s76, -2
	ds_read_b128 v[140:143], v149
	ds_read_b128 v[152:155], v149 offset:1024
	ds_read_b128 v[156:159], v149 offset:2048
	ds_read_b128 v[160:163], v149 offset:3072
	s_add_u32 s40, s38, 0xfffc0080
	s_addc_u32 s41, s39, -1
	s_cmp_eq_u32 s76, 12
	s_cselect_b32 s43, s29, s41
	s_cselect_b32 s42, s72, s40
	s_cselect_b32 s41, s27, s75
	s_cselect_b32 s40, s73, s74
	v_lshl_add_u64 v[144:145], s[38:39], 0, v[132:133]
	s_add_i32 m0, s8, 0xc000
	ds_read_b128 v[164:167], v150
	ds_read_b128 v[168:171], v150 offset:1024
	ds_read_b128 v[172:175], v150 offset:2048
	ds_read_b128 v[176:179], v150 offset:3072
	ds_read_b128 v[180:183], v150 offset:4096
	ds_read_b128 v[184:187], v150 offset:5120
	ds_read_b128 v[188:191], v150 offset:6144
	ds_read_b128 v[192:195], v150 offset:7168
	global_load_lds_dwordx4 v[144:145], off
	v_lshl_add_u64 v[144:145], s[38:39], 0, v[134:135]
	s_add_i32 m0, s8, 0xe000
	s_nop 0
	global_load_lds_dwordx4 v[144:145], off
	ds_read_b128 v[196:199], v151
	ds_read_b128 v[200:203], v151 offset:1024
	ds_read_b128 v[204:207], v151 offset:2048
	ds_read_b128 v[208:211], v151 offset:3072
	s_waitcnt lgkmcnt(0)
	s_barrier
	s_setprio 1
	v_mfma_f32_16x16x32_bf16 v[124:127], v[140:143], v[164:167], 0
	v_mfma_f32_16x16x32_bf16 v[120:123], v[156:159], v[164:167], 0
	v_mfma_f32_16x16x32_bf16 v[112:115], v[140:143], v[172:175], 0
	v_mfma_f32_16x16x32_bf16 v[104:107], v[156:159], v[172:175], 0
	v_mfma_f32_16x16x32_bf16 v[92:95], v[140:143], v[180:183], 0
	v_mfma_f32_16x16x32_bf16 v[88:91], v[156:159], v[180:183], 0
	v_mfma_f32_16x16x32_bf16 v[80:83], v[140:143], v[188:191], 0
	v_mfma_f32_16x16x32_bf16 v[72:75], v[156:159], v[188:191], 0
	v_mfma_f32_16x16x32_bf16 v[124:127], v[152:155], v[168:171], v[124:127]
	v_mfma_f32_16x16x32_bf16 v[120:123], v[160:163], v[168:171], v[120:123]
	v_mfma_f32_16x16x32_bf16 v[112:115], v[152:155], v[176:179], v[112:115]
	v_mfma_f32_16x16x32_bf16 v[104:107], v[160:163], v[176:179], v[104:107]
	v_mfma_f32_16x16x32_bf16 v[92:95], v[152:155], v[184:187], v[92:95]
	v_mfma_f32_16x16x32_bf16 v[88:91], v[160:163], v[184:187], v[88:91]
	v_mfma_f32_16x16x32_bf16 v[80:83], v[152:155], v[192:195], v[80:83]
	v_mfma_f32_16x16x32_bf16 v[72:75], v[160:163], v[192:195], v[72:75]
	v_mfma_f32_16x16x32_bf16 v[116:119], v[196:199], v[164:167], 0
	v_mfma_f32_16x16x32_bf16 v[108:111], v[204:207], v[164:167], 0
	v_mfma_f32_16x16x32_bf16 v[100:103], v[196:199], v[172:175], 0
	v_mfma_f32_16x16x32_bf16 v[96:99], v[204:207], v[172:175], 0
	v_mfma_f32_16x16x32_bf16 v[84:87], v[196:199], v[180:183], 0
	v_mfma_f32_16x16x32_bf16 v[76:79], v[204:207], v[180:183], 0
	v_mfma_f32_16x16x32_bf16 v[68:71], v[196:199], v[188:191], 0
	v_mfma_f32_16x16x32_bf16 v[64:67], v[204:207], v[188:191], 0
	v_mfma_f32_16x16x32_bf16 v[116:119], v[200:203], v[168:171], v[116:119]
	v_mfma_f32_16x16x32_bf16 v[108:111], v[208:211], v[168:171], v[108:111]
	v_mfma_f32_16x16x32_bf16 v[100:103], v[200:203], v[176:179], v[100:103]
	v_mfma_f32_16x16x32_bf16 v[96:99], v[208:211], v[176:179], v[96:99]
	v_mfma_f32_16x16x32_bf16 v[84:87], v[200:203], v[184:187], v[84:87]
	v_mfma_f32_16x16x32_bf16 v[76:79], v[208:211], v[184:187], v[76:79]
	v_mfma_f32_16x16x32_bf16 v[68:71], v[200:203], v[192:195], v[68:71]
	v_mfma_f32_16x16x32_bf16 v[64:67], v[208:211], v[192:195], v[64:67]
	s_setprio 0
	s_barrier
	s_nop 1
	ds_read_b128 v[164:167], v150 offset:16384
	ds_read_b128 v[168:171], v150 offset:17408
	ds_read_b128 v[172:175], v150 offset:18432
	ds_read_b128 v[176:179], v150 offset:19456
	ds_read_b128 v[180:183], v150 offset:20480
	ds_read_b128 v[184:187], v150 offset:21504
	ds_read_b128 v[188:191], v150 offset:22528
	ds_read_b128 v[192:195], v150 offset:23552
	s_add_i32 s77, s48, s7
	v_lshl_add_u64 v[144:145], s[40:41], 0, v[128:129]
	s_mov_b32 m0, s77
	s_nop 0
	global_load_lds_dwordx4 v[144:145], off
	v_lshl_add_u64 v[212:213], s[40:41], 0, v[130:131]
	s_add_i32 m0, s77, 0x2000
	s_nop 0
	global_load_lds_dwordx4 v[212:213], off
	s_mov_b32 m0, s8
	v_lshl_add_u64 v[214:215], s[42:43], 0, v[128:129]
	global_load_lds_dwordx4 v[214:215], off
	v_lshl_add_u64 v[216:217], s[42:43], 0, v[130:131]
	s_mov_b32 m0, s9
	s_nop 0
	global_load_lds_dwordx4 v[216:217], off
	s_add_u32 s78, s40, 0x40000
	s_addc_u32 s79, s41, 0
	s_add_i32 s77, s49, s7
	v_lshl_add_u64 v[254:255], s[78:79], 0, v[128:129]
	s_mov_b32 m0, s77
	s_nop 0
	global_load_lds_dwordx4 v[254:255], off
	v_lshl_add_u64 v[254:255], s[78:79], 0, v[130:131]
	s_add_i32 m0, s77, 0x2000
	s_nop 0
	global_load_lds_dwordx4 v[254:255], off
	s_waitcnt vmcnt(6)
	s_waitcnt lgkmcnt(0)
	s_barrier
; #define PG8_STAGE(bufoff, gbase, voff) do { _Pragma("unroll") for (int _i = 0; _i < 2; ++_i) \
;         __builtin_amdgcn_global_load_lds((const unsigned*)((const char*)(gbase) + (voff)[_i]), (LAS unsigned*)(lds + (bufoff) + ldsw + _i * 8192), 16, 0, 0); } while (0)
; #define PG8_LDA(dst, b, h) do { _Pragma("unroll") for (int m = 0; m < 4; ++m) _Pragma("unroll") for (int k = 0; k < 2; ++k) dst[m][k] = *(const LAS bf16x8*)(lds + PG8_SA(b, h) + aoff + m * 2048 + k * 1024); } while (0)
; #define PG8_LDB(dst, b, h) do { _Pragma("unroll") for (int n = 0; n < 2; ++n) _Pragma("unroll") for (int k = 0; k < 2; ++k) dst[n][k] = *(const LAS bf16x8*)(lds + PG8_SB(b, h) + boff + n * 2048 + k * 1024); } while (0)
; #define PG8_MMA(ai, bj, At, Bt) do { __builtin_amdgcn_s_setprio(1); _Pragma("unroll") for (int m = 0; m < 4; ++m) _Pragma("unroll") for (int n = 0; n < 2; ++n) _Pragma("unroll") for (int k = 0; k < 2; ++k) \
;         acc[ai][bj][m][n] = __builtin_amdgcn_mfma_f32_16x16x32_bf16(Bt[n][k], At[m][k], acc[ai][bj][m][n], 0, 0, 0); __builtin_amdgcn_s_setprio(0); } while (0)
; #define PG8_WAIT_V(n) asm volatile("s_waitcnt vmcnt(" #n ")" ::: "memory")
; #define PG8_WAIT_L(n) asm volatile("s_waitcnt lgkmcnt(" #n ")" ::: "memory")
; #define PG8_BAR __builtin_amdgcn_s_barrier()
; #define PG8_SCHED __builtin_amdgcn_sched_barrier(0)
; template <class Epi>
; __device__ __forceinline__ void gemm_phase(LAS unsigned char* lds, const Gemm g, const StaticOrder& S, const Epi& E) {
;     ...
;             PG8_BAR; PG8_WAIT_L(0); PG8_MMA(1, 0, At, B0); PG8_BAR; PG8_SCHED;
;             PG8_STAGE(PG8_SB(0, 1), b2 + hstepB, voffB);
;             PG8_WAIT_V(6); PG8_BAR; PG8_MMA(1, 1, At, B1); PG8_BAR;
;             PG8_LDB(B0, 1, 0); PG8_SCHED; PG8_LDA(At, 1, 0); PG8_STAGE(PG8_SA(0, 1), a2 + hstepA, voffA);
;             PG8_WAIT_L(8); PG8_BAR; PG8_WAIT_L(0); PG8_MMA(0, 0, At, B0); PG8_BAR; PG8_SCHED;
;             PG8_LDB(B1, 1, 1); PG8_STAGE(PG8_SB(1, 0), b3, voffB);
;             PG8_BAR; PG8_WAIT_L(0); PG8_MMA(0, 1, At, B1); PG8_BAR;
	s_setprio 1
	v_mfma_f32_16x16x32_bf16 v[60:63], v[140:143], v[164:167], 0
	v_mfma_f32_16x16x32_bf16 v[56:59], v[156:159], v[164:167], 0
	v_mfma_f32_16x16x32_bf16 v[48:51], v[140:143], v[172:175], 0
	v_mfma_f32_16x16x32_bf16 v[40:43], v[156:159], v[172:175], 0
	v_mfma_f32_16x16x32_bf16 v[28:31], v[140:143], v[180:183], 0
	v_mfma_f32_16x16x32_bf16 v[24:27], v[156:159], v[180:183], 0
	v_mfma_f32_16x16x32_bf16 v[16:19], v[140:143], v[188:191], 0
	v_mfma_f32_16x16x32_bf16 v[8:11], v[156:159], v[188:191], 0
	v_mfma_f32_16x16x32_bf16 v[60:63], v[152:155], v[168:171], v[60:63]
	v_mfma_f32_16x16x32_bf16 v[56:59], v[160:163], v[168:171], v[56:59]
	v_mfma_f32_16x16x32_bf16 v[48:51], v[152:155], v[176:179], v[48:51]
	v_mfma_f32_16x16x32_bf16 v[40:43], v[160:163], v[176:179], v[40:43]
	v_mfma_f32_16x16x32_bf16 v[28:31], v[152:155], v[184:187], v[28:31]
	v_mfma_f32_16x16x32_bf16 v[24:27], v[160:163], v[184:187], v[24:27]
	v_mfma_f32_16x16x32_bf16 v[16:19], v[152:155], v[192:195], v[16:19]
	v_mfma_f32_16x16x32_bf16 v[8:11], v[160:163], v[192:195], v[8:11]
	v_mfma_f32_16x16x32_bf16 v[52:55], v[196:199], v[164:167], 0
	v_mfma_f32_16x16x32_bf16 v[44:47], v[204:207], v[164:167], 0
	v_mfma_f32_16x16x32_bf16 v[36:39], v[196:199], v[172:175], 0
	v_mfma_f32_16x16x32_bf16 v[32:35], v[204:207], v[172:175], 0
	v_mfma_f32_16x16x32_bf16 v[20:23], v[196:199], v[180:183], 0
	v_mfma_f32_16x16x32_bf16 v[12:15], v[204:207], v[180:183], 0
	v_mfma_f32_16x16x32_bf16 v[4:7], v[196:199], v[188:191], 0
	v_mfma_f32_16x16x32_bf16 v[0:3], v[204:207], v[188:191], 0
	v_mfma_f32_16x16x32_bf16 v[52:55], v[200:203], v[168:171], v[52:55]
	v_mfma_f32_16x16x32_bf16 v[44:47], v[208:211], v[168:171], v[44:47]
	v_mfma_f32_16x16x32_bf16 v[36:39], v[200:203], v[176:179], v[36:39]
	v_mfma_f32_16x16x32_bf16 v[32:35], v[208:211], v[176:179], v[32:35]
	v_mfma_f32_16x16x32_bf16 v[20:23], v[200:203], v[184:187], v[20:23]
	v_mfma_f32_16x16x32_bf16 v[12:15], v[208:211], v[184:187], v[12:15]
	v_mfma_f32_16x16x32_bf16 v[4:7], v[200:203], v[192:195], v[4:7]
	v_mfma_f32_16x16x32_bf16 v[0:3], v[208:211], v[192:195], v[0:3]
	s_setprio 0
	s_add_i32 s77, 0, 0x18000
	v_add_u32_e32 v160, s77, v147
	s_barrier
	ds_read_b128 v[140:143], v160
	ds_read_b128 v[152:155], v160 offset:1024
	ds_read_b128 v[156:159], v160 offset:2048
	ds_read_b128 v[160:163], v160 offset:3072
	s_add_u32 s42, s42, 0x40000
	s_addc_u32 s43, s43, 0
	s_mov_b32 m0, s37
	v_lshl_add_u64 v[196:197], s[42:43], 0, v[128:129]
	ds_read_b128 v[164:167], v150 offset:32768
	ds_read_b128 v[168:171], v150 offset:33792
	ds_read_b128 v[172:175], v150 offset:34816
	ds_read_b128 v[176:179], v150 offset:35840
	ds_read_b128 v[180:183], v150 offset:36864
	ds_read_b128 v[184:187], v150 offset:37888
	ds_read_b128 v[188:191], v150 offset:38912
	ds_read_b128 v[192:195], v150 offset:39936
	global_load_lds_dwordx4 v[196:197], off
	v_lshl_add_u64 v[196:197], s[42:43], 0, v[130:131]
	s_mov_b32 m0, s44
	s_nop 0
	global_load_lds_dwordx4 v[196:197], off
	s_add_i32 s42, 0, 0x1c000
	v_add_u32_e32 v208, s42, v147
	ds_read_b128 v[196:199], v208
	ds_read_b128 v[200:203], v208 offset:1024
	ds_read_b128 v[204:207], v208 offset:2048
	ds_read_b128 v[208:211], v208 offset:3072
	s_waitcnt lgkmcnt(0)
	s_barrier
	s_setprio 1
	v_mfma_f32_16x16x32_bf16 v[124:127], v[140:143], v[164:167], v[124:127]
	v_mfma_f32_16x16x32_bf16 v[120:123], v[156:159], v[164:167], v[120:123]
	v_mfma_f32_16x16x32_bf16 v[112:115], v[140:143], v[172:175], v[112:115]
	v_mfma_f32_16x16x32_bf16 v[104:107], v[156:159], v[172:175], v[104:107]
	v_mfma_f32_16x16x32_bf16 v[92:95], v[140:143], v[180:183], v[92:95]
	v_mfma_f32_16x16x32_bf16 v[88:91], v[156:159], v[180:183], v[88:91]
	v_mfma_f32_16x16x32_bf16 v[80:83], v[140:143], v[188:191], v[80:83]
	v_mfma_f32_16x16x32_bf16 v[72:75], v[156:159], v[188:191], v[72:75]
	v_mfma_f32_16x16x32_bf16 v[124:127], v[152:155], v[168:171], v[124:127]
	v_mfma_f32_16x16x32_bf16 v[120:123], v[160:163], v[168:171], v[120:123]
	v_mfma_f32_16x16x32_bf16 v[112:115], v[152:155], v[176:179], v[112:115]
	v_mfma_f32_16x16x32_bf16 v[104:107], v[160:163], v[176:179], v[104:107]
	v_mfma_f32_16x16x32_bf16 v[92:95], v[152:155], v[184:187], v[92:95]
	v_mfma_f32_16x16x32_bf16 v[88:91], v[160:163], v[184:187], v[88:91]
	v_mfma_f32_16x16x32_bf16 v[80:83], v[152:155], v[192:195], v[80:83]
	v_mfma_f32_16x16x32_bf16 v[72:75], v[160:163], v[192:195], v[72:75]
	v_mfma_f32_16x16x32_bf16 v[116:119], v[196:199], v[164:167], v[116:119]
	v_mfma_f32_16x16x32_bf16 v[108:111], v[204:207], v[164:167], v[108:111]
	v_mfma_f32_16x16x32_bf16 v[100:103], v[196:199], v[172:175], v[100:103]
	v_mfma_f32_16x16x32_bf16 v[96:99], v[204:207], v[172:175], v[96:99]
	v_mfma_f32_16x16x32_bf16 v[84:87], v[196:199], v[180:183], v[84:87]
	v_mfma_f32_16x16x32_bf16 v[76:79], v[204:207], v[180:183], v[76:79]
	v_mfma_f32_16x16x32_bf16 v[68:71], v[196:199], v[188:191], v[68:71]
	v_mfma_f32_16x16x32_bf16 v[64:67], v[204:207], v[188:191], v[64:67]
	v_mfma_f32_16x16x32_bf16 v[116:119], v[200:203], v[168:171], v[116:119]
	v_mfma_f32_16x16x32_bf16 v[108:111], v[208:211], v[168:171], v[108:111]
	v_mfma_f32_16x16x32_bf16 v[100:103], v[200:203], v[176:179], v[100:103]
	v_mfma_f32_16x16x32_bf16 v[96:99], v[208:211], v[176:179], v[96:99]
	v_mfma_f32_16x16x32_bf16 v[84:87], v[200:203], v[184:187], v[84:87]
	v_mfma_f32_16x16x32_bf16 v[76:79], v[208:211], v[184:187], v[76:79]
	v_mfma_f32_16x16x32_bf16 v[68:71], v[200:203], v[192:195], v[68:71]
	v_mfma_f32_16x16x32_bf16 v[64:67], v[208:211], v[192:195], v[64:67]
	s_setprio 0
	s_barrier
; #define PG8_STAGE(bufoff, gbase, voff) do { _Pragma("unroll") for (int _i = 0; _i < 2; ++_i) \
;         __builtin_amdgcn_global_load_lds((const unsigned*)((const char*)(gbase) + (voff)[_i]), (LAS unsigned*)(lds + (bufoff) + ldsw + _i * 8192), 16, 0, 0); } while (0)
; #define PG8_LDA(dst, b, h) do { _Pragma("unroll") for (int m = 0; m < 4; ++m) _Pragma("unroll") for (int k = 0; k < 2; ++k) dst[m][k] = *(const LAS bf16x8*)(lds + PG8_SA(b, h) + aoff + m * 2048 + k * 1024); } while (0)
; #define PG8_LDB(dst, b, h) do { _Pragma("unroll") for (int n = 0; n < 2; ++n) _Pragma("unroll") for (int k = 0; k < 2; ++k) dst[n][k] = *(const LAS bf16x8*)(lds + PG8_SB(b, h) + boff + n * 2048 + k * 1024); } while (0)
; #define PG8_MMA(ai, bj, At, Bt) do { __builtin_amdgcn_s_setprio(1); _Pragma("unroll") for (int m = 0; m < 4; ++m) _Pragma("unroll") for (int n = 0; n < 2; ++n) _Pragma("unroll") for (int k = 0; k < 2; ++k) \
;         acc[ai][bj][m][n] = __builtin_amdgcn_mfma_f32_16x16x32_bf16(Bt[n][k], At[m][k], acc[ai][bj][m][n], 0, 0, 0); __builtin_amdgcn_s_setprio(0); } while (0)
; #define PG8_WAIT_V(n) asm volatile("s_waitcnt vmcnt(" #n ")" ::: "memory")
; #define PG8_WAIT_L(n) asm volatile("s_waitcnt lgkmcnt(" #n ")" ::: "memory")
; #define PG8_BAR __builtin_amdgcn_s_barrier()
; #define PG8_SCHED __builtin_amdgcn_sched_barrier(0)
; template <class Epi>
; __device__ __forceinline__ void gemm_phase(LAS unsigned char* lds, const Gemm g, const StaticOrder& S, const Epi& E) {
;     ...
;             PG8_LDB(B1, 1, 1); PG8_STAGE(PG8_SB(1, 0), b3, voffB);
;             PG8_BAR; PG8_WAIT_L(0); PG8_MMA(0, 1, At, B1); PG8_BAR;
;             PG8_LDA(At, 1, 1); PG8_STAGE(PG8_SA(1, 0), a3, voffA);
;             PG8_BAR; PG8_WAIT_L(0); PG8_MMA(1, 0, At, B0); PG8_BAR; PG8_SCHED;
;             PG8_STAGE(PG8_SB(1, 1), b3 + hstepB, voffB);
;             PG8_WAIT_V(6); PG8_BAR; PG8_MMA(1, 1, At, B1); PG8_BAR;
	s_nop 1
	ds_read_b128 v[164:167], v150 offset:49152
	ds_read_b128 v[168:171], v150 offset:50176
	ds_read_b128 v[172:175], v150 offset:51200
	ds_read_b128 v[176:179], v150 offset:52224
	ds_read_b128 v[180:183], v150 offset:53248
	ds_read_b128 v[184:187], v150 offset:54272
	ds_read_b128 v[188:191], v150 offset:55296
	ds_read_b128 v[192:195], v150 offset:56320
	s_add_i32 s43, s77, s7
	v_lshl_add_u64 v[254:255], v[144:145], 0, s[12:13]
	s_mov_b32 m0, s43
	s_nop 0
	global_load_lds_dwordx4 v[254:255], off
	v_lshl_add_u64 v[254:255], v[212:213], 0, s[12:13]
	s_add_i32 m0, s43, 0x2000
	s_nop 0
	global_load_lds_dwordx4 v[254:255], off
	s_mov_b32 m0, s46
	v_lshl_add_u64 v[254:255], v[214:215], 0, s[12:13]
	global_load_lds_dwordx4 v[254:255], off
	v_lshl_add_u64 v[144:145], v[216:217], 0, s[12:13]
	s_mov_b32 m0, s47
	s_nop 0
	global_load_lds_dwordx4 v[144:145], off
	s_add_u32 s40, s40, 0x40080
	s_addc_u32 s41, s41, 0
	s_add_i32 s42, s42, s7
	v_lshl_add_u64 v[254:255], s[40:41], 0, v[128:129]
	s_mov_b32 m0, s42
	s_nop 0
	global_load_lds_dwordx4 v[254:255], off
	v_lshl_add_u64 v[254:255], s[40:41], 0, v[130:131]
	s_add_i32 m0, s42, 0x2000
	s_nop 0
	global_load_lds_dwordx4 v[254:255], off
	s_waitcnt vmcnt(6)
	s_waitcnt lgkmcnt(0)
	s_barrier
	s_setprio 1
	v_mfma_f32_16x16x32_bf16 v[60:63], v[140:143], v[164:167], v[60:63]
	v_mfma_f32_16x16x32_bf16 v[56:59], v[156:159], v[164:167], v[56:59]
	v_mfma_f32_16x16x32_bf16 v[48:51], v[140:143], v[172:175], v[48:51]
	v_mfma_f32_16x16x32_bf16 v[40:43], v[156:159], v[172:175], v[40:43]
	v_mfma_f32_16x16x32_bf16 v[28:31], v[140:143], v[180:183], v[28:31]
	v_mfma_f32_16x16x32_bf16 v[24:27], v[156:159], v[180:183], v[24:27]
	v_mfma_f32_16x16x32_bf16 v[16:19], v[140:143], v[188:191], v[16:19]
	v_mfma_f32_16x16x32_bf16 v[8:11], v[156:159], v[188:191], v[8:11]
	v_mfma_f32_16x16x32_bf16 v[60:63], v[152:155], v[168:171], v[60:63]
	v_mfma_f32_16x16x32_bf16 v[56:59], v[160:163], v[168:171], v[56:59]
	v_mfma_f32_16x16x32_bf16 v[48:51], v[152:155], v[176:179], v[48:51]
	v_mfma_f32_16x16x32_bf16 v[40:43], v[160:163], v[176:179], v[40:43]
	v_mfma_f32_16x16x32_bf16 v[28:31], v[152:155], v[184:187], v[28:31]
	v_mfma_f32_16x16x32_bf16 v[24:27], v[160:163], v[184:187], v[24:27]
	v_mfma_f32_16x16x32_bf16 v[16:19], v[152:155], v[192:195], v[16:19]
	v_mfma_f32_16x16x32_bf16 v[8:11], v[160:163], v[192:195], v[8:11]
	v_mfma_f32_16x16x32_bf16 v[52:55], v[196:199], v[164:167], v[52:55]
	v_mfma_f32_16x16x32_bf16 v[44:47], v[204:207], v[164:167], v[44:47]
	v_mfma_f32_16x16x32_bf16 v[36:39], v[196:199], v[172:175], v[36:39]
	v_mfma_f32_16x16x32_bf16 v[32:35], v[204:207], v[172:175], v[32:35]
	v_mfma_f32_16x16x32_bf16 v[20:23], v[196:199], v[180:183], v[20:23]
	v_mfma_f32_16x16x32_bf16 v[12:15], v[204:207], v[180:183], v[12:15]
	v_mfma_f32_16x16x32_bf16 v[4:7], v[196:199], v[188:191], v[4:7]
	v_mfma_f32_16x16x32_bf16 v[0:3], v[204:207], v[188:191], v[0:3]
	v_mfma_f32_16x16x32_bf16 v[52:55], v[200:203], v[168:171], v[52:55]
	v_mfma_f32_16x16x32_bf16 v[44:47], v[208:211], v[168:171], v[44:47]
	v_mfma_f32_16x16x32_bf16 v[36:39], v[200:203], v[176:179], v[36:39]
	v_mfma_f32_16x16x32_bf16 v[32:35], v[208:211], v[176:179], v[32:35]
	v_mfma_f32_16x16x32_bf16 v[20:23], v[200:203], v[184:187], v[20:23]
	v_mfma_f32_16x16x32_bf16 v[12:15], v[208:211], v[184:187], v[12:15]
	v_mfma_f32_16x16x32_bf16 v[4:7], v[200:203], v[192:195], v[4:7]
	v_mfma_f32_16x16x32_bf16 v[0:3], v[208:211], v[192:195], v[0:3]
	s_setprio 0
	s_add_i32 s76, s76, 2
	s_add_u32 s38, s38, 0x100
	s_addc_u32 s39, s39, 0
	s_add_u32 s74, s74, 0x100
	s_addc_u32 s75, s75, 0
	s_cmp_gt_u32 s76, 13
	s_barrier

; #define PG8_STAGE(bufoff, gbase, voff) do { _Pragma("unroll") for (int _i = 0; _i < 2; ++_i) \
;         __builtin_amdgcn_global_load_lds((const unsigned*)((const char*)(gbase) + (voff)[_i]), (LAS unsigned*)(lds + (bufoff) + ldsw + _i * 8192), 16, 0, 0); } while (0)
; #define PG8_LDA(dst, b, h) do { _Pragma("unroll") for (int m = 0; m < 4; ++m) _Pragma("unroll") for (int k = 0; k < 2; ++k) dst[m][k] = *(const LAS bf16x8*)(lds + PG8_SA(b, h) + aoff + m * 2048 + k * 1024); } while (0)
; #define PG8_LDB(dst, b, h) do { _Pragma("unroll") for (int n = 0; n < 2; ++n) _Pragma("unroll") for (int k = 0; k < 2; ++k) dst[n][k] = *(const LAS bf16x8*)(lds + PG8_SB(b, h) + boff + n * 2048 + k * 1024); } while (0)
; #define PG8_WAIT_V(n) asm volatile("s_waitcnt vmcnt(" #n ")" ::: "memory")
; #define PG8_WAIT_L(n) asm volatile("s_waitcnt lgkmcnt(" #n ")" ::: "memory")
; #define PG8_BAR __builtin_amdgcn_s_barrier()
; #define PG8_SCHED __builtin_amdgcn_sched_barrier(0)
; template <class Epi>
; __device__ __forceinline__ void gemm_phase(LAS unsigned char* lds, const Gemm g, const StaticOrder& S, const Epi& E) {
;     ...
;         const bool has_next = S.next(ui + 1, nxt);
;         const char* nA = has_next ? (const char*)g.A + (size_t)nxt.pm * tstepA + (size_t)(nxt.pn >> g.a_shift) * g.a_step : cA; const char* nB = has_next ? (const char*)g.Bt + (size_t)nxt.pn * tstepB : cB;
;         for (int t = 0; t < nt; t += 2) {
;             const bool last = (t == nt - 2);
;             const char* a1 = cA + (size_t)(t + 1) * kstep;
;             const char* a2 = last ? nA : cA + (size_t)(t + 2) * kstep; const char* b2 = last ? nB : cB + (size_t)(t + 2) * kstep;
;             const char* a3 = a2 + kstep; const char* b3 = b2 + kstep;
;             PG8_LDB(B0, 0, 0); PG8_SCHED; PG8_LDA(At, 0, 0); PG8_STAGE(PG8_SA(1, 1), a1 + hstepA, voffA);
;             PG8_WAIT_L(8); PG8_BAR; PG8_WAIT_L(0); PG8_MMA(0, 0, At, B0); PG8_BAR; PG8_SCHED;
;             PG8_LDB(B1, 0, 1); PG8_STAGE(PG8_SB(0, 0), b2, voffB);
;             PG8_BAR; PG8_WAIT_L(0); PG8_MMA(0, 1, At, B1); PG8_BAR;
;             PG8_LDA(At, 0, 1); PG8_STAGE(PG8_SA(0, 0), a2, voffA);
;             PG8_BAR; PG8_WAIT_L(0); PG8_MMA(1, 0, At, B0); PG8_BAR; PG8_SCHED;
;             PG8_STAGE(PG8_SB(0, 1), b2 + hstepB, voffB);
;             PG8_WAIT_V(6); PG8_BAR; PG8_MMA(1, 1, At, B1); PG8_BAR;
.LBB0_1358:
	s_ashr_i32 s37, s36, 31
	v_cmp_lt_i64_e32 vcc, s[38:39], v[228:229]
	s_lshl_b64 s[38:39], s[36:37], 19
	s_add_u32 s38, s66, s38
	s_addc_u32 s39, s67, s39
	s_and_b64 s[40:41], vcc, exec
	s_cselect_b32 s37, s39, s45
	s_cselect_b32 s83, s38, s44
	s_ashr_i32 s35, s34, 31
	s_lshl_b64 s[40:41], s[34:35], 19
	s_add_u32 s40, s5, s40
	s_addc_u32 s41, s6, s41
	s_and_b64 s[48:49], vcc, exec
	s_cselect_b32 s35, s41, s47
	s_cselect_b32 s84, s40, s46
	s_add_u32 s85, s46, 0x100
	s_addc_u32 s86, s47, 0
	s_mov_b32 s87, -2
	ds_read_b128 v[96:99], v243
	ds_read_b128 v[100:103], v243 offset:1024
	ds_read_b128 v[104:107], v243 offset:2048
	ds_read_b128 v[108:111], v243 offset:3072
	s_add_u32 s46, s44, 0x100
	s_addc_u32 s47, s45, 0
	s_cmp_eq_u32 s87, 12
	s_cselect_b32 s73, s37, s47
	s_cselect_b32 s72, s83, s46
	s_cselect_b32 s49, s35, s86
	s_cselect_b32 s48, s84, s85
	v_lshl_add_u64 v[176:177], s[44:45], 0, v[224:225]
	s_add_i32 m0, s9, 0xc000
	ds_read_b128 v[112:115], v244
	ds_read_b128 v[116:119], v244 offset:1024
	ds_read_b128 v[120:123], v244 offset:2048
	ds_read_b128 v[124:127], v244 offset:3072
	ds_read_b128 v[160:163], v244 offset:4096
	ds_read_b128 v[164:167], v244 offset:5120
	ds_read_b128 v[168:171], v244 offset:6144
	ds_read_b128 v[172:175], v244 offset:7168
	global_load_lds_dwordx4 v[176:177], off
	v_lshl_add_u64 v[176:177], s[44:45], 0, v[226:227]
	s_add_i32 m0, s9, 0xe000
	s_nop 0
	global_load_lds_dwordx4 v[176:177], off
	ds_read_b128 v[176:179], v245
	ds_read_b128 v[180:183], v245 offset:1024
	ds_read_b128 v[184:187], v245 offset:2048
	ds_read_b128 v[188:191], v245 offset:3072
	s_waitcnt lgkmcnt(0)
	s_barrier
	s_setprio 1
	v_mfma_f32_16x16x32_bf16 v[156:159], v[96:99], v[112:115], 0
	v_mfma_f32_16x16x32_bf16 v[60:63], v[104:107], v[112:115], 0
	v_mfma_f32_16x16x32_bf16 v[144:147], v[96:99], v[120:123], 0
	v_mfma_f32_16x16x32_bf16 v[48:51], v[104:107], v[120:123], 0
	v_mfma_f32_16x16x32_bf16 v[136:139], v[96:99], v[160:163], 0
	v_mfma_f32_16x16x32_bf16 v[40:43], v[104:107], v[160:163], 0
	v_mfma_f32_16x16x32_bf16 v[148:151], v[96:99], v[168:171], 0
	v_mfma_f32_16x16x32_bf16 v[52:55], v[104:107], v[168:171], 0
	v_mfma_f32_16x16x32_bf16 v[156:159], v[100:103], v[116:119], v[156:159]
	v_mfma_f32_16x16x32_bf16 v[60:63], v[108:111], v[116:119], v[60:63]
	v_mfma_f32_16x16x32_bf16 v[144:147], v[100:103], v[124:127], v[144:147]
	v_mfma_f32_16x16x32_bf16 v[48:51], v[108:111], v[124:127], v[48:51]
	v_mfma_f32_16x16x32_bf16 v[136:139], v[100:103], v[164:167], v[136:139]
	v_mfma_f32_16x16x32_bf16 v[40:43], v[108:111], v[164:167], v[40:43]
	v_mfma_f32_16x16x32_bf16 v[148:151], v[100:103], v[172:175], v[148:151]
	v_mfma_f32_16x16x32_bf16 v[52:55], v[108:111], v[172:175], v[52:55]
	v_mfma_f32_16x16x32_bf16 v[152:155], v[176:179], v[112:115], 0
	v_mfma_f32_16x16x32_bf16 v[56:59], v[184:187], v[112:115], 0
	v_mfma_f32_16x16x32_bf16 v[36:39], v[184:187], v[120:123], 0
	v_mfma_f32_16x16x32_bf16 v[32:35], v[184:187], v[160:163], 0
	v_mfma_f32_16x16x32_bf16 v[44:47], v[184:187], v[168:171], 0
	v_mfma_f32_16x16x32_bf16 v[152:155], v[180:183], v[116:119], v[152:155]
	v_mfma_f32_16x16x32_bf16 v[56:59], v[188:191], v[116:119], v[56:59]
	v_mfma_f32_16x16x32_bf16 v[112:115], v[176:179], v[120:123], 0
	v_mfma_f32_16x16x32_bf16 v[36:39], v[188:191], v[124:127], v[36:39]
	v_mfma_f32_16x16x32_bf16 v[116:119], v[176:179], v[160:163], 0
	v_mfma_f32_16x16x32_bf16 v[32:35], v[188:191], v[164:167], v[32:35]
	v_mfma_f32_16x16x32_bf16 v[120:123], v[176:179], v[168:171], 0
	v_mfma_f32_16x16x32_bf16 v[44:47], v[188:191], v[172:175], v[44:47]
	v_mfma_f32_16x16x32_bf16 v[112:115], v[180:183], v[124:127], v[112:115]
	v_mfma_f32_16x16x32_bf16 v[116:119], v[180:183], v[164:167], v[116:119]
	v_mfma_f32_16x16x32_bf16 v[120:123], v[180:183], v[172:175], v[120:123]
	s_setprio 0
	s_barrier
	s_nop 1
	ds_read_b128 v[124:127], v244 offset:16384
	ds_read_b128 v[128:131], v244 offset:17408
	ds_read_b128 v[132:135], v244 offset:18432
	ds_read_b128 v[140:143], v244 offset:19456
	ds_read_b128 v[160:163], v244 offset:20480
	ds_read_b128 v[164:167], v244 offset:21504
	ds_read_b128 v[168:171], v244 offset:22528
	ds_read_b128 v[172:175], v244 offset:23552
	s_add_i32 s44, s80, s7
	v_lshl_add_u64 v[196:197], s[48:49], 0, v[214:215]
	s_mov_b32 m0, s44
	s_nop 0
	global_load_lds_dwordx4 v[196:197], off
	v_lshl_add_u64 v[198:199], s[48:49], 0, v[210:211]
	s_add_i32 m0, s44, 0x2000
	s_nop 0
	global_load_lds_dwordx4 v[198:199], off
	s_mov_b32 m0, s9
	v_lshl_add_u64 v[200:201], s[72:73], 0, v[216:217]
	global_load_lds_dwordx4 v[200:201], off
	v_lshl_add_u64 v[202:203], s[72:73], 0, v[212:213]
	s_mov_b32 m0, s63
	s_nop 0
	global_load_lds_dwordx4 v[202:203], off
	s_add_u32 s44, s48, 0x40000
	s_addc_u32 s45, s49, 0
	s_add_i32 s88, s81, s7
	v_lshl_add_u64 v[254:255], s[44:45], 0, v[214:215]
	s_mov_b32 m0, s88
	s_nop 0
	global_load_lds_dwordx4 v[254:255], off
	v_lshl_add_u64 v[254:255], s[44:45], 0, v[210:211]
	s_add_i32 m0, s88, 0x2000
	s_nop 0
	global_load_lds_dwordx4 v[254:255], off
	s_waitcnt vmcnt(6)
	s_waitcnt lgkmcnt(0)
	s_barrier
; #define PG8_STAGE(bufoff, gbase, voff) do { _Pragma("unroll") for (int _i = 0; _i < 2; ++_i) \
;         __builtin_amdgcn_global_load_lds((const unsigned*)((const char*)(gbase) + (voff)[_i]), (LAS unsigned*)(lds + (bufoff) + ldsw + _i * 8192), 16, 0, 0); } while (0)
; #define PG8_LDA(dst, b, h) do { _Pragma("unroll") for (int m = 0; m < 4; ++m) _Pragma("unroll") for (int k = 0; k < 2; ++k) dst[m][k] = *(const LAS bf16x8*)(lds + PG8_SA(b, h) + aoff + m * 2048 + k * 1024); } while (0)
; #define PG8_LDB(dst, b, h) do { _Pragma("unroll") for (int n = 0; n < 2; ++n) _Pragma("unroll") for (int k = 0; k < 2; ++k) dst[n][k] = *(const LAS bf16x8*)(lds + PG8_SB(b, h) + boff + n * 2048 + k * 1024); } while (0)
; #define PG8_MMA(ai, bj, At, Bt) do { __builtin_amdgcn_s_setprio(1); _Pragma("unroll") for (int m = 0; m < 4; ++m) _Pragma("unroll") for (int n = 0; n < 2; ++n) _Pragma("unroll") for (int k = 0; k < 2; ++k) \
;         acc[ai][bj][m][n] = __builtin_amdgcn_mfma_f32_16x16x32_bf16(Bt[n][k], At[m][k], acc[ai][bj][m][n], 0, 0, 0); __builtin_amdgcn_s_setprio(0); } while (0)
; #define PG8_WAIT_V(n) asm volatile("s_waitcnt vmcnt(" #n ")" ::: "memory")
; #define PG8_WAIT_L(n) asm volatile("s_waitcnt lgkmcnt(" #n ")" ::: "memory")
; #define PG8_BAR __builtin_amdgcn_s_barrier()
; #define PG8_SCHED __builtin_amdgcn_sched_barrier(0)
; template <class Epi>
; __device__ __forceinline__ void gemm_phase(LAS unsigned char* lds, const Gemm g, const StaticOrder& S, const Epi& E) {
;     ...
;             PG8_BAR; PG8_WAIT_L(0); PG8_MMA(1, 0, At, B0); PG8_BAR; PG8_SCHED;
;             PG8_STAGE(PG8_SB(0, 1), b2 + hstepB, voffB);
;             PG8_WAIT_V(6); PG8_BAR; PG8_MMA(1, 1, At, B1); PG8_BAR;
;             PG8_LDB(B0, 1, 0); PG8_SCHED; PG8_LDA(At, 1, 0); PG8_STAGE(PG8_SA(0, 1), a2 + hstepA, voffA);
;             PG8_WAIT_L(8); PG8_BAR; PG8_WAIT_L(0); PG8_MMA(0, 0, At, B0); PG8_BAR; PG8_SCHED;
;             PG8_LDB(B1, 1, 1); PG8_STAGE(PG8_SB(1, 0), b3, voffB);
;             PG8_BAR; PG8_WAIT_L(0); PG8_MMA(0, 1, At, B1); PG8_BAR;
	s_setprio 1
	v_mfma_f32_16x16x32_bf16 v[92:95], v[96:99], v[124:127], 0
	v_mfma_f32_16x16x32_bf16 v[28:31], v[104:107], v[124:127], 0
	v_mfma_f32_16x16x32_bf16 v[80:83], v[96:99], v[132:135], 0
	v_mfma_f32_16x16x32_bf16 v[16:19], v[104:107], v[132:135], 0
	v_mfma_f32_16x16x32_bf16 v[76:79], v[96:99], v[160:163], 0
	v_mfma_f32_16x16x32_bf16 v[12:15], v[104:107], v[160:163], 0
	v_mfma_f32_16x16x32_bf16 v[84:87], v[96:99], v[168:171], 0
	v_mfma_f32_16x16x32_bf16 v[20:23], v[104:107], v[168:171], 0
	v_mfma_f32_16x16x32_bf16 v[92:95], v[100:103], v[128:131], v[92:95]
	v_mfma_f32_16x16x32_bf16 v[28:31], v[108:111], v[128:131], v[28:31]
	v_mfma_f32_16x16x32_bf16 v[80:83], v[100:103], v[140:143], v[80:83]
	v_mfma_f32_16x16x32_bf16 v[16:19], v[108:111], v[140:143], v[16:19]
	v_mfma_f32_16x16x32_bf16 v[76:79], v[100:103], v[164:167], v[76:79]
	v_mfma_f32_16x16x32_bf16 v[12:15], v[108:111], v[164:167], v[12:15]
	v_mfma_f32_16x16x32_bf16 v[84:87], v[100:103], v[172:175], v[84:87]
	v_mfma_f32_16x16x32_bf16 v[20:23], v[108:111], v[172:175], v[20:23]
	v_mfma_f32_16x16x32_bf16 v[88:91], v[176:179], v[124:127], 0
	v_mfma_f32_16x16x32_bf16 v[24:27], v[184:187], v[124:127], 0
	v_mfma_f32_16x16x32_bf16 v[68:71], v[176:179], v[132:135], 0
	v_mfma_f32_16x16x32_bf16 v[4:7], v[184:187], v[132:135], 0
	v_mfma_f32_16x16x32_bf16 v[64:67], v[176:179], v[160:163], 0
	v_mfma_f32_16x16x32_bf16 v[0:3], v[184:187], v[160:163], 0
	v_mfma_f32_16x16x32_bf16 v[72:75], v[176:179], v[168:171], 0
	v_mfma_f32_16x16x32_bf16 v[8:11], v[184:187], v[168:171], 0
	v_mfma_f32_16x16x32_bf16 v[88:91], v[180:183], v[128:131], v[88:91]
	v_mfma_f32_16x16x32_bf16 v[24:27], v[188:191], v[128:131], v[24:27]
	v_mfma_f32_16x16x32_bf16 v[68:71], v[180:183], v[140:143], v[68:71]
	v_mfma_f32_16x16x32_bf16 v[4:7], v[188:191], v[140:143], v[4:7]
	v_mfma_f32_16x16x32_bf16 v[64:67], v[180:183], v[164:167], v[64:67]
	v_mfma_f32_16x16x32_bf16 v[0:3], v[188:191], v[164:167], v[0:3]
	v_mfma_f32_16x16x32_bf16 v[72:75], v[180:183], v[172:175], v[72:75]
	v_mfma_f32_16x16x32_bf16 v[8:11], v[188:191], v[172:175], v[8:11]
	s_setprio 0
	s_add_i32 s88, 0, 0x18000
	v_add_u32_e32 v108, s88, v235
	s_barrier
	ds_read_b128 v[96:99], v108
	ds_read_b128 v[100:103], v108 offset:1024
	ds_read_b128 v[104:107], v108 offset:2048
	ds_read_b128 v[108:111], v108 offset:3072
	s_add_u32 s44, s72, 0x40000
	s_addc_u32 s45, s73, 0
	s_mov_b32 m0, s74
	v_lshl_add_u64 v[132:133], s[44:45], 0, v[216:217]
	ds_read_b128 v[124:127], v244 offset:32768
	ds_read_b128 v[128:131], v244 offset:33792
	ds_read_b128 v[140:143], v244 offset:34816
	ds_read_b128 v[160:163], v244 offset:35840
	ds_read_b128 v[164:167], v244 offset:36864
	ds_read_b128 v[168:171], v244 offset:37888
	ds_read_b128 v[172:175], v244 offset:38912
	ds_read_b128 v[176:179], v244 offset:39936
	global_load_lds_dwordx4 v[132:133], off
	v_lshl_add_u64 v[132:133], s[44:45], 0, v[212:213]
	s_mov_b32 m0, s75
	s_nop 0
	global_load_lds_dwordx4 v[132:133], off
	s_add_i32 s72, 0, 0x1c000
	v_add_u32_e32 v132, s72, v235
	ds_read_b128 v[180:183], v132
	ds_read_b128 v[184:187], v132 offset:1024
	ds_read_b128 v[188:191], v132 offset:2048
	ds_read_b128 v[192:195], v132 offset:3072
	s_waitcnt lgkmcnt(0)
	s_barrier
	s_setprio 1
	v_mfma_f32_16x16x32_bf16 v[132:135], v[96:99], v[124:127], v[156:159]
	v_mfma_f32_16x16x32_bf16 v[156:159], v[100:103], v[128:131], v[132:135]
	v_mfma_f32_16x16x32_bf16 v[132:135], v[96:99], v[140:143], v[144:147]
	v_mfma_f32_16x16x32_bf16 v[144:147], v[100:103], v[160:163], v[132:135]
	v_mfma_f32_16x16x32_bf16 v[132:135], v[96:99], v[164:167], v[136:139]
	v_mfma_f32_16x16x32_bf16 v[60:63], v[104:107], v[124:127], v[60:63]
	v_mfma_f32_16x16x32_bf16 v[48:51], v[104:107], v[140:143], v[48:51]
	v_mfma_f32_16x16x32_bf16 v[136:139], v[100:103], v[168:171], v[132:135]
	v_mfma_f32_16x16x32_bf16 v[40:43], v[104:107], v[164:167], v[40:43]
	v_mfma_f32_16x16x32_bf16 v[132:135], v[96:99], v[172:175], v[148:151]
	v_mfma_f32_16x16x32_bf16 v[52:55], v[104:107], v[172:175], v[52:55]
	v_mfma_f32_16x16x32_bf16 v[60:63], v[108:111], v[128:131], v[60:63]
	v_mfma_f32_16x16x32_bf16 v[48:51], v[108:111], v[160:163], v[48:51]
	v_mfma_f32_16x16x32_bf16 v[40:43], v[108:111], v[168:171], v[40:43]
	v_mfma_f32_16x16x32_bf16 v[148:151], v[100:103], v[176:179], v[132:135]
	v_mfma_f32_16x16x32_bf16 v[52:55], v[108:111], v[176:179], v[52:55]
	v_mfma_f32_16x16x32_bf16 v[132:135], v[180:183], v[124:127], v[152:155]
	v_mfma_f32_16x16x32_bf16 v[112:115], v[180:183], v[140:143], v[112:115]
	v_mfma_f32_16x16x32_bf16 v[152:155], v[184:187], v[128:131], v[132:135]
	v_mfma_f32_16x16x32_bf16 v[56:59], v[188:191], v[124:127], v[56:59]
	v_mfma_f32_16x16x32_bf16 v[132:135], v[184:187], v[160:163], v[112:115]
	v_mfma_f32_16x16x32_bf16 v[112:115], v[180:183], v[164:167], v[116:119]
	v_mfma_f32_16x16x32_bf16 v[56:59], v[192:195], v[128:131], v[56:59]
	v_mfma_f32_16x16x32_bf16 v[36:39], v[188:191], v[140:143], v[36:39]
	v_mfma_f32_16x16x32_bf16 v[128:131], v[184:187], v[168:171], v[112:115]
	v_mfma_f32_16x16x32_bf16 v[32:35], v[188:191], v[164:167], v[32:35]
	v_mfma_f32_16x16x32_bf16 v[112:115], v[180:183], v[172:175], v[120:123]
	v_mfma_f32_16x16x32_bf16 v[44:47], v[188:191], v[172:175], v[44:47]
	v_mfma_f32_16x16x32_bf16 v[36:39], v[192:195], v[160:163], v[36:39]
	v_mfma_f32_16x16x32_bf16 v[32:35], v[192:195], v[168:171], v[32:35]
	v_mfma_f32_16x16x32_bf16 v[140:143], v[184:187], v[176:179], v[112:115]
	v_mfma_f32_16x16x32_bf16 v[44:47], v[192:195], v[176:179], v[44:47]
	s_setprio 0
	s_barrier
; #define PG8_STAGE(bufoff, gbase, voff) do { _Pragma("unroll") for (int _i = 0; _i < 2; ++_i) \
;         __builtin_amdgcn_global_load_lds((const unsigned*)((const char*)(gbase) + (voff)[_i]), (LAS unsigned*)(lds + (bufoff) + ldsw + _i * 8192), 16, 0, 0); } while (0)
; #define PG8_LDA(dst, b, h) do { _Pragma("unroll") for (int m = 0; m < 4; ++m) _Pragma("unroll") for (int k = 0; k < 2; ++k) dst[m][k] = *(const LAS bf16x8*)(lds + PG8_SA(b, h) + aoff + m * 2048 + k * 1024); } while (0)
; #define PG8_MMA(ai, bj, At, Bt) do { __builtin_amdgcn_s_setprio(1); _Pragma("unroll") for (int m = 0; m < 4; ++m) _Pragma("unroll") for (int n = 0; n < 2; ++n) _Pragma("unroll") for (int k = 0; k < 2; ++k) \
;         acc[ai][bj][m][n] = __builtin_amdgcn_mfma_f32_16x16x32_bf16(Bt[n][k], At[m][k], acc[ai][bj][m][n], 0, 0, 0); __builtin_amdgcn_s_setprio(0); } while (0)
; #define PG8_WAIT_V(n) asm volatile("s_waitcnt vmcnt(" #n ")" ::: "memory")
; #define PG8_WAIT_L(n) asm volatile("s_waitcnt lgkmcnt(" #n ")" ::: "memory")
; #define PG8_BAR __builtin_amdgcn_s_barrier()
; #define PG8_SCHED __builtin_amdgcn_sched_barrier(0)
; template <class Epi>
; __device__ __forceinline__ void gemm_phase(LAS unsigned char* lds, const Gemm g, const StaticOrder& S, const Epi& E) {
;     ...
;             PG8_LDA(At, 1, 1); PG8_STAGE(PG8_SA(1, 0), a3, voffA);
;             PG8_BAR; PG8_WAIT_L(0); PG8_MMA(1, 0, At, B0); PG8_BAR; PG8_SCHED;
;             PG8_STAGE(PG8_SB(1, 1), b3 + hstepB, voffB);
;             PG8_WAIT_V(6); PG8_BAR; PG8_MMA(1, 1, At, B1); PG8_BAR;
	s_nop 1
	ds_read_b128 v[112:115], v244 offset:49152
	ds_read_b128 v[116:119], v244 offset:50176
	ds_read_b128 v[120:123], v244 offset:51200
	ds_read_b128 v[124:127], v244 offset:52224
	ds_read_b128 v[160:163], v244 offset:53248
	ds_read_b128 v[164:167], v244 offset:54272
	ds_read_b128 v[168:171], v244 offset:55296
	ds_read_b128 v[172:175], v244 offset:56320
	s_add_i32 s44, s88, s7
	v_lshl_add_u64 v[254:255], v[196:197], 0, s[24:25]
	s_mov_b32 m0, s44
	s_nop 0
	global_load_lds_dwordx4 v[254:255], off
	v_lshl_add_u64 v[254:255], v[198:199], 0, s[24:25]
	s_add_i32 m0, s44, 0x2000
	s_nop 0
	global_load_lds_dwordx4 v[254:255], off
	s_mov_b32 m0, s78
	v_lshl_add_u64 v[254:255], v[200:201], 0, s[24:25]
	global_load_lds_dwordx4 v[254:255], off
	v_lshl_add_u64 v[254:255], v[202:203], 0, s[24:25]
	s_mov_b32 m0, s79
	s_nop 0
	global_load_lds_dwordx4 v[254:255], off
	s_add_u32 s44, s48, 0x40080
	s_addc_u32 s45, s49, 0
	s_add_i32 s48, s72, s7
	v_lshl_add_u64 v[254:255], s[44:45], 0, v[214:215]
	s_mov_b32 m0, s48
	s_nop 0
	global_load_lds_dwordx4 v[254:255], off
	v_lshl_add_u64 v[254:255], s[44:45], 0, v[210:211]
	s_add_i32 m0, s48, 0x2000
	s_nop 0
	global_load_lds_dwordx4 v[254:255], off
	s_waitcnt vmcnt(6)
	s_waitcnt lgkmcnt(0)
	s_barrier
	s_setprio 1
	v_mfma_f32_16x16x32_bf16 v[92:95], v[96:99], v[112:115], v[92:95]
	v_mfma_f32_16x16x32_bf16 v[28:31], v[104:107], v[112:115], v[28:31]
	v_mfma_f32_16x16x32_bf16 v[80:83], v[96:99], v[120:123], v[80:83]
	v_mfma_f32_16x16x32_bf16 v[16:19], v[104:107], v[120:123], v[16:19]
	v_mfma_f32_16x16x32_bf16 v[76:79], v[96:99], v[160:163], v[76:79]
	v_mfma_f32_16x16x32_bf16 v[12:15], v[104:107], v[160:163], v[12:15]
	v_mfma_f32_16x16x32_bf16 v[84:87], v[96:99], v[168:171], v[84:87]
	v_mfma_f32_16x16x32_bf16 v[20:23], v[104:107], v[168:171], v[20:23]
	v_mfma_f32_16x16x32_bf16 v[92:95], v[100:103], v[116:119], v[92:95]
	v_mfma_f32_16x16x32_bf16 v[28:31], v[108:111], v[116:119], v[28:31]
	v_mfma_f32_16x16x32_bf16 v[80:83], v[100:103], v[124:127], v[80:83]
	v_mfma_f32_16x16x32_bf16 v[16:19], v[108:111], v[124:127], v[16:19]
	v_mfma_f32_16x16x32_bf16 v[76:79], v[100:103], v[164:167], v[76:79]
	v_mfma_f32_16x16x32_bf16 v[12:15], v[108:111], v[164:167], v[12:15]
	v_mfma_f32_16x16x32_bf16 v[84:87], v[100:103], v[172:175], v[84:87]
	v_mfma_f32_16x16x32_bf16 v[20:23], v[108:111], v[172:175], v[20:23]
	v_mfma_f32_16x16x32_bf16 v[88:91], v[180:183], v[112:115], v[88:91]
	v_mfma_f32_16x16x32_bf16 v[24:27], v[188:191], v[112:115], v[24:27]
	v_mfma_f32_16x16x32_bf16 v[68:71], v[180:183], v[120:123], v[68:71]
	v_mfma_f32_16x16x32_bf16 v[4:7], v[188:191], v[120:123], v[4:7]
	v_mfma_f32_16x16x32_bf16 v[64:67], v[180:183], v[160:163], v[64:67]
	v_mfma_f32_16x16x32_bf16 v[0:3], v[188:191], v[160:163], v[0:3]
	v_mfma_f32_16x16x32_bf16 v[72:75], v[180:183], v[168:171], v[72:75]
	v_mfma_f32_16x16x32_bf16 v[8:11], v[188:191], v[168:171], v[8:11]
	v_mfma_f32_16x16x32_bf16 v[88:91], v[184:187], v[116:119], v[88:91]
	v_mfma_f32_16x16x32_bf16 v[24:27], v[192:195], v[116:119], v[24:27]
	v_mfma_f32_16x16x32_bf16 v[68:71], v[184:187], v[124:127], v[68:71]
	v_mfma_f32_16x16x32_bf16 v[4:7], v[192:195], v[124:127], v[4:7]
	v_mfma_f32_16x16x32_bf16 v[64:67], v[184:187], v[164:167], v[64:67]
	v_mfma_f32_16x16x32_bf16 v[0:3], v[192:195], v[164:167], v[0:3]
	v_mfma_f32_16x16x32_bf16 v[72:75], v[184:187], v[172:175], v[72:75]
	v_mfma_f32_16x16x32_bf16 v[8:11], v[192:195], v[172:175], v[8:11]
	s_setprio 0
	s_add_i32 s87, s87, 2
	s_add_u32 s85, s85, 0x100
	s_addc_u32 s86, s86, 0
	s_cmp_gt_u32 s87, 13
	s_mov_b64 s[44:45], s[46:47]
	s_barrier

; #define PG8_STAGE(bufoff, gbase, voff) do { _Pragma("unroll") for (int _i = 0; _i < 2; ++_i) \
;         __builtin_amdgcn_global_load_lds((const unsigned*)((const char*)(gbase) + (voff)[_i]), (LAS unsigned*)(lds + (bufoff) + ldsw + _i * 8192), 16, 0, 0); } while (0)
; #define PG8_LDA(dst, b, h) do { _Pragma("unroll") for (int m = 0; m < 4; ++m) _Pragma("unroll") for (int k = 0; k < 2; ++k) dst[m][k] = *(const LAS bf16x8*)(lds + PG8_SA(b, h) + aoff + m * 2048 + k * 1024); } while (0)
; #define PG8_LDB(dst, b, h) do { _Pragma("unroll") for (int n = 0; n < 2; ++n) _Pragma("unroll") for (int k = 0; k < 2; ++k) dst[n][k] = *(const LAS bf16x8*)(lds + PG8_SB(b, h) + boff + n * 2048 + k * 1024); } while (0)
; #define PG8_MMA(ai, bj, At, Bt) do { __builtin_amdgcn_s_setprio(1); _Pragma("unroll") for (int m = 0; m < 4; ++m) _Pragma("unroll") for (int n = 0; n < 2; ++n) _Pragma("unroll") for (int k = 0; k < 2; ++k) \
;         acc[ai][bj][m][n] = __builtin_amdgcn_mfma_f32_16x16x32_bf16(Bt[n][k], At[m][k], acc[ai][bj][m][n], 0, 0, 0); __builtin_amdgcn_s_setprio(0); } while (0)
; #define PG8_WAIT_L(n) asm volatile("s_waitcnt lgkmcnt(" #n ")" ::: "memory")
; #define PG8_BAR __builtin_amdgcn_s_barrier()
; #define PG8_SCHED __builtin_amdgcn_sched_barrier(0)
; template <class Epi>
; __device__ __forceinline__ void gemm_phase(LAS unsigned char* lds, const Gemm g, const StaticOrder& S, const Epi& E) {
;     ...
;         for (int t = 0; t < nt; t += 2) {
;             const bool last = (t == nt - 2);
;             const char* a1 = cA + (size_t)(t + 1) * kstep;
;             const char* a2 = last ? nA : cA + (size_t)(t + 2) * kstep; const char* b2 = last ? nB : cB + (size_t)(t + 2) * kstep;
;             const char* a3 = a2 + kstep; const char* b3 = b2 + kstep;
;             PG8_LDB(B0, 0, 0); PG8_SCHED; PG8_LDA(At, 0, 0); PG8_STAGE(PG8_SA(1, 1), a1 + hstepA, voffA);
;             PG8_WAIT_L(8); PG8_BAR; PG8_WAIT_L(0); PG8_MMA(0, 0, At, B0); PG8_BAR; PG8_SCHED;
;             PG8_LDB(B1, 0, 1); PG8_STAGE(PG8_SB(0, 0), b2, voffB);
;             PG8_BAR; PG8_WAIT_L(0); PG8_MMA(0, 1, At, B1); PG8_BAR;
;             PG8_LDA(At, 0, 1); PG8_STAGE(PG8_SA(0, 0), a2, voffA);
;             PG8_BAR; PG8_WAIT_L(0); PG8_MMA(1, 0, At, B0); PG8_BAR; PG8_SCHED;
;             PG8_STAGE(PG8_SB(0, 1), b2 + hstepB, voffB);
.LBB0_1460:
	s_add_u32 s72, s34, 0x100
	s_addc_u32 s73, s35, 0
	s_mov_b32 s74, -2
	ds_read_b128 v[140:143], v149
	ds_read_b128 v[152:155], v149 offset:1024
	ds_read_b128 v[156:159], v149 offset:2048
	ds_read_b128 v[160:163], v149 offset:3072
	s_add_u32 s34, s30, 0x100
	s_addc_u32 s35, s31, 0
	s_cmp_eq_u32 s74, 40
	s_cselect_b32 s39, s13, s35
	s_cselect_b32 s38, s12, s34
	s_cselect_b32 s37, s15, s73
	s_cselect_b32 s36, s14, s72
	v_lshl_add_u64 v[144:145], s[30:31], 0, v[132:133]
	s_add_i32 m0, s8, 0xc000
	ds_read_b128 v[164:167], v150
	ds_read_b128 v[168:171], v150 offset:1024
	ds_read_b128 v[172:175], v150 offset:2048
	ds_read_b128 v[176:179], v150 offset:3072
	ds_read_b128 v[180:183], v150 offset:4096
	ds_read_b128 v[184:187], v150 offset:5120
	ds_read_b128 v[188:191], v150 offset:6144
	ds_read_b128 v[192:195], v150 offset:7168
	global_load_lds_dwordx4 v[144:145], off
	v_lshl_add_u64 v[144:145], s[30:31], 0, v[134:135]
	s_add_i32 m0, s8, 0xe000
	s_nop 0
	global_load_lds_dwordx4 v[144:145], off
	ds_read_b128 v[196:199], v151
	ds_read_b128 v[200:203], v151 offset:1024
	ds_read_b128 v[204:207], v151 offset:2048
	ds_read_b128 v[208:211], v151 offset:3072
	s_waitcnt lgkmcnt(0)
	s_barrier
	s_setprio 1
	v_mfma_f32_16x16x32_bf16 v[124:127], v[140:143], v[164:167], 0
	v_mfma_f32_16x16x32_bf16 v[120:123], v[156:159], v[164:167], 0
	v_mfma_f32_16x16x32_bf16 v[112:115], v[140:143], v[172:175], 0
	v_mfma_f32_16x16x32_bf16 v[104:107], v[156:159], v[172:175], 0
	v_mfma_f32_16x16x32_bf16 v[92:95], v[140:143], v[180:183], 0
	v_mfma_f32_16x16x32_bf16 v[88:91], v[156:159], v[180:183], 0
	v_mfma_f32_16x16x32_bf16 v[80:83], v[140:143], v[188:191], 0
	v_mfma_f32_16x16x32_bf16 v[72:75], v[156:159], v[188:191], 0
	v_mfma_f32_16x16x32_bf16 v[124:127], v[152:155], v[168:171], v[124:127]
	v_mfma_f32_16x16x32_bf16 v[120:123], v[160:163], v[168:171], v[120:123]
	v_mfma_f32_16x16x32_bf16 v[112:115], v[152:155], v[176:179], v[112:115]
	v_mfma_f32_16x16x32_bf16 v[104:107], v[160:163], v[176:179], v[104:107]
	v_mfma_f32_16x16x32_bf16 v[92:95], v[152:155], v[184:187], v[92:95]
	v_mfma_f32_16x16x32_bf16 v[88:91], v[160:163], v[184:187], v[88:91]
	v_mfma_f32_16x16x32_bf16 v[80:83], v[152:155], v[192:195], v[80:83]
	v_mfma_f32_16x16x32_bf16 v[72:75], v[160:163], v[192:195], v[72:75]
	v_mfma_f32_16x16x32_bf16 v[116:119], v[196:199], v[164:167], 0
	v_mfma_f32_16x16x32_bf16 v[108:111], v[204:207], v[164:167], 0
	v_mfma_f32_16x16x32_bf16 v[100:103], v[196:199], v[172:175], 0
	v_mfma_f32_16x16x32_bf16 v[96:99], v[204:207], v[172:175], 0
	v_mfma_f32_16x16x32_bf16 v[84:87], v[196:199], v[180:183], 0
	v_mfma_f32_16x16x32_bf16 v[76:79], v[204:207], v[180:183], 0
	v_mfma_f32_16x16x32_bf16 v[68:71], v[196:199], v[188:191], 0
	v_mfma_f32_16x16x32_bf16 v[64:67], v[204:207], v[188:191], 0
	v_mfma_f32_16x16x32_bf16 v[116:119], v[200:203], v[168:171], v[116:119]
	v_mfma_f32_16x16x32_bf16 v[108:111], v[208:211], v[168:171], v[108:111]
	v_mfma_f32_16x16x32_bf16 v[100:103], v[200:203], v[176:179], v[100:103]
	v_mfma_f32_16x16x32_bf16 v[96:99], v[208:211], v[176:179], v[96:99]
	v_mfma_f32_16x16x32_bf16 v[84:87], v[200:203], v[184:187], v[84:87]
	v_mfma_f32_16x16x32_bf16 v[76:79], v[208:211], v[184:187], v[76:79]
	v_mfma_f32_16x16x32_bf16 v[68:71], v[200:203], v[192:195], v[68:71]
	v_mfma_f32_16x16x32_bf16 v[64:67], v[208:211], v[192:195], v[64:67]
	s_setprio 0
	s_barrier
	s_nop 1
	ds_read_b128 v[164:167], v150 offset:16384
	ds_read_b128 v[168:171], v150 offset:17408
	ds_read_b128 v[172:175], v150 offset:18432
	ds_read_b128 v[176:179], v150 offset:19456
	ds_read_b128 v[180:183], v150 offset:20480
	ds_read_b128 v[184:187], v150 offset:21504
	ds_read_b128 v[188:191], v150 offset:22528
	ds_read_b128 v[192:195], v150 offset:23552
	s_add_i32 s30, s45, s7
	v_lshl_add_u64 v[144:145], s[36:37], 0, v[128:129]
	s_mov_b32 m0, s30
	s_nop 0
	global_load_lds_dwordx4 v[144:145], off
	v_lshl_add_u64 v[212:213], s[36:37], 0, v[130:131]
	s_add_i32 m0, s30, 0x2000
	s_nop 0
	global_load_lds_dwordx4 v[212:213], off
	s_mov_b32 m0, s8
	v_lshl_add_u64 v[214:215], s[38:39], 0, v[128:129]
	global_load_lds_dwordx4 v[214:215], off
	v_lshl_add_u64 v[216:217], s[38:39], 0, v[130:131]
	s_mov_b32 m0, s9
	s_nop 0
	global_load_lds_dwordx4 v[216:217], off
	s_add_u32 s30, s36, 0xb0000
	s_addc_u32 s31, s37, 0
	s_add_i32 s75, s46, s7
	v_lshl_add_u64 v[254:255], s[30:31], 0, v[128:129]
	s_mov_b32 m0, s75
	s_nop 0
	global_load_lds_dwordx4 v[254:255], off
	v_lshl_add_u64 v[254:255], s[30:31], 0, v[130:131]
	s_add_i32 m0, s75, 0x2000
	s_nop 0
	global_load_lds_dwordx4 v[254:255], off
	s_waitcnt vmcnt(6)
	s_waitcnt lgkmcnt(0)
	s_barrier
; #define PG8_STAGE(bufoff, gbase, voff) do { _Pragma("unroll") for (int _i = 0; _i < 2; ++_i) \
;         __builtin_amdgcn_global_load_lds((const unsigned*)((const char*)(gbase) + (voff)[_i]), (LAS unsigned*)(lds + (bufoff) + ldsw + _i * 8192), 16, 0, 0); } while (0)
; #define PG8_LDA(dst, b, h) do { _Pragma("unroll") for (int m = 0; m < 4; ++m) _Pragma("unroll") for (int k = 0; k < 2; ++k) dst[m][k] = *(const LAS bf16x8*)(lds + PG8_SA(b, h) + aoff + m * 2048 + k * 1024); } while (0)
; #define PG8_LDB(dst, b, h) do { _Pragma("unroll") for (int n = 0; n < 2; ++n) _Pragma("unroll") for (int k = 0; k < 2; ++k) dst[n][k] = *(const LAS bf16x8*)(lds + PG8_SB(b, h) + boff + n * 2048 + k * 1024); } while (0)
; #define PG8_MMA(ai, bj, At, Bt) do { __builtin_amdgcn_s_setprio(1); _Pragma("unroll") for (int m = 0; m < 4; ++m) _Pragma("unroll") for (int n = 0; n < 2; ++n) _Pragma("unroll") for (int k = 0; k < 2; ++k) \
;         acc[ai][bj][m][n] = __builtin_amdgcn_mfma_f32_16x16x32_bf16(Bt[n][k], At[m][k], acc[ai][bj][m][n], 0, 0, 0); __builtin_amdgcn_s_setprio(0); } while (0)
; #define PG8_WAIT_V(n) asm volatile("s_waitcnt vmcnt(" #n ")" ::: "memory")
; #define PG8_WAIT_L(n) asm volatile("s_waitcnt lgkmcnt(" #n ")" ::: "memory")
; #define PG8_BAR __builtin_amdgcn_s_barrier()
; #define PG8_SCHED __builtin_amdgcn_sched_barrier(0)
; template <class Epi>
; __device__ __forceinline__ void gemm_phase(LAS unsigned char* lds, const Gemm g, const StaticOrder& S, const Epi& E) {
;     ...
;             PG8_BAR; PG8_WAIT_L(0); PG8_MMA(1, 0, At, B0); PG8_BAR; PG8_SCHED;
;             PG8_STAGE(PG8_SB(0, 1), b2 + hstepB, voffB);
;             PG8_WAIT_V(6); PG8_BAR; PG8_MMA(1, 1, At, B1); PG8_BAR;
;             PG8_LDB(B0, 1, 0); PG8_SCHED; PG8_LDA(At, 1, 0); PG8_STAGE(PG8_SA(0, 1), a2 + hstepA, voffA);
;             PG8_WAIT_L(8); PG8_BAR; PG8_WAIT_L(0); PG8_MMA(0, 0, At, B0); PG8_BAR; PG8_SCHED;
;             PG8_LDB(B1, 1, 1); PG8_STAGE(PG8_SB(1, 0), b3, voffB);
;             PG8_BAR; PG8_WAIT_L(0); PG8_MMA(0, 1, At, B1); PG8_BAR;
	s_setprio 1
	v_mfma_f32_16x16x32_bf16 v[60:63], v[140:143], v[164:167], 0
	v_mfma_f32_16x16x32_bf16 v[56:59], v[156:159], v[164:167], 0
	v_mfma_f32_16x16x32_bf16 v[48:51], v[140:143], v[172:175], 0
	v_mfma_f32_16x16x32_bf16 v[40:43], v[156:159], v[172:175], 0
	v_mfma_f32_16x16x32_bf16 v[28:31], v[140:143], v[180:183], 0
	v_mfma_f32_16x16x32_bf16 v[24:27], v[156:159], v[180:183], 0
	v_mfma_f32_16x16x32_bf16 v[16:19], v[140:143], v[188:191], 0
	v_mfma_f32_16x16x32_bf16 v[8:11], v[156:159], v[188:191], 0
	v_mfma_f32_16x16x32_bf16 v[60:63], v[152:155], v[168:171], v[60:63]
	v_mfma_f32_16x16x32_bf16 v[56:59], v[160:163], v[168:171], v[56:59]
	v_mfma_f32_16x16x32_bf16 v[48:51], v[152:155], v[176:179], v[48:51]
	v_mfma_f32_16x16x32_bf16 v[40:43], v[160:163], v[176:179], v[40:43]
	v_mfma_f32_16x16x32_bf16 v[28:31], v[152:155], v[184:187], v[28:31]
	v_mfma_f32_16x16x32_bf16 v[24:27], v[160:163], v[184:187], v[24:27]
	v_mfma_f32_16x16x32_bf16 v[16:19], v[152:155], v[192:195], v[16:19]
	v_mfma_f32_16x16x32_bf16 v[8:11], v[160:163], v[192:195], v[8:11]
	v_mfma_f32_16x16x32_bf16 v[52:55], v[196:199], v[164:167], 0
	v_mfma_f32_16x16x32_bf16 v[44:47], v[204:207], v[164:167], 0
	v_mfma_f32_16x16x32_bf16 v[36:39], v[196:199], v[172:175], 0
	v_mfma_f32_16x16x32_bf16 v[32:35], v[204:207], v[172:175], 0
	v_mfma_f32_16x16x32_bf16 v[20:23], v[196:199], v[180:183], 0
	v_mfma_f32_16x16x32_bf16 v[12:15], v[204:207], v[180:183], 0
	v_mfma_f32_16x16x32_bf16 v[4:7], v[196:199], v[188:191], 0
	v_mfma_f32_16x16x32_bf16 v[0:3], v[204:207], v[188:191], 0
	v_mfma_f32_16x16x32_bf16 v[52:55], v[200:203], v[168:171], v[52:55]
	v_mfma_f32_16x16x32_bf16 v[44:47], v[208:211], v[168:171], v[44:47]
	v_mfma_f32_16x16x32_bf16 v[36:39], v[200:203], v[176:179], v[36:39]
	v_mfma_f32_16x16x32_bf16 v[32:35], v[208:211], v[176:179], v[32:35]
	v_mfma_f32_16x16x32_bf16 v[20:23], v[200:203], v[184:187], v[20:23]
	v_mfma_f32_16x16x32_bf16 v[12:15], v[208:211], v[184:187], v[12:15]
	v_mfma_f32_16x16x32_bf16 v[4:7], v[200:203], v[192:195], v[4:7]
	v_mfma_f32_16x16x32_bf16 v[0:3], v[208:211], v[192:195], v[0:3]
	s_setprio 0
	s_add_i32 s75, 0, 0x18000
	v_add_u32_e32 v160, s75, v147
	s_barrier
	ds_read_b128 v[140:143], v160
	ds_read_b128 v[152:155], v160 offset:1024
	ds_read_b128 v[156:159], v160 offset:2048
	ds_read_b128 v[160:163], v160 offset:3072
	s_add_u32 s30, s38, 0xb0000
	s_addc_u32 s31, s39, 0
	s_mov_b32 m0, s40
	v_lshl_add_u64 v[196:197], s[30:31], 0, v[128:129]
	ds_read_b128 v[164:167], v150 offset:32768
	ds_read_b128 v[168:171], v150 offset:33792
	ds_read_b128 v[172:175], v150 offset:34816
	ds_read_b128 v[176:179], v150 offset:35840
	ds_read_b128 v[180:183], v150 offset:36864
	ds_read_b128 v[184:187], v150 offset:37888
	ds_read_b128 v[188:191], v150 offset:38912
	ds_read_b128 v[192:195], v150 offset:39936
	global_load_lds_dwordx4 v[196:197], off
	v_lshl_add_u64 v[196:197], s[30:31], 0, v[130:131]
	s_mov_b32 m0, s41
	s_nop 0
	global_load_lds_dwordx4 v[196:197], off
	s_add_i32 s38, 0, 0x1c000
	v_add_u32_e32 v208, s38, v147
	ds_read_b128 v[196:199], v208
	ds_read_b128 v[200:203], v208 offset:1024
	ds_read_b128 v[204:207], v208 offset:2048
	ds_read_b128 v[208:211], v208 offset:3072
	s_waitcnt lgkmcnt(0)
	s_barrier
	s_setprio 1
	v_mfma_f32_16x16x32_bf16 v[124:127], v[140:143], v[164:167], v[124:127]
	v_mfma_f32_16x16x32_bf16 v[120:123], v[156:159], v[164:167], v[120:123]
	v_mfma_f32_16x16x32_bf16 v[112:115], v[140:143], v[172:175], v[112:115]
	v_mfma_f32_16x16x32_bf16 v[104:107], v[156:159], v[172:175], v[104:107]
	v_mfma_f32_16x16x32_bf16 v[92:95], v[140:143], v[180:183], v[92:95]
	v_mfma_f32_16x16x32_bf16 v[88:91], v[156:159], v[180:183], v[88:91]
	v_mfma_f32_16x16x32_bf16 v[80:83], v[140:143], v[188:191], v[80:83]
	v_mfma_f32_16x16x32_bf16 v[72:75], v[156:159], v[188:191], v[72:75]
	v_mfma_f32_16x16x32_bf16 v[124:127], v[152:155], v[168:171], v[124:127]
	v_mfma_f32_16x16x32_bf16 v[120:123], v[160:163], v[168:171], v[120:123]
	v_mfma_f32_16x16x32_bf16 v[112:115], v[152:155], v[176:179], v[112:115]
	v_mfma_f32_16x16x32_bf16 v[104:107], v[160:163], v[176:179], v[104:107]
	v_mfma_f32_16x16x32_bf16 v[92:95], v[152:155], v[184:187], v[92:95]
	v_mfma_f32_16x16x32_bf16 v[88:91], v[160:163], v[184:187], v[88:91]
	v_mfma_f32_16x16x32_bf16 v[80:83], v[152:155], v[192:195], v[80:83]
	v_mfma_f32_16x16x32_bf16 v[72:75], v[160:163], v[192:195], v[72:75]
	v_mfma_f32_16x16x32_bf16 v[116:119], v[196:199], v[164:167], v[116:119]
	v_mfma_f32_16x16x32_bf16 v[108:111], v[204:207], v[164:167], v[108:111]
	v_mfma_f32_16x16x32_bf16 v[100:103], v[196:199], v[172:175], v[100:103]
	v_mfma_f32_16x16x32_bf16 v[96:99], v[204:207], v[172:175], v[96:99]
	v_mfma_f32_16x16x32_bf16 v[84:87], v[196:199], v[180:183], v[84:87]
	v_mfma_f32_16x16x32_bf16 v[76:79], v[204:207], v[180:183], v[76:79]
	v_mfma_f32_16x16x32_bf16 v[68:71], v[196:199], v[188:191], v[68:71]
	v_mfma_f32_16x16x32_bf16 v[64:67], v[204:207], v[188:191], v[64:67]
	v_mfma_f32_16x16x32_bf16 v[116:119], v[200:203], v[168:171], v[116:119]
	v_mfma_f32_16x16x32_bf16 v[108:111], v[208:211], v[168:171], v[108:111]
	v_mfma_f32_16x16x32_bf16 v[100:103], v[200:203], v[176:179], v[100:103]
	v_mfma_f32_16x16x32_bf16 v[96:99], v[208:211], v[176:179], v[96:99]
	v_mfma_f32_16x16x32_bf16 v[84:87], v[200:203], v[184:187], v[84:87]
	v_mfma_f32_16x16x32_bf16 v[76:79], v[208:211], v[184:187], v[76:79]
	v_mfma_f32_16x16x32_bf16 v[68:71], v[200:203], v[192:195], v[68:71]
	v_mfma_f32_16x16x32_bf16 v[64:67], v[208:211], v[192:195], v[64:67]
	s_setprio 0
	s_barrier
; #define PG8_STAGE(bufoff, gbase, voff) do { _Pragma("unroll") for (int _i = 0; _i < 2; ++_i) \
;         __builtin_amdgcn_global_load_lds((const unsigned*)((const char*)(gbase) + (voff)[_i]), (LAS unsigned*)(lds + (bufoff) + ldsw + _i * 8192), 16, 0, 0); } while (0)
; #define PG8_LDA(dst, b, h) do { _Pragma("unroll") for (int m = 0; m < 4; ++m) _Pragma("unroll") for (int k = 0; k < 2; ++k) dst[m][k] = *(const LAS bf16x8*)(lds + PG8_SA(b, h) + aoff + m * 2048 + k * 1024); } while (0)
; #define PG8_MMA(ai, bj, At, Bt) do { __builtin_amdgcn_s_setprio(1); _Pragma("unroll") for (int m = 0; m < 4; ++m) _Pragma("unroll") for (int n = 0; n < 2; ++n) _Pragma("unroll") for (int k = 0; k < 2; ++k) \
;         acc[ai][bj][m][n] = __builtin_amdgcn_mfma_f32_16x16x32_bf16(Bt[n][k], At[m][k], acc[ai][bj][m][n], 0, 0, 0); __builtin_amdgcn_s_setprio(0); } while (0)
; #define PG8_WAIT_V(n) asm volatile("s_waitcnt vmcnt(" #n ")" ::: "memory")
; #define PG8_WAIT_L(n) asm volatile("s_waitcnt lgkmcnt(" #n ")" ::: "memory")
; #define PG8_BAR __builtin_amdgcn_s_barrier()
; #define PG8_SCHED __builtin_amdgcn_sched_barrier(0)
; template <class Epi>
; __device__ __forceinline__ void gemm_phase(LAS unsigned char* lds, const Gemm g, const StaticOrder& S, const Epi& E) {
;     ...
;             PG8_LDA(At, 1, 1); PG8_STAGE(PG8_SA(1, 0), a3, voffA);
;             PG8_BAR; PG8_WAIT_L(0); PG8_MMA(1, 0, At, B0); PG8_BAR; PG8_SCHED;
;             PG8_STAGE(PG8_SB(1, 1), b3 + hstepB, voffB);
;             PG8_WAIT_V(6); PG8_BAR; PG8_MMA(1, 1, At, B1); PG8_BAR;
	s_nop 1
	ds_read_b128 v[164:167], v150 offset:49152
	ds_read_b128 v[168:171], v150 offset:50176
	ds_read_b128 v[172:175], v150 offset:51200
	ds_read_b128 v[176:179], v150 offset:52224
	ds_read_b128 v[180:183], v150 offset:53248
	ds_read_b128 v[184:187], v150 offset:54272
	ds_read_b128 v[188:191], v150 offset:55296
	ds_read_b128 v[192:195], v150 offset:56320
	s_add_i32 s30, s75, s7
	v_lshl_add_u64 v[254:255], v[144:145], 0, s[22:23]
	s_mov_b32 m0, s30
	s_nop 0
	global_load_lds_dwordx4 v[254:255], off
	v_lshl_add_u64 v[254:255], v[212:213], 0, s[22:23]
	s_add_i32 m0, s30, 0x2000
	s_nop 0
	global_load_lds_dwordx4 v[254:255], off
	s_mov_b32 m0, s43
	v_lshl_add_u64 v[254:255], v[214:215], 0, s[22:23]
	global_load_lds_dwordx4 v[254:255], off
	v_lshl_add_u64 v[144:145], v[216:217], 0, s[22:23]
	s_mov_b32 m0, s44
	s_nop 0
	global_load_lds_dwordx4 v[144:145], off
	s_add_u32 s30, s36, 0xb0080
	s_addc_u32 s31, s37, 0
	s_add_i32 s36, s38, s7
	v_lshl_add_u64 v[254:255], s[30:31], 0, v[128:129]
	s_mov_b32 m0, s36
	s_nop 0
	global_load_lds_dwordx4 v[254:255], off
	v_lshl_add_u64 v[254:255], s[30:31], 0, v[130:131]
	s_add_i32 m0, s36, 0x2000
	s_nop 0
	global_load_lds_dwordx4 v[254:255], off
	s_waitcnt vmcnt(6)
	s_waitcnt lgkmcnt(0)
	s_barrier
	s_setprio 1
	v_mfma_f32_16x16x32_bf16 v[60:63], v[140:143], v[164:167], v[60:63]
	v_mfma_f32_16x16x32_bf16 v[56:59], v[156:159], v[164:167], v[56:59]
	v_mfma_f32_16x16x32_bf16 v[48:51], v[140:143], v[172:175], v[48:51]
	v_mfma_f32_16x16x32_bf16 v[40:43], v[156:159], v[172:175], v[40:43]
	v_mfma_f32_16x16x32_bf16 v[28:31], v[140:143], v[180:183], v[28:31]
	v_mfma_f32_16x16x32_bf16 v[24:27], v[156:159], v[180:183], v[24:27]
	v_mfma_f32_16x16x32_bf16 v[16:19], v[140:143], v[188:191], v[16:19]
	v_mfma_f32_16x16x32_bf16 v[8:11], v[156:159], v[188:191], v[8:11]
	v_mfma_f32_16x16x32_bf16 v[60:63], v[152:155], v[168:171], v[60:63]
	v_mfma_f32_16x16x32_bf16 v[56:59], v[160:163], v[168:171], v[56:59]
	v_mfma_f32_16x16x32_bf16 v[48:51], v[152:155], v[176:179], v[48:51]
	v_mfma_f32_16x16x32_bf16 v[40:43], v[160:163], v[176:179], v[40:43]
	v_mfma_f32_16x16x32_bf16 v[28:31], v[152:155], v[184:187], v[28:31]
	v_mfma_f32_16x16x32_bf16 v[24:27], v[160:163], v[184:187], v[24:27]
	v_mfma_f32_16x16x32_bf16 v[16:19], v[152:155], v[192:195], v[16:19]
	v_mfma_f32_16x16x32_bf16 v[8:11], v[160:163], v[192:195], v[8:11]
	v_mfma_f32_16x16x32_bf16 v[52:55], v[196:199], v[164:167], v[52:55]
	v_mfma_f32_16x16x32_bf16 v[44:47], v[204:207], v[164:167], v[44:47]
	v_mfma_f32_16x16x32_bf16 v[36:39], v[196:199], v[172:175], v[36:39]
	v_mfma_f32_16x16x32_bf16 v[32:35], v[204:207], v[172:175], v[32:35]
	v_mfma_f32_16x16x32_bf16 v[20:23], v[196:199], v[180:183], v[20:23]
	v_mfma_f32_16x16x32_bf16 v[12:15], v[204:207], v[180:183], v[12:15]
	v_mfma_f32_16x16x32_bf16 v[4:7], v[196:199], v[188:191], v[4:7]
	v_mfma_f32_16x16x32_bf16 v[0:3], v[204:207], v[188:191], v[0:3]
	v_mfma_f32_16x16x32_bf16 v[52:55], v[200:203], v[168:171], v[52:55]
	v_mfma_f32_16x16x32_bf16 v[44:47], v[208:211], v[168:171], v[44:47]
	v_mfma_f32_16x16x32_bf16 v[36:39], v[200:203], v[176:179], v[36:39]
	v_mfma_f32_16x16x32_bf16 v[32:35], v[208:211], v[176:179], v[32:35]
	v_mfma_f32_16x16x32_bf16 v[20:23], v[200:203], v[184:187], v[20:23]
	v_mfma_f32_16x16x32_bf16 v[12:15], v[208:211], v[184:187], v[12:15]
	v_mfma_f32_16x16x32_bf16 v[4:7], v[200:203], v[192:195], v[4:7]
	v_mfma_f32_16x16x32_bf16 v[0:3], v[208:211], v[192:195], v[0:3]
	s_setprio 0
	s_add_i32 s74, s74, 2
	s_add_u32 s72, s72, 0x100
	s_addc_u32 s73, s73, 0
	s_cmp_gt_u32 s74, 41
	s_mov_b64 s[30:31], s[34:35]
	s_barrier

; #define PG8_STAGE(bufoff, gbase, voff) do { _Pragma("unroll") for (int _i = 0; _i < 2; ++_i) \
;         __builtin_amdgcn_global_load_lds((const unsigned*)((const char*)(gbase) + (voff)[_i]), (LAS unsigned*)(lds + (bufoff) + ldsw + _i * 8192), 16, 0, 0); } while (0)
; #define PG8_LDA(dst, b, h) do { _Pragma("unroll") for (int m = 0; m < 4; ++m) _Pragma("unroll") for (int k = 0; k < 2; ++k) dst[m][k] = *(const LAS bf16x8*)(lds + PG8_SA(b, h) + aoff + m * 2048 + k * 1024); } while (0)
; #define PG8_LDB(dst, b, h) do { _Pragma("unroll") for (int n = 0; n < 2; ++n) _Pragma("unroll") for (int k = 0; k < 2; ++k) dst[n][k] = *(const LAS bf16x8*)(lds + PG8_SB(b, h) + boff + n * 2048 + k * 1024); } while (0)
; #define PG8_MMA(ai, bj, At, Bt) do { __builtin_amdgcn_s_setprio(1); _Pragma("unroll") for (int m = 0; m < 4; ++m) _Pragma("unroll") for (int n = 0; n < 2; ++n) _Pragma("unroll") for (int k = 0; k < 2; ++k) \
;         acc[ai][bj][m][n] = __builtin_amdgcn_mfma_f32_16x16x32_bf16(Bt[n][k], At[m][k], acc[ai][bj][m][n], 0, 0, 0); __builtin_amdgcn_s_setprio(0); } while (0)
; template <class Epi>
; __device__ __forceinline__ void gemm_phase(LAS unsigned char* lds, const Gemm g, const StaticOrder& S, const Epi& E) {
;     ...
;         const bool has_next = S.next(ui + 1, nxt);
;         const char* nA = has_next ? (const char*)g.A + (size_t)nxt.pm * tstepA + (size_t)(nxt.pn >> g.a_shift) * g.a_step : cA; const char* nB = has_next ? (const char*)g.Bt + (size_t)nxt.pn * tstepB : cB;
;         for (int t = 0; t < nt; t += 2) {
;             const bool last = (t == nt - 2);
;             const char* a1 = cA + (size_t)(t + 1) * kstep;
;             const char* a2 = last ? nA : cA + (size_t)(t + 2) * kstep; const char* b2 = last ? nB : cB + (size_t)(t + 2) * kstep;
;             const char* a3 = a2 + kstep; const char* b3 = b2 + kstep;
;             PG8_LDB(B0, 0, 0); PG8_SCHED; PG8_LDA(At, 0, 0); PG8_STAGE(PG8_SA(1, 1), a1 + hstepA, voffA);
;             PG8_WAIT_L(8); PG8_BAR; PG8_WAIT_L(0); PG8_MMA(0, 0, At, B0); PG8_BAR; PG8_SCHED;
;             PG8_LDB(B1, 0, 1); PG8_STAGE(PG8_SB(0, 0), b2, voffB);
;             PG8_BAR; PG8_WAIT_L(0); PG8_MMA(0, 1, At, B1); PG8_BAR;
;             PG8_LDA(At, 0, 1); PG8_STAGE(PG8_SA(0, 0), a2, voffA);
;             PG8_BAR; PG8_WAIT_L(0); PG8_MMA(1, 0, At, B0); PG8_BAR; PG8_SCHED;
;             PG8_STAGE(PG8_SB(0, 1), b2 + hstepB, voffB);
.LBB0_1582:
	s_ashr_i32 s25, s24, 31
	v_cmp_lt_i64_e32 vcc, s[12:13], v[162:163]
	s_lshl_b64 s[12:13], s[24:25], 19
	s_add_u32 s26, s66, s12
	s_addc_u32 s27, s67, s13
	s_and_b64 s[12:13], vcc, exec
	s_cselect_b32 s25, s27, s39
	s_cselect_b32 s31, s26, s38
	s_ashr_i32 s23, s22, 31
	s_lshl_b64 s[12:13], s[22:23], 19
	s_add_u32 s28, s5, s12
	s_addc_u32 s29, s6, s13
	s_and_b64 s[12:13], vcc, exec
	s_cselect_b32 s23, s29, s37
	s_cselect_b32 s35, s28, s36
	s_add_u32 s12, s38, 0x40080
	s_addc_u32 s13, s39, 0
	s_add_u32 s38, s36, 0x100
	s_addc_u32 s39, s37, 0
	s_mov_b32 s74, -2
	ds_read_b128 v[80:83], v180
	ds_read_b128 v[84:87], v180 offset:1024
	ds_read_b128 v[88:91], v180 offset:2048
	ds_read_b128 v[92:95], v180 offset:3072
	s_add_u32 s14, s12, 0xfffc0080
	s_addc_u32 s15, s13, -1
	s_cmp_eq_u32 s74, 12
	s_cselect_b32 s37, s25, s15
	s_cselect_b32 s36, s31, s14
	s_cselect_b32 s15, s23, s39
	s_cselect_b32 s14, s35, s38
	v_lshl_add_u64 v[210:211], s[12:13], 0, v[158:159]
	s_add_i32 m0, s8, 0xc000
	ds_read_b128 v[166:169], v181
	ds_read_b128 v[170:173], v181 offset:1024
	ds_read_b128 v[186:189], v181 offset:2048
	ds_read_b128 v[190:193], v181 offset:3072
	ds_read_b128 v[194:197], v181 offset:4096
	ds_read_b128 v[198:201], v181 offset:5120
	ds_read_b128 v[202:205], v181 offset:6144
	ds_read_b128 v[206:209], v181 offset:7168
	global_load_lds_dwordx4 v[210:211], off
	v_lshl_add_u64 v[210:211], s[12:13], 0, v[160:161]
	s_add_i32 m0, s8, 0xe000
	s_nop 0
	global_load_lds_dwordx4 v[210:211], off
	ds_read_b128 v[210:213], v182
	ds_read_b128 v[214:217], v182 offset:1024
	ds_read_b128 v[220:223], v182 offset:2048
	ds_read_b128 v[224:227], v182 offset:3072
	s_waitcnt lgkmcnt(0)
	s_barrier
	s_setprio 1
	v_mfma_f32_16x16x32_bf16 v[140:143], v[80:83], v[166:169], 0
	v_mfma_f32_16x16x32_bf16 v[136:139], v[88:91], v[166:169], 0
	v_mfma_f32_16x16x32_bf16 v[124:127], v[80:83], v[186:189], 0
	v_mfma_f32_16x16x32_bf16 v[120:123], v[88:91], v[186:189], 0
	v_mfma_f32_16x16x32_bf16 v[108:111], v[80:83], v[194:197], 0
	v_mfma_f32_16x16x32_bf16 v[104:107], v[88:91], v[194:197], 0
	v_mfma_f32_16x16x32_bf16 v[76:79], v[80:83], v[202:205], 0
	v_mfma_f32_16x16x32_bf16 v[72:75], v[88:91], v[202:205], 0
	v_mfma_f32_16x16x32_bf16 v[140:143], v[84:87], v[170:173], v[140:143]
	v_mfma_f32_16x16x32_bf16 v[136:139], v[92:95], v[170:173], v[136:139]
	v_mfma_f32_16x16x32_bf16 v[124:127], v[84:87], v[190:193], v[124:127]
	v_mfma_f32_16x16x32_bf16 v[120:123], v[92:95], v[190:193], v[120:123]
	v_mfma_f32_16x16x32_bf16 v[108:111], v[84:87], v[198:201], v[108:111]
	v_mfma_f32_16x16x32_bf16 v[104:107], v[92:95], v[198:201], v[104:107]
	v_mfma_f32_16x16x32_bf16 v[76:79], v[84:87], v[206:209], v[76:79]
	v_mfma_f32_16x16x32_bf16 v[72:75], v[92:95], v[206:209], v[72:75]
	v_mfma_f32_16x16x32_bf16 v[132:135], v[210:213], v[166:169], 0
	v_mfma_f32_16x16x32_bf16 v[128:131], v[220:223], v[166:169], 0
	v_mfma_f32_16x16x32_bf16 v[116:119], v[210:213], v[186:189], 0
	v_mfma_f32_16x16x32_bf16 v[112:115], v[220:223], v[186:189], 0
	v_mfma_f32_16x16x32_bf16 v[100:103], v[210:213], v[194:197], 0
	v_mfma_f32_16x16x32_bf16 v[96:99], v[220:223], v[194:197], 0
	v_mfma_f32_16x16x32_bf16 v[68:71], v[210:213], v[202:205], 0
	v_mfma_f32_16x16x32_bf16 v[64:67], v[220:223], v[202:205], 0
	v_mfma_f32_16x16x32_bf16 v[132:135], v[214:217], v[170:173], v[132:135]
	v_mfma_f32_16x16x32_bf16 v[128:131], v[224:227], v[170:173], v[128:131]
	v_mfma_f32_16x16x32_bf16 v[116:119], v[214:217], v[190:193], v[116:119]
	v_mfma_f32_16x16x32_bf16 v[112:115], v[224:227], v[190:193], v[112:115]
	v_mfma_f32_16x16x32_bf16 v[100:103], v[214:217], v[198:201], v[100:103]
	v_mfma_f32_16x16x32_bf16 v[96:99], v[224:227], v[198:201], v[96:99]
	v_mfma_f32_16x16x32_bf16 v[68:71], v[214:217], v[206:209], v[68:71]
	v_mfma_f32_16x16x32_bf16 v[64:67], v[224:227], v[206:209], v[64:67]
	s_setprio 0
	s_barrier
	s_nop 1
	ds_read_b128 v[166:169], v181 offset:16384
	ds_read_b128 v[170:173], v181 offset:17408
	ds_read_b128 v[186:189], v181 offset:18432
	ds_read_b128 v[190:193], v181 offset:19456
	ds_read_b128 v[194:197], v181 offset:20480
	ds_read_b128 v[198:201], v181 offset:21504
	ds_read_b128 v[202:205], v181 offset:22528
	ds_read_b128 v[206:209], v181 offset:23552
	s_add_i32 s75, s48, s7
	v_lshl_add_u64 v[228:229], s[14:15], 0, v[146:147]
	s_mov_b32 m0, s75
	s_nop 0
	global_load_lds_dwordx4 v[228:229], off
	v_lshl_add_u64 v[230:231], s[14:15], 0, v[150:151]
	s_add_i32 m0, s75, 0x2000
	s_nop 0
	global_load_lds_dwordx4 v[230:231], off
	s_mov_b32 m0, s8
	v_lshl_add_u64 v[232:233], s[36:37], 0, v[144:145]
	global_load_lds_dwordx4 v[232:233], off
	v_lshl_add_u64 v[236:237], s[36:37], 0, v[148:149]
	s_mov_b32 m0, s9
	s_nop 0
	global_load_lds_dwordx4 v[236:237], off
	s_add_u32 s76, s14, 0x40000
	s_addc_u32 s77, s15, 0
	s_add_i32 s75, s49, s7
	v_lshl_add_u64 v[254:255], s[76:77], 0, v[146:147]
	s_mov_b32 m0, s75
	s_nop 0
	global_load_lds_dwordx4 v[254:255], off
	v_lshl_add_u64 v[254:255], s[76:77], 0, v[150:151]
	s_add_i32 m0, s75, 0x2000
	s_nop 0
	global_load_lds_dwordx4 v[254:255], off
	s_waitcnt vmcnt(6)
	s_waitcnt lgkmcnt(0)
	s_barrier
; #define PG8_STAGE(bufoff, gbase, voff) do { _Pragma("unroll") for (int _i = 0; _i < 2; ++_i) \
;         __builtin_amdgcn_global_load_lds((const unsigned*)((const char*)(gbase) + (voff)[_i]), (LAS unsigned*)(lds + (bufoff) + ldsw + _i * 8192), 16, 0, 0); } while (0)
; #define PG8_LDA(dst, b, h) do { _Pragma("unroll") for (int m = 0; m < 4; ++m) _Pragma("unroll") for (int k = 0; k < 2; ++k) dst[m][k] = *(const LAS bf16x8*)(lds + PG8_SA(b, h) + aoff + m * 2048 + k * 1024); } while (0)
; #define PG8_LDB(dst, b, h) do { _Pragma("unroll") for (int n = 0; n < 2; ++n) _Pragma("unroll") for (int k = 0; k < 2; ++k) dst[n][k] = *(const LAS bf16x8*)(lds + PG8_SB(b, h) + boff + n * 2048 + k * 1024); } while (0)
; #define PG8_MMA(ai, bj, At, Bt) do { __builtin_amdgcn_s_setprio(1); _Pragma("unroll") for (int m = 0; m < 4; ++m) _Pragma("unroll") for (int n = 0; n < 2; ++n) _Pragma("unroll") for (int k = 0; k < 2; ++k) \
;         acc[ai][bj][m][n] = __builtin_amdgcn_mfma_f32_16x16x32_bf16(Bt[n][k], At[m][k], acc[ai][bj][m][n], 0, 0, 0); __builtin_amdgcn_s_setprio(0); } while (0)
; #define PG8_WAIT_V(n) asm volatile("s_waitcnt vmcnt(" #n ")" ::: "memory")
; #define PG8_WAIT_L(n) asm volatile("s_waitcnt lgkmcnt(" #n ")" ::: "memory")
; #define PG8_BAR __builtin_amdgcn_s_barrier()
; #define PG8_SCHED __builtin_amdgcn_sched_barrier(0)
; template <class Epi>
; __device__ __forceinline__ void gemm_phase(LAS unsigned char* lds, const Gemm g, const StaticOrder& S, const Epi& E) {
;     ...
;             PG8_BAR; PG8_WAIT_L(0); PG8_MMA(1, 0, At, B0); PG8_BAR; PG8_SCHED;
;             PG8_STAGE(PG8_SB(0, 1), b2 + hstepB, voffB);
;             PG8_WAIT_V(6); PG8_BAR; PG8_MMA(1, 1, At, B1); PG8_BAR;
;             PG8_LDB(B0, 1, 0); PG8_SCHED; PG8_LDA(At, 1, 0); PG8_STAGE(PG8_SA(0, 1), a2 + hstepA, voffA);
;             PG8_WAIT_L(8); PG8_BAR; PG8_WAIT_L(0); PG8_MMA(0, 0, At, B0); PG8_BAR; PG8_SCHED;
;             PG8_LDB(B1, 1, 1); PG8_STAGE(PG8_SB(1, 0), b3, voffB);
;             PG8_BAR; PG8_WAIT_L(0); PG8_MMA(0, 1, At, B1); PG8_BAR;
	s_setprio 1
	v_mfma_f32_16x16x32_bf16 v[60:63], v[80:83], v[166:169], 0
	v_mfma_f32_16x16x32_bf16 v[56:59], v[88:91], v[166:169], 0
	v_mfma_f32_16x16x32_bf16 v[44:47], v[80:83], v[186:189], 0
	v_mfma_f32_16x16x32_bf16 v[40:43], v[88:91], v[186:189], 0
	v_mfma_f32_16x16x32_bf16 v[28:31], v[80:83], v[194:197], 0
	v_mfma_f32_16x16x32_bf16 v[24:27], v[88:91], v[194:197], 0
	v_mfma_f32_16x16x32_bf16 v[12:15], v[80:83], v[202:205], 0
	v_mfma_f32_16x16x32_bf16 v[8:11], v[88:91], v[202:205], 0
	v_mfma_f32_16x16x32_bf16 v[60:63], v[84:87], v[170:173], v[60:63]
	v_mfma_f32_16x16x32_bf16 v[56:59], v[92:95], v[170:173], v[56:59]
	v_mfma_f32_16x16x32_bf16 v[44:47], v[84:87], v[190:193], v[44:47]
	v_mfma_f32_16x16x32_bf16 v[40:43], v[92:95], v[190:193], v[40:43]
	v_mfma_f32_16x16x32_bf16 v[28:31], v[84:87], v[198:201], v[28:31]
	v_mfma_f32_16x16x32_bf16 v[24:27], v[92:95], v[198:201], v[24:27]
	v_mfma_f32_16x16x32_bf16 v[12:15], v[84:87], v[206:209], v[12:15]
	v_mfma_f32_16x16x32_bf16 v[8:11], v[92:95], v[206:209], v[8:11]
	v_mfma_f32_16x16x32_bf16 v[52:55], v[210:213], v[166:169], 0
	v_mfma_f32_16x16x32_bf16 v[48:51], v[220:223], v[166:169], 0
	v_mfma_f32_16x16x32_bf16 v[36:39], v[210:213], v[186:189], 0
	v_mfma_f32_16x16x32_bf16 v[32:35], v[220:223], v[186:189], 0
	v_mfma_f32_16x16x32_bf16 v[20:23], v[210:213], v[194:197], 0
	v_mfma_f32_16x16x32_bf16 v[16:19], v[220:223], v[194:197], 0
	v_mfma_f32_16x16x32_bf16 v[4:7], v[210:213], v[202:205], 0
	v_mfma_f32_16x16x32_bf16 v[0:3], v[220:223], v[202:205], 0
	v_mfma_f32_16x16x32_bf16 v[52:55], v[214:217], v[170:173], v[52:55]
	v_mfma_f32_16x16x32_bf16 v[48:51], v[224:227], v[170:173], v[48:51]
	v_mfma_f32_16x16x32_bf16 v[36:39], v[214:217], v[190:193], v[36:39]
	v_mfma_f32_16x16x32_bf16 v[32:35], v[224:227], v[190:193], v[32:35]
	v_mfma_f32_16x16x32_bf16 v[20:23], v[214:217], v[198:201], v[20:23]
	v_mfma_f32_16x16x32_bf16 v[16:19], v[224:227], v[198:201], v[16:19]
	v_mfma_f32_16x16x32_bf16 v[4:7], v[214:217], v[206:209], v[4:7]
	v_mfma_f32_16x16x32_bf16 v[0:3], v[224:227], v[206:209], v[0:3]
	s_setprio 0
	s_add_i32 s75, 0, 0x18000
	v_add_u32_e32 v92, s75, v175
	s_barrier
	ds_read_b128 v[80:83], v92
	ds_read_b128 v[84:87], v92 offset:1024
	ds_read_b128 v[88:91], v92 offset:2048
	ds_read_b128 v[92:95], v92 offset:3072
	s_add_u32 s36, s36, 0x40000
	s_addc_u32 s37, s37, 0
	s_mov_b32 m0, s40
	v_lshl_add_u64 v[210:211], s[36:37], 0, v[144:145]
	ds_read_b128 v[166:169], v181 offset:32768
	ds_read_b128 v[170:173], v181 offset:33792
	ds_read_b128 v[186:189], v181 offset:34816
	ds_read_b128 v[190:193], v181 offset:35840
	ds_read_b128 v[194:197], v181 offset:36864
	ds_read_b128 v[198:201], v181 offset:37888
	ds_read_b128 v[202:205], v181 offset:38912
	ds_read_b128 v[206:209], v181 offset:39936
	global_load_lds_dwordx4 v[210:211], off
	v_lshl_add_u64 v[210:211], s[36:37], 0, v[148:149]
	s_mov_b32 m0, s41
	s_nop 0
	global_load_lds_dwordx4 v[210:211], off
	s_add_i32 s36, 0, 0x1c000
	v_add_u32_e32 v152, s36, v175
	ds_read_b128 v[210:213], v152
	ds_read_b128 v[214:217], v152 offset:1024
	ds_read_b128 v[220:223], v152 offset:2048
	ds_read_b128 v[224:227], v152 offset:3072
	s_waitcnt lgkmcnt(0)
	s_barrier
	s_setprio 1
	v_mfma_f32_16x16x32_bf16 v[140:143], v[80:83], v[166:169], v[140:143]
	v_mfma_f32_16x16x32_bf16 v[136:139], v[88:91], v[166:169], v[136:139]
	v_mfma_f32_16x16x32_bf16 v[124:127], v[80:83], v[186:189], v[124:127]
	v_mfma_f32_16x16x32_bf16 v[120:123], v[88:91], v[186:189], v[120:123]
	v_mfma_f32_16x16x32_bf16 v[108:111], v[80:83], v[194:197], v[108:111]
	v_mfma_f32_16x16x32_bf16 v[104:107], v[88:91], v[194:197], v[104:107]
	v_mfma_f32_16x16x32_bf16 v[76:79], v[80:83], v[202:205], v[76:79]
	v_mfma_f32_16x16x32_bf16 v[72:75], v[88:91], v[202:205], v[72:75]
	v_mfma_f32_16x16x32_bf16 v[140:143], v[84:87], v[170:173], v[140:143]
	v_mfma_f32_16x16x32_bf16 v[136:139], v[92:95], v[170:173], v[136:139]
	v_mfma_f32_16x16x32_bf16 v[124:127], v[84:87], v[190:193], v[124:127]
	v_mfma_f32_16x16x32_bf16 v[120:123], v[92:95], v[190:193], v[120:123]
	v_mfma_f32_16x16x32_bf16 v[108:111], v[84:87], v[198:201], v[108:111]
	v_mfma_f32_16x16x32_bf16 v[104:107], v[92:95], v[198:201], v[104:107]
	v_mfma_f32_16x16x32_bf16 v[76:79], v[84:87], v[206:209], v[76:79]
	v_mfma_f32_16x16x32_bf16 v[72:75], v[92:95], v[206:209], v[72:75]
	v_mfma_f32_16x16x32_bf16 v[132:135], v[210:213], v[166:169], v[132:135]
	v_mfma_f32_16x16x32_bf16 v[128:131], v[220:223], v[166:169], v[128:131]
	v_mfma_f32_16x16x32_bf16 v[116:119], v[210:213], v[186:189], v[116:119]
	v_mfma_f32_16x16x32_bf16 v[112:115], v[220:223], v[186:189], v[112:115]
	v_mfma_f32_16x16x32_bf16 v[100:103], v[210:213], v[194:197], v[100:103]
	v_mfma_f32_16x16x32_bf16 v[96:99], v[220:223], v[194:197], v[96:99]
	v_mfma_f32_16x16x32_bf16 v[68:71], v[210:213], v[202:205], v[68:71]
	v_mfma_f32_16x16x32_bf16 v[64:67], v[220:223], v[202:205], v[64:67]
	v_mfma_f32_16x16x32_bf16 v[132:135], v[214:217], v[170:173], v[132:135]
	v_mfma_f32_16x16x32_bf16 v[128:131], v[224:227], v[170:173], v[128:131]
	v_mfma_f32_16x16x32_bf16 v[116:119], v[214:217], v[190:193], v[116:119]
	v_mfma_f32_16x16x32_bf16 v[112:115], v[224:227], v[190:193], v[112:115]
	v_mfma_f32_16x16x32_bf16 v[100:103], v[214:217], v[198:201], v[100:103]
	v_mfma_f32_16x16x32_bf16 v[96:99], v[224:227], v[198:201], v[96:99]
	v_mfma_f32_16x16x32_bf16 v[68:71], v[214:217], v[206:209], v[68:71]
	v_mfma_f32_16x16x32_bf16 v[64:67], v[224:227], v[206:209], v[64:67]
	s_setprio 0
	s_barrier
; #define PG8_STAGE(bufoff, gbase, voff) do { _Pragma("unroll") for (int _i = 0; _i < 2; ++_i) \
;         __builtin_amdgcn_global_load_lds((const unsigned*)((const char*)(gbase) + (voff)[_i]), (LAS unsigned*)(lds + (bufoff) + ldsw + _i * 8192), 16, 0, 0); } while (0)
; #define PG8_LDA(dst, b, h) do { _Pragma("unroll") for (int m = 0; m < 4; ++m) _Pragma("unroll") for (int k = 0; k < 2; ++k) dst[m][k] = *(const LAS bf16x8*)(lds + PG8_SA(b, h) + aoff + m * 2048 + k * 1024); } while (0)
; #define PG8_MMA(ai, bj, At, Bt) do { __builtin_amdgcn_s_setprio(1); _Pragma("unroll") for (int m = 0; m < 4; ++m) _Pragma("unroll") for (int n = 0; n < 2; ++n) _Pragma("unroll") for (int k = 0; k < 2; ++k) \
;         acc[ai][bj][m][n] = __builtin_amdgcn_mfma_f32_16x16x32_bf16(Bt[n][k], At[m][k], acc[ai][bj][m][n], 0, 0, 0); __builtin_amdgcn_s_setprio(0); } while (0)
; #define PG8_WAIT_V(n) asm volatile("s_waitcnt vmcnt(" #n ")" ::: "memory")
; #define PG8_WAIT_L(n) asm volatile("s_waitcnt lgkmcnt(" #n ")" ::: "memory")
; #define PG8_BAR __builtin_amdgcn_s_barrier()
; #define PG8_SCHED __builtin_amdgcn_sched_barrier(0)
; template <class Epi>
; __device__ __forceinline__ void gemm_phase(LAS unsigned char* lds, const Gemm g, const StaticOrder& S, const Epi& E) {
;     ...
;             PG8_LDA(At, 1, 1); PG8_STAGE(PG8_SA(1, 0), a3, voffA);
;             PG8_BAR; PG8_WAIT_L(0); PG8_MMA(1, 0, At, B0); PG8_BAR; PG8_SCHED;
;             PG8_STAGE(PG8_SB(1, 1), b3 + hstepB, voffB);
;             PG8_WAIT_V(6); PG8_BAR; PG8_MMA(1, 1, At, B1); PG8_BAR;
	s_nop 1
	ds_read_b128 v[166:169], v181 offset:49152
	ds_read_b128 v[170:173], v181 offset:50176
	ds_read_b128 v[186:189], v181 offset:51200
	ds_read_b128 v[190:193], v181 offset:52224
	ds_read_b128 v[194:197], v181 offset:53248
	ds_read_b128 v[198:201], v181 offset:54272
	ds_read_b128 v[202:205], v181 offset:55296
	ds_read_b128 v[206:209], v181 offset:56320
	s_add_i32 s37, s75, s7
	v_lshl_add_u64 v[254:255], v[228:229], 0, s[16:17]
	s_mov_b32 m0, s37
	s_nop 0
	global_load_lds_dwordx4 v[254:255], off
	v_lshl_add_u64 v[254:255], v[230:231], 0, s[16:17]
	s_add_i32 m0, s37, 0x2000
	s_nop 0
	global_load_lds_dwordx4 v[254:255], off
	s_mov_b32 m0, s45
	v_lshl_add_u64 v[254:255], v[232:233], 0, s[16:17]
	global_load_lds_dwordx4 v[254:255], off
	v_lshl_add_u64 v[228:229], v[236:237], 0, s[16:17]
	s_mov_b32 m0, s46
	s_nop 0
	global_load_lds_dwordx4 v[228:229], off
	s_add_u32 s14, s14, 0x40080
	s_addc_u32 s15, s15, 0
	s_add_i32 s36, s36, s7
	v_lshl_add_u64 v[254:255], s[14:15], 0, v[146:147]
	s_mov_b32 m0, s36
	s_nop 0
	global_load_lds_dwordx4 v[254:255], off
	v_lshl_add_u64 v[254:255], s[14:15], 0, v[150:151]
	s_add_i32 m0, s36, 0x2000
	s_nop 0
	global_load_lds_dwordx4 v[254:255], off
	s_waitcnt vmcnt(6)
	s_waitcnt lgkmcnt(0)
	s_barrier
	s_setprio 1
	v_mfma_f32_16x16x32_bf16 v[60:63], v[80:83], v[166:169], v[60:63]
	v_mfma_f32_16x16x32_bf16 v[56:59], v[88:91], v[166:169], v[56:59]
	v_mfma_f32_16x16x32_bf16 v[44:47], v[80:83], v[186:189], v[44:47]
	v_mfma_f32_16x16x32_bf16 v[40:43], v[88:91], v[186:189], v[40:43]
	v_mfma_f32_16x16x32_bf16 v[28:31], v[80:83], v[194:197], v[28:31]
	v_mfma_f32_16x16x32_bf16 v[24:27], v[88:91], v[194:197], v[24:27]
	v_mfma_f32_16x16x32_bf16 v[12:15], v[80:83], v[202:205], v[12:15]
	v_mfma_f32_16x16x32_bf16 v[8:11], v[88:91], v[202:205], v[8:11]
	v_mfma_f32_16x16x32_bf16 v[60:63], v[84:87], v[170:173], v[60:63]
	v_mfma_f32_16x16x32_bf16 v[56:59], v[92:95], v[170:173], v[56:59]
	v_mfma_f32_16x16x32_bf16 v[44:47], v[84:87], v[190:193], v[44:47]
	v_mfma_f32_16x16x32_bf16 v[40:43], v[92:95], v[190:193], v[40:43]
	v_mfma_f32_16x16x32_bf16 v[28:31], v[84:87], v[198:201], v[28:31]
	v_mfma_f32_16x16x32_bf16 v[24:27], v[92:95], v[198:201], v[24:27]
	v_mfma_f32_16x16x32_bf16 v[12:15], v[84:87], v[206:209], v[12:15]
	v_mfma_f32_16x16x32_bf16 v[8:11], v[92:95], v[206:209], v[8:11]
	v_mfma_f32_16x16x32_bf16 v[52:55], v[210:213], v[166:169], v[52:55]
	v_mfma_f32_16x16x32_bf16 v[48:51], v[220:223], v[166:169], v[48:51]
	v_mfma_f32_16x16x32_bf16 v[36:39], v[210:213], v[186:189], v[36:39]
	v_mfma_f32_16x16x32_bf16 v[32:35], v[220:223], v[186:189], v[32:35]
	v_mfma_f32_16x16x32_bf16 v[20:23], v[210:213], v[194:197], v[20:23]
	v_mfma_f32_16x16x32_bf16 v[16:19], v[220:223], v[194:197], v[16:19]
	v_mfma_f32_16x16x32_bf16 v[4:7], v[210:213], v[202:205], v[4:7]
	v_mfma_f32_16x16x32_bf16 v[0:3], v[220:223], v[202:205], v[0:3]
	v_mfma_f32_16x16x32_bf16 v[52:55], v[214:217], v[170:173], v[52:55]
	v_mfma_f32_16x16x32_bf16 v[48:51], v[224:227], v[170:173], v[48:51]
	v_mfma_f32_16x16x32_bf16 v[36:39], v[214:217], v[190:193], v[36:39]
	v_mfma_f32_16x16x32_bf16 v[32:35], v[224:227], v[190:193], v[32:35]
	v_mfma_f32_16x16x32_bf16 v[20:23], v[214:217], v[198:201], v[20:23]
	v_mfma_f32_16x16x32_bf16 v[16:19], v[224:227], v[198:201], v[16:19]
	v_mfma_f32_16x16x32_bf16 v[4:7], v[214:217], v[206:209], v[4:7]
	v_mfma_f32_16x16x32_bf16 v[0:3], v[224:227], v[206:209], v[0:3]
	s_setprio 0
	s_add_i32 s74, s74, 2
	s_add_u32 s12, s12, 0x100
	s_addc_u32 s13, s13, 0
	s_add_u32 s38, s38, 0x100
	s_addc_u32 s39, s39, 0
	s_cmp_gt_u32 s74, 13
	s_barrier

; #define PG8_STAGE(bufoff, gbase, voff) do { _Pragma("unroll") for (int _i = 0; _i < 2; ++_i) \
;         __builtin_amdgcn_global_load_lds((const unsigned*)((const char*)(gbase) + (voff)[_i]), (LAS unsigned*)(lds + (bufoff) + ldsw + _i * 8192), 16, 0, 0); } while (0)
; #define PG8_LDA(dst, b, h) do { _Pragma("unroll") for (int m = 0; m < 4; ++m) _Pragma("unroll") for (int k = 0; k < 2; ++k) dst[m][k] = *(const LAS bf16x8*)(lds + PG8_SA(b, h) + aoff + m * 2048 + k * 1024); } while (0)
; #define PG8_LDB(dst, b, h) do { _Pragma("unroll") for (int n = 0; n < 2; ++n) _Pragma("unroll") for (int k = 0; k < 2; ++k) dst[n][k] = *(const LAS bf16x8*)(lds + PG8_SB(b, h) + boff + n * 2048 + k * 1024); } while (0)
; #define PG8_MMA(ai, bj, At, Bt) do { __builtin_amdgcn_s_setprio(1); _Pragma("unroll") for (int m = 0; m < 4; ++m) _Pragma("unroll") for (int n = 0; n < 2; ++n) _Pragma("unroll") for (int k = 0; k < 2; ++k) \
;         acc[ai][bj][m][n] = __builtin_amdgcn_mfma_f32_16x16x32_bf16(Bt[n][k], At[m][k], acc[ai][bj][m][n], 0, 0, 0); __builtin_amdgcn_s_setprio(0); } while (0)
; template <class Epi>
; __device__ __forceinline__ void gemm_phase(LAS unsigned char* lds, const Gemm g, const StaticOrder& S, const Epi& E) {
;     ...
;         const bool has_next = S.next(ui + 1, nxt);
;         const char* nA = has_next ? (const char*)g.A + (size_t)nxt.pm * tstepA + (size_t)(nxt.pn >> g.a_shift) * g.a_step : cA; const char* nB = has_next ? (const char*)g.Bt + (size_t)nxt.pn * tstepB : cB;
;         for (int t = 0; t < nt; t += 2) {
;             const bool last = (t == nt - 2);
;             const char* a1 = cA + (size_t)(t + 1) * kstep;
;             const char* a2 = last ? nA : cA + (size_t)(t + 2) * kstep; const char* b2 = last ? nB : cB + (size_t)(t + 2) * kstep;
;             const char* a3 = a2 + kstep; const char* b3 = b2 + kstep;
;             PG8_LDB(B0, 0, 0); PG8_SCHED; PG8_LDA(At, 0, 0); PG8_STAGE(PG8_SA(1, 1), a1 + hstepA, voffA);
;             PG8_WAIT_L(8); PG8_BAR; PG8_WAIT_L(0); PG8_MMA(0, 0, At, B0); PG8_BAR; PG8_SCHED;
;             PG8_LDB(B1, 0, 1); PG8_STAGE(PG8_SB(0, 0), b2, voffB);
;             PG8_BAR; PG8_WAIT_L(0); PG8_MMA(0, 1, At, B1); PG8_BAR;
;             PG8_LDA(At, 0, 1); PG8_STAGE(PG8_SA(0, 0), a2, voffA);
;             PG8_BAR; PG8_WAIT_L(0); PG8_MMA(1, 0, At, B0); PG8_BAR; PG8_SCHED;
;             PG8_STAGE(PG8_SB(0, 1), b2 + hstepB, voffB);
.LBB0_1819:
	s_ashr_i32 s25, s24, 31
	v_cmp_lt_i64_e32 vcc, s[26:27], v[136:137]
	s_lshl_b64 s[26:27], s[24:25], 19
	s_add_u32 s26, s68, s26
	s_addc_u32 s27, s69, s27
	s_and_b64 s[28:29], vcc, exec
	s_cselect_b32 s25, s27, s35
	s_cselect_b32 s47, s26, s34
	s_ashr_i32 s23, s22, 31
	s_lshl_b64 s[28:29], s[22:23], 19
	s_add_u32 s28, s5, s28
	s_addc_u32 s29, s6, s29
	s_and_b64 s[38:39], vcc, exec
	s_cselect_b32 s23, s29, s37
	s_cselect_b32 s48, s28, s36
	s_add_u32 s34, s34, 0x40080
	s_addc_u32 s35, s35, 0
	s_add_u32 s49, s36, 0x100
	s_addc_u32 s63, s37, 0
	s_mov_b32 s70, -2
	ds_read_b128 v[140:143], v149
	ds_read_b128 v[152:155], v149 offset:1024
	ds_read_b128 v[156:159], v149 offset:2048
	ds_read_b128 v[160:163], v149 offset:3072
	s_add_u32 s36, s34, 0xfffc0080
	s_addc_u32 s37, s35, -1
	s_cmp_eq_u32 s70, 12
	s_cselect_b32 s39, s25, s37
	s_cselect_b32 s38, s47, s36
	s_cselect_b32 s37, s23, s63
	s_cselect_b32 s36, s48, s49
	v_lshl_add_u64 v[144:145], s[34:35], 0, v[132:133]
	s_add_i32 m0, s8, 0xc000
	ds_read_b128 v[164:167], v150
	ds_read_b128 v[168:171], v150 offset:1024
	ds_read_b128 v[172:175], v150 offset:2048
	ds_read_b128 v[176:179], v150 offset:3072
	ds_read_b128 v[180:183], v150 offset:4096
	ds_read_b128 v[184:187], v150 offset:5120
	ds_read_b128 v[188:191], v150 offset:6144
	ds_read_b128 v[192:195], v150 offset:7168
	global_load_lds_dwordx4 v[144:145], off
	v_lshl_add_u64 v[144:145], s[34:35], 0, v[134:135]
	s_add_i32 m0, s8, 0xe000
	s_nop 0
	global_load_lds_dwordx4 v[144:145], off
	ds_read_b128 v[196:199], v151
	ds_read_b128 v[200:203], v151 offset:1024
	ds_read_b128 v[204:207], v151 offset:2048
	ds_read_b128 v[208:211], v151 offset:3072
	s_waitcnt lgkmcnt(0)
	s_barrier
	s_setprio 1
	v_mfma_f32_16x16x32_bf16 v[124:127], v[140:143], v[164:167], 0
	v_mfma_f32_16x16x32_bf16 v[120:123], v[156:159], v[164:167], 0
	v_mfma_f32_16x16x32_bf16 v[112:115], v[140:143], v[172:175], 0
	v_mfma_f32_16x16x32_bf16 v[104:107], v[156:159], v[172:175], 0
	v_mfma_f32_16x16x32_bf16 v[92:95], v[140:143], v[180:183], 0
	v_mfma_f32_16x16x32_bf16 v[88:91], v[156:159], v[180:183], 0
	v_mfma_f32_16x16x32_bf16 v[80:83], v[140:143], v[188:191], 0
	v_mfma_f32_16x16x32_bf16 v[72:75], v[156:159], v[188:191], 0
	v_mfma_f32_16x16x32_bf16 v[124:127], v[152:155], v[168:171], v[124:127]
	v_mfma_f32_16x16x32_bf16 v[120:123], v[160:163], v[168:171], v[120:123]
	v_mfma_f32_16x16x32_bf16 v[112:115], v[152:155], v[176:179], v[112:115]
	v_mfma_f32_16x16x32_bf16 v[104:107], v[160:163], v[176:179], v[104:107]
	v_mfma_f32_16x16x32_bf16 v[92:95], v[152:155], v[184:187], v[92:95]
	v_mfma_f32_16x16x32_bf16 v[88:91], v[160:163], v[184:187], v[88:91]
	v_mfma_f32_16x16x32_bf16 v[80:83], v[152:155], v[192:195], v[80:83]
	v_mfma_f32_16x16x32_bf16 v[72:75], v[160:163], v[192:195], v[72:75]
	v_mfma_f32_16x16x32_bf16 v[116:119], v[196:199], v[164:167], 0
	v_mfma_f32_16x16x32_bf16 v[108:111], v[204:207], v[164:167], 0
	v_mfma_f32_16x16x32_bf16 v[100:103], v[196:199], v[172:175], 0
	v_mfma_f32_16x16x32_bf16 v[96:99], v[204:207], v[172:175], 0
	v_mfma_f32_16x16x32_bf16 v[84:87], v[196:199], v[180:183], 0
	v_mfma_f32_16x16x32_bf16 v[76:79], v[204:207], v[180:183], 0
	v_mfma_f32_16x16x32_bf16 v[68:71], v[196:199], v[188:191], 0
	v_mfma_f32_16x16x32_bf16 v[64:67], v[204:207], v[188:191], 0
	v_mfma_f32_16x16x32_bf16 v[116:119], v[200:203], v[168:171], v[116:119]
	v_mfma_f32_16x16x32_bf16 v[108:111], v[208:211], v[168:171], v[108:111]
	v_mfma_f32_16x16x32_bf16 v[100:103], v[200:203], v[176:179], v[100:103]
	v_mfma_f32_16x16x32_bf16 v[96:99], v[208:211], v[176:179], v[96:99]
	v_mfma_f32_16x16x32_bf16 v[84:87], v[200:203], v[184:187], v[84:87]
	v_mfma_f32_16x16x32_bf16 v[76:79], v[208:211], v[184:187], v[76:79]
	v_mfma_f32_16x16x32_bf16 v[68:71], v[200:203], v[192:195], v[68:71]
	v_mfma_f32_16x16x32_bf16 v[64:67], v[208:211], v[192:195], v[64:67]
	s_setprio 0
	s_barrier
	s_nop 1
	ds_read_b128 v[164:167], v150 offset:16384
	ds_read_b128 v[168:171], v150 offset:17408
	ds_read_b128 v[172:175], v150 offset:18432
	ds_read_b128 v[176:179], v150 offset:19456
	ds_read_b128 v[180:183], v150 offset:20480
	ds_read_b128 v[184:187], v150 offset:21504
	ds_read_b128 v[188:191], v150 offset:22528
	ds_read_b128 v[192:195], v150 offset:23552
	s_add_i32 s71, s44, s7
	v_lshl_add_u64 v[144:145], s[36:37], 0, v[128:129]
	s_mov_b32 m0, s71
	s_nop 0
	global_load_lds_dwordx4 v[144:145], off
	v_lshl_add_u64 v[212:213], s[36:37], 0, v[130:131]
	s_add_i32 m0, s71, 0x2000
	s_nop 0
	global_load_lds_dwordx4 v[212:213], off
	s_mov_b32 m0, s8
	v_lshl_add_u64 v[214:215], s[38:39], 0, v[128:129]
	global_load_lds_dwordx4 v[214:215], off
	v_lshl_add_u64 v[216:217], s[38:39], 0, v[130:131]
	s_mov_b32 m0, s9
	s_nop 0
	global_load_lds_dwordx4 v[216:217], off
	s_add_u32 s72, s36, 0x40000
	s_addc_u32 s73, s37, 0
	s_add_i32 s71, s45, s7
	v_lshl_add_u64 v[254:255], s[72:73], 0, v[128:129]
	s_mov_b32 m0, s71
	s_nop 0
	global_load_lds_dwordx4 v[254:255], off
	v_lshl_add_u64 v[254:255], s[72:73], 0, v[130:131]
	s_add_i32 m0, s71, 0x2000
	s_nop 0
	global_load_lds_dwordx4 v[254:255], off
	s_waitcnt vmcnt(6)
	s_waitcnt lgkmcnt(0)
	s_barrier
; #define PG8_STAGE(bufoff, gbase, voff) do { _Pragma("unroll") for (int _i = 0; _i < 2; ++_i) \
;         __builtin_amdgcn_global_load_lds((const unsigned*)((const char*)(gbase) + (voff)[_i]), (LAS unsigned*)(lds + (bufoff) + ldsw + _i * 8192), 16, 0, 0); } while (0)
; #define PG8_LDA(dst, b, h) do { _Pragma("unroll") for (int m = 0; m < 4; ++m) _Pragma("unroll") for (int k = 0; k < 2; ++k) dst[m][k] = *(const LAS bf16x8*)(lds + PG8_SA(b, h) + aoff + m * 2048 + k * 1024); } while (0)
; #define PG8_LDB(dst, b, h) do { _Pragma("unroll") for (int n = 0; n < 2; ++n) _Pragma("unroll") for (int k = 0; k < 2; ++k) dst[n][k] = *(const LAS bf16x8*)(lds + PG8_SB(b, h) + boff + n * 2048 + k * 1024); } while (0)
; #define PG8_MMA(ai, bj, At, Bt) do { __builtin_amdgcn_s_setprio(1); _Pragma("unroll") for (int m = 0; m < 4; ++m) _Pragma("unroll") for (int n = 0; n < 2; ++n) _Pragma("unroll") for (int k = 0; k < 2; ++k) \
;         acc[ai][bj][m][n] = __builtin_amdgcn_mfma_f32_16x16x32_bf16(Bt[n][k], At[m][k], acc[ai][bj][m][n], 0, 0, 0); __builtin_amdgcn_s_setprio(0); } while (0)
; #define PG8_WAIT_V(n) asm volatile("s_waitcnt vmcnt(" #n ")" ::: "memory")
; #define PG8_WAIT_L(n) asm volatile("s_waitcnt lgkmcnt(" #n ")" ::: "memory")
; #define PG8_BAR __builtin_amdgcn_s_barrier()
; #define PG8_SCHED __builtin_amdgcn_sched_barrier(0)
; template <class Epi>
; __device__ __forceinline__ void gemm_phase(LAS unsigned char* lds, const Gemm g, const StaticOrder& S, const Epi& E) {
;     ...
;             PG8_BAR; PG8_WAIT_L(0); PG8_MMA(1, 0, At, B0); PG8_BAR; PG8_SCHED;
;             PG8_STAGE(PG8_SB(0, 1), b2 + hstepB, voffB);
;             PG8_WAIT_V(6); PG8_BAR; PG8_MMA(1, 1, At, B1); PG8_BAR;
;             PG8_LDB(B0, 1, 0); PG8_SCHED; PG8_LDA(At, 1, 0); PG8_STAGE(PG8_SA(0, 1), a2 + hstepA, voffA);
;             PG8_WAIT_L(8); PG8_BAR; PG8_WAIT_L(0); PG8_MMA(0, 0, At, B0); PG8_BAR; PG8_SCHED;
;             PG8_LDB(B1, 1, 1); PG8_STAGE(PG8_SB(1, 0), b3, voffB);
;             PG8_BAR; PG8_WAIT_L(0); PG8_MMA(0, 1, At, B1); PG8_BAR;
	s_setprio 1
	v_mfma_f32_16x16x32_bf16 v[60:63], v[140:143], v[164:167], 0
	v_mfma_f32_16x16x32_bf16 v[56:59], v[156:159], v[164:167], 0
	v_mfma_f32_16x16x32_bf16 v[48:51], v[140:143], v[172:175], 0
	v_mfma_f32_16x16x32_bf16 v[40:43], v[156:159], v[172:175], 0
	v_mfma_f32_16x16x32_bf16 v[28:31], v[140:143], v[180:183], 0
	v_mfma_f32_16x16x32_bf16 v[24:27], v[156:159], v[180:183], 0
	v_mfma_f32_16x16x32_bf16 v[16:19], v[140:143], v[188:191], 0
	v_mfma_f32_16x16x32_bf16 v[8:11], v[156:159], v[188:191], 0
	v_mfma_f32_16x16x32_bf16 v[60:63], v[152:155], v[168:171], v[60:63]
	v_mfma_f32_16x16x32_bf16 v[56:59], v[160:163], v[168:171], v[56:59]
	v_mfma_f32_16x16x32_bf16 v[48:51], v[152:155], v[176:179], v[48:51]
	v_mfma_f32_16x16x32_bf16 v[40:43], v[160:163], v[176:179], v[40:43]
	v_mfma_f32_16x16x32_bf16 v[28:31], v[152:155], v[184:187], v[28:31]
	v_mfma_f32_16x16x32_bf16 v[24:27], v[160:163], v[184:187], v[24:27]
	v_mfma_f32_16x16x32_bf16 v[16:19], v[152:155], v[192:195], v[16:19]
	v_mfma_f32_16x16x32_bf16 v[8:11], v[160:163], v[192:195], v[8:11]
	v_mfma_f32_16x16x32_bf16 v[52:55], v[196:199], v[164:167], 0
	v_mfma_f32_16x16x32_bf16 v[44:47], v[204:207], v[164:167], 0
	v_mfma_f32_16x16x32_bf16 v[36:39], v[196:199], v[172:175], 0
	v_mfma_f32_16x16x32_bf16 v[32:35], v[204:207], v[172:175], 0
	v_mfma_f32_16x16x32_bf16 v[20:23], v[196:199], v[180:183], 0
	v_mfma_f32_16x16x32_bf16 v[12:15], v[204:207], v[180:183], 0
	v_mfma_f32_16x16x32_bf16 v[4:7], v[196:199], v[188:191], 0
	v_mfma_f32_16x16x32_bf16 v[0:3], v[204:207], v[188:191], 0
	v_mfma_f32_16x16x32_bf16 v[52:55], v[200:203], v[168:171], v[52:55]
	v_mfma_f32_16x16x32_bf16 v[44:47], v[208:211], v[168:171], v[44:47]
	v_mfma_f32_16x16x32_bf16 v[36:39], v[200:203], v[176:179], v[36:39]
	v_mfma_f32_16x16x32_bf16 v[32:35], v[208:211], v[176:179], v[32:35]
	v_mfma_f32_16x16x32_bf16 v[20:23], v[200:203], v[184:187], v[20:23]
	v_mfma_f32_16x16x32_bf16 v[12:15], v[208:211], v[184:187], v[12:15]
	v_mfma_f32_16x16x32_bf16 v[4:7], v[200:203], v[192:195], v[4:7]
	v_mfma_f32_16x16x32_bf16 v[0:3], v[208:211], v[192:195], v[0:3]
	s_setprio 0
	s_add_i32 s71, 0, 0x18000
	v_add_u32_e32 v160, s71, v147
	s_barrier
	ds_read_b128 v[140:143], v160
	ds_read_b128 v[152:155], v160 offset:1024
	ds_read_b128 v[156:159], v160 offset:2048
	ds_read_b128 v[160:163], v160 offset:3072
	s_add_u32 s38, s38, 0x40000
	s_addc_u32 s39, s39, 0
	s_mov_b32 m0, s31
	v_lshl_add_u64 v[196:197], s[38:39], 0, v[128:129]
	ds_read_b128 v[164:167], v150 offset:32768
	ds_read_b128 v[168:171], v150 offset:33792
	ds_read_b128 v[172:175], v150 offset:34816
	ds_read_b128 v[176:179], v150 offset:35840
	ds_read_b128 v[180:183], v150 offset:36864
	ds_read_b128 v[184:187], v150 offset:37888
	ds_read_b128 v[188:191], v150 offset:38912
	ds_read_b128 v[192:195], v150 offset:39936
	global_load_lds_dwordx4 v[196:197], off
	v_lshl_add_u64 v[196:197], s[38:39], 0, v[130:131]
	s_mov_b32 m0, s40
	s_nop 0
	global_load_lds_dwordx4 v[196:197], off
	s_add_i32 s38, 0, 0x1c000
	v_add_u32_e32 v208, s38, v147
	ds_read_b128 v[196:199], v208
	ds_read_b128 v[200:203], v208 offset:1024
	ds_read_b128 v[204:207], v208 offset:2048
	ds_read_b128 v[208:211], v208 offset:3072
	s_waitcnt lgkmcnt(0)
	s_barrier
	s_setprio 1
	v_mfma_f32_16x16x32_bf16 v[124:127], v[140:143], v[164:167], v[124:127]
	v_mfma_f32_16x16x32_bf16 v[120:123], v[156:159], v[164:167], v[120:123]
	v_mfma_f32_16x16x32_bf16 v[112:115], v[140:143], v[172:175], v[112:115]
	v_mfma_f32_16x16x32_bf16 v[104:107], v[156:159], v[172:175], v[104:107]
	v_mfma_f32_16x16x32_bf16 v[92:95], v[140:143], v[180:183], v[92:95]
	v_mfma_f32_16x16x32_bf16 v[88:91], v[156:159], v[180:183], v[88:91]
	v_mfma_f32_16x16x32_bf16 v[80:83], v[140:143], v[188:191], v[80:83]
	v_mfma_f32_16x16x32_bf16 v[72:75], v[156:159], v[188:191], v[72:75]
	v_mfma_f32_16x16x32_bf16 v[124:127], v[152:155], v[168:171], v[124:127]
	v_mfma_f32_16x16x32_bf16 v[120:123], v[160:163], v[168:171], v[120:123]
	v_mfma_f32_16x16x32_bf16 v[112:115], v[152:155], v[176:179], v[112:115]
	v_mfma_f32_16x16x32_bf16 v[104:107], v[160:163], v[176:179], v[104:107]
	v_mfma_f32_16x16x32_bf16 v[92:95], v[152:155], v[184:187], v[92:95]
	v_mfma_f32_16x16x32_bf16 v[88:91], v[160:163], v[184:187], v[88:91]
	v_mfma_f32_16x16x32_bf16 v[80:83], v[152:155], v[192:195], v[80:83]
	v_mfma_f32_16x16x32_bf16 v[72:75], v[160:163], v[192:195], v[72:75]
	v_mfma_f32_16x16x32_bf16 v[116:119], v[196:199], v[164:167], v[116:119]
	v_mfma_f32_16x16x32_bf16 v[108:111], v[204:207], v[164:167], v[108:111]
	v_mfma_f32_16x16x32_bf16 v[100:103], v[196:199], v[172:175], v[100:103]
	v_mfma_f32_16x16x32_bf16 v[96:99], v[204:207], v[172:175], v[96:99]
	v_mfma_f32_16x16x32_bf16 v[84:87], v[196:199], v[180:183], v[84:87]
	v_mfma_f32_16x16x32_bf16 v[76:79], v[204:207], v[180:183], v[76:79]
	v_mfma_f32_16x16x32_bf16 v[68:71], v[196:199], v[188:191], v[68:71]
	v_mfma_f32_16x16x32_bf16 v[64:67], v[204:207], v[188:191], v[64:67]
	v_mfma_f32_16x16x32_bf16 v[116:119], v[200:203], v[168:171], v[116:119]
	v_mfma_f32_16x16x32_bf16 v[108:111], v[208:211], v[168:171], v[108:111]
	v_mfma_f32_16x16x32_bf16 v[100:103], v[200:203], v[176:179], v[100:103]
	v_mfma_f32_16x16x32_bf16 v[96:99], v[208:211], v[176:179], v[96:99]
	v_mfma_f32_16x16x32_bf16 v[84:87], v[200:203], v[184:187], v[84:87]
	v_mfma_f32_16x16x32_bf16 v[76:79], v[208:211], v[184:187], v[76:79]
	v_mfma_f32_16x16x32_bf16 v[68:71], v[200:203], v[192:195], v[68:71]
	v_mfma_f32_16x16x32_bf16 v[64:67], v[208:211], v[192:195], v[64:67]
	s_setprio 0
	s_barrier
; #define PG8_STAGE(bufoff, gbase, voff) do { _Pragma("unroll") for (int _i = 0; _i < 2; ++_i) \
;         __builtin_amdgcn_global_load_lds((const unsigned*)((const char*)(gbase) + (voff)[_i]), (LAS unsigned*)(lds + (bufoff) + ldsw + _i * 8192), 16, 0, 0); } while (0)
; #define PG8_LDA(dst, b, h) do { _Pragma("unroll") for (int m = 0; m < 4; ++m) _Pragma("unroll") for (int k = 0; k < 2; ++k) dst[m][k] = *(const LAS bf16x8*)(lds + PG8_SA(b, h) + aoff + m * 2048 + k * 1024); } while (0)
; #define PG8_MMA(ai, bj, At, Bt) do { __builtin_amdgcn_s_setprio(1); _Pragma("unroll") for (int m = 0; m < 4; ++m) _Pragma("unroll") for (int n = 0; n < 2; ++n) _Pragma("unroll") for (int k = 0; k < 2; ++k) \
;         acc[ai][bj][m][n] = __builtin_amdgcn_mfma_f32_16x16x32_bf16(Bt[n][k], At[m][k], acc[ai][bj][m][n], 0, 0, 0); __builtin_amdgcn_s_setprio(0); } while (0)
; #define PG8_WAIT_V(n) asm volatile("s_waitcnt vmcnt(" #n ")" ::: "memory")
; #define PG8_WAIT_L(n) asm volatile("s_waitcnt lgkmcnt(" #n ")" ::: "memory")
; #define PG8_BAR __builtin_amdgcn_s_barrier()
; #define PG8_SCHED __builtin_amdgcn_sched_barrier(0)
; template <class Epi>
; __device__ __forceinline__ void gemm_phase(LAS unsigned char* lds, const Gemm g, const StaticOrder& S, const Epi& E) {
;     ...
;             PG8_LDA(At, 1, 1); PG8_STAGE(PG8_SA(1, 0), a3, voffA);
;             PG8_BAR; PG8_WAIT_L(0); PG8_MMA(1, 0, At, B0); PG8_BAR; PG8_SCHED;
;             PG8_STAGE(PG8_SB(1, 1), b3 + hstepB, voffB);
;             PG8_WAIT_V(6); PG8_BAR; PG8_MMA(1, 1, At, B1); PG8_BAR;
	s_nop 1
	ds_read_b128 v[164:167], v150 offset:49152
	ds_read_b128 v[168:171], v150 offset:50176
	ds_read_b128 v[172:175], v150 offset:51200
	ds_read_b128 v[176:179], v150 offset:52224
	ds_read_b128 v[180:183], v150 offset:53248
	ds_read_b128 v[184:187], v150 offset:54272
	ds_read_b128 v[188:191], v150 offset:55296
	ds_read_b128 v[192:195], v150 offset:56320
	s_add_i32 s39, s71, s7
	v_lshl_add_u64 v[254:255], v[144:145], 0, s[12:13]
	s_mov_b32 m0, s39
	s_nop 0
	global_load_lds_dwordx4 v[254:255], off
	v_lshl_add_u64 v[254:255], v[212:213], 0, s[12:13]
	s_add_i32 m0, s39, 0x2000
	s_nop 0
	global_load_lds_dwordx4 v[254:255], off
	s_mov_b32 m0, s42
	v_lshl_add_u64 v[254:255], v[214:215], 0, s[12:13]
	global_load_lds_dwordx4 v[254:255], off
	v_lshl_add_u64 v[144:145], v[216:217], 0, s[12:13]
	s_mov_b32 m0, s43
	s_nop 0
	global_load_lds_dwordx4 v[144:145], off
	s_add_u32 s36, s36, 0x40080
	s_addc_u32 s37, s37, 0
	s_add_i32 s38, s38, s7
	v_lshl_add_u64 v[254:255], s[36:37], 0, v[128:129]
	s_mov_b32 m0, s38
	s_nop 0
	global_load_lds_dwordx4 v[254:255], off
	v_lshl_add_u64 v[254:255], s[36:37], 0, v[130:131]
	s_add_i32 m0, s38, 0x2000
	s_nop 0
	global_load_lds_dwordx4 v[254:255], off
	s_waitcnt vmcnt(6)
	s_waitcnt lgkmcnt(0)
	s_barrier
	s_setprio 1
	v_mfma_f32_16x16x32_bf16 v[60:63], v[140:143], v[164:167], v[60:63]
	v_mfma_f32_16x16x32_bf16 v[56:59], v[156:159], v[164:167], v[56:59]
	v_mfma_f32_16x16x32_bf16 v[48:51], v[140:143], v[172:175], v[48:51]
	v_mfma_f32_16x16x32_bf16 v[40:43], v[156:159], v[172:175], v[40:43]
	v_mfma_f32_16x16x32_bf16 v[28:31], v[140:143], v[180:183], v[28:31]
	v_mfma_f32_16x16x32_bf16 v[24:27], v[156:159], v[180:183], v[24:27]
	v_mfma_f32_16x16x32_bf16 v[16:19], v[140:143], v[188:191], v[16:19]
	v_mfma_f32_16x16x32_bf16 v[8:11], v[156:159], v[188:191], v[8:11]
	v_mfma_f32_16x16x32_bf16 v[60:63], v[152:155], v[168:171], v[60:63]
	v_mfma_f32_16x16x32_bf16 v[56:59], v[160:163], v[168:171], v[56:59]
	v_mfma_f32_16x16x32_bf16 v[48:51], v[152:155], v[176:179], v[48:51]
	v_mfma_f32_16x16x32_bf16 v[40:43], v[160:163], v[176:179], v[40:43]
	v_mfma_f32_16x16x32_bf16 v[28:31], v[152:155], v[184:187], v[28:31]
	v_mfma_f32_16x16x32_bf16 v[24:27], v[160:163], v[184:187], v[24:27]
	v_mfma_f32_16x16x32_bf16 v[16:19], v[152:155], v[192:195], v[16:19]
	v_mfma_f32_16x16x32_bf16 v[8:11], v[160:163], v[192:195], v[8:11]
	v_mfma_f32_16x16x32_bf16 v[52:55], v[196:199], v[164:167], v[52:55]
	v_mfma_f32_16x16x32_bf16 v[44:47], v[204:207], v[164:167], v[44:47]
	v_mfma_f32_16x16x32_bf16 v[36:39], v[196:199], v[172:175], v[36:39]
	v_mfma_f32_16x16x32_bf16 v[32:35], v[204:207], v[172:175], v[32:35]
	v_mfma_f32_16x16x32_bf16 v[20:23], v[196:199], v[180:183], v[20:23]
	v_mfma_f32_16x16x32_bf16 v[12:15], v[204:207], v[180:183], v[12:15]
	v_mfma_f32_16x16x32_bf16 v[4:7], v[196:199], v[188:191], v[4:7]
	v_mfma_f32_16x16x32_bf16 v[0:3], v[204:207], v[188:191], v[0:3]
	v_mfma_f32_16x16x32_bf16 v[52:55], v[200:203], v[168:171], v[52:55]
	v_mfma_f32_16x16x32_bf16 v[44:47], v[208:211], v[168:171], v[44:47]
	v_mfma_f32_16x16x32_bf16 v[36:39], v[200:203], v[176:179], v[36:39]
	v_mfma_f32_16x16x32_bf16 v[32:35], v[208:211], v[176:179], v[32:35]
	v_mfma_f32_16x16x32_bf16 v[20:23], v[200:203], v[184:187], v[20:23]
	v_mfma_f32_16x16x32_bf16 v[12:15], v[208:211], v[184:187], v[12:15]
	v_mfma_f32_16x16x32_bf16 v[4:7], v[200:203], v[192:195], v[4:7]
	v_mfma_f32_16x16x32_bf16 v[0:3], v[208:211], v[192:195], v[0:3]
	s_setprio 0
	s_add_i32 s70, s70, 2
	s_add_u32 s34, s34, 0x100
	s_addc_u32 s35, s35, 0
	s_add_u32 s49, s49, 0x100
	s_addc_u32 s63, s63, 0
	s_cmp_gt_u32 s70, 13
	s_barrier

; #define PG8_STAGE(bufoff, gbase, voff) do { _Pragma("unroll") for (int _i = 0; _i < 2; ++_i) \
;         __builtin_amdgcn_global_load_lds((const unsigned*)((const char*)(gbase) + (voff)[_i]), (LAS unsigned*)(lds + (bufoff) + ldsw + _i * 8192), 16, 0, 0); } while (0)
; #define PG8_LDA(dst, b, h) do { _Pragma("unroll") for (int m = 0; m < 4; ++m) _Pragma("unroll") for (int k = 0; k < 2; ++k) dst[m][k] = *(const LAS bf16x8*)(lds + PG8_SA(b, h) + aoff + m * 2048 + k * 1024); } while (0)
; #define PG8_LDB(dst, b, h) do { _Pragma("unroll") for (int n = 0; n < 2; ++n) _Pragma("unroll") for (int k = 0; k < 2; ++k) dst[n][k] = *(const LAS bf16x8*)(lds + PG8_SB(b, h) + boff + n * 2048 + k * 1024); } while (0)
; #define PG8_MMA(ai, bj, At, Bt) do { __builtin_amdgcn_s_setprio(1); _Pragma("unroll") for (int m = 0; m < 4; ++m) _Pragma("unroll") for (int n = 0; n < 2; ++n) _Pragma("unroll") for (int k = 0; k < 2; ++k) \
;         acc[ai][bj][m][n] = __builtin_amdgcn_mfma_f32_16x16x32_bf16(Bt[n][k], At[m][k], acc[ai][bj][m][n], 0, 0, 0); __builtin_amdgcn_s_setprio(0); } while (0)
; template <class Epi>
; __device__ __forceinline__ void gemm_phase(LAS unsigned char* lds, const Gemm g, const StaticOrder& S, const Epi& E) {
;     ...
;         const bool has_next = S.next(ui + 1, nxt);
;         const char* nA = has_next ? (const char*)g.A + (size_t)nxt.pm * tstepA + (size_t)(nxt.pn >> g.a_shift) * g.a_step : cA; const char* nB = has_next ? (const char*)g.Bt + (size_t)nxt.pn * tstepB : cB;
;         for (int t = 0; t < nt; t += 2) {
;             const bool last = (t == nt - 2);
;             const char* a1 = cA + (size_t)(t + 1) * kstep;
;             const char* a2 = last ? nA : cA + (size_t)(t + 2) * kstep; const char* b2 = last ? nB : cB + (size_t)(t + 2) * kstep;
;             const char* a3 = a2 + kstep; const char* b3 = b2 + kstep;
;             PG8_LDB(B0, 0, 0); PG8_SCHED; PG8_LDA(At, 0, 0); PG8_STAGE(PG8_SA(1, 1), a1 + hstepA, voffA);
;             PG8_WAIT_L(8); PG8_BAR; PG8_WAIT_L(0); PG8_MMA(0, 0, At, B0); PG8_BAR; PG8_SCHED;
;             PG8_LDB(B1, 0, 1); PG8_STAGE(PG8_SB(0, 0), b2, voffB);
;             PG8_BAR; PG8_WAIT_L(0); PG8_MMA(0, 1, At, B1); PG8_BAR;
;             PG8_LDA(At, 0, 1); PG8_STAGE(PG8_SA(0, 0), a2, voffA);
;             PG8_BAR; PG8_WAIT_L(0); PG8_MMA(1, 0, At, B0); PG8_BAR; PG8_SCHED;
;             PG8_STAGE(PG8_SB(0, 1), b2 + hstepB, voffB);
.LBB0_1939:
	s_ashr_i32 s27, s26, 31
	v_cmp_lt_i64_e32 vcc, s[28:29], v[228:229]
	s_lshl_b64 s[28:29], s[26:27], 19
	s_add_u32 s28, s66, s28
	s_addc_u32 s29, s67, s29
	s_and_b64 s[30:31], vcc, exec
	s_cselect_b32 s27, s29, s37
	s_cselect_b32 s68, s28, s36
	s_ashr_i32 s25, s24, 31
	s_lshl_b64 s[30:31], s[24:25], 19
	s_add_u32 s30, s5, s30
	s_addc_u32 s31, s6, s31
	s_and_b64 s[40:41], vcc, exec
	s_cselect_b32 s25, s31, s39
	s_cselect_b32 s69, s30, s38
	s_add_u32 s70, s38, 0x100
	s_addc_u32 s71, s39, 0
	s_mov_b32 s72, -2
	ds_read_b128 v[96:99], v242
	ds_read_b128 v[100:103], v242 offset:1024
	ds_read_b128 v[104:107], v242 offset:2048
	ds_read_b128 v[108:111], v242 offset:3072
	s_add_u32 s38, s36, 0x100
	s_addc_u32 s39, s37, 0
	s_cmp_eq_u32 s72, 12
	s_cselect_b32 s43, s27, s39
	s_cselect_b32 s42, s68, s38
	s_cselect_b32 s41, s25, s71
	s_cselect_b32 s40, s69, s70
	v_lshl_add_u64 v[176:177], s[36:37], 0, v[224:225]
	s_add_i32 m0, s45, 0xc000
	ds_read_b128 v[112:115], v243
	ds_read_b128 v[116:119], v243 offset:1024
	ds_read_b128 v[120:123], v243 offset:2048
	ds_read_b128 v[124:127], v243 offset:3072
	ds_read_b128 v[160:163], v243 offset:4096
	ds_read_b128 v[164:167], v243 offset:5120
	ds_read_b128 v[168:171], v243 offset:6144
	ds_read_b128 v[172:175], v243 offset:7168
	global_load_lds_dwordx4 v[176:177], off
	v_lshl_add_u64 v[176:177], s[36:37], 0, v[226:227]
	s_add_i32 m0, s45, 0xe000
	s_nop 0
	global_load_lds_dwordx4 v[176:177], off
	ds_read_b128 v[176:179], v244
	ds_read_b128 v[180:183], v244 offset:1024
	ds_read_b128 v[184:187], v244 offset:2048
	ds_read_b128 v[188:191], v244 offset:3072
	s_waitcnt lgkmcnt(0)
	s_barrier
	s_setprio 1
	v_mfma_f32_16x16x32_bf16 v[156:159], v[96:99], v[112:115], 0
	v_mfma_f32_16x16x32_bf16 v[60:63], v[104:107], v[112:115], 0
	v_mfma_f32_16x16x32_bf16 v[144:147], v[96:99], v[120:123], 0
	v_mfma_f32_16x16x32_bf16 v[48:51], v[104:107], v[120:123], 0
	v_mfma_f32_16x16x32_bf16 v[136:139], v[96:99], v[160:163], 0
	v_mfma_f32_16x16x32_bf16 v[40:43], v[104:107], v[160:163], 0
	v_mfma_f32_16x16x32_bf16 v[148:151], v[96:99], v[168:171], 0
	v_mfma_f32_16x16x32_bf16 v[52:55], v[104:107], v[168:171], 0
	v_mfma_f32_16x16x32_bf16 v[156:159], v[100:103], v[116:119], v[156:159]
	v_mfma_f32_16x16x32_bf16 v[60:63], v[108:111], v[116:119], v[60:63]
	v_mfma_f32_16x16x32_bf16 v[144:147], v[100:103], v[124:127], v[144:147]
	v_mfma_f32_16x16x32_bf16 v[48:51], v[108:111], v[124:127], v[48:51]
	v_mfma_f32_16x16x32_bf16 v[136:139], v[100:103], v[164:167], v[136:139]
	v_mfma_f32_16x16x32_bf16 v[40:43], v[108:111], v[164:167], v[40:43]
	v_mfma_f32_16x16x32_bf16 v[148:151], v[100:103], v[172:175], v[148:151]
	v_mfma_f32_16x16x32_bf16 v[52:55], v[108:111], v[172:175], v[52:55]
	v_mfma_f32_16x16x32_bf16 v[152:155], v[176:179], v[112:115], 0
	v_mfma_f32_16x16x32_bf16 v[56:59], v[184:187], v[112:115], 0
	v_mfma_f32_16x16x32_bf16 v[36:39], v[184:187], v[120:123], 0
	v_mfma_f32_16x16x32_bf16 v[32:35], v[184:187], v[160:163], 0
	v_mfma_f32_16x16x32_bf16 v[44:47], v[184:187], v[168:171], 0
	v_mfma_f32_16x16x32_bf16 v[152:155], v[180:183], v[116:119], v[152:155]
	v_mfma_f32_16x16x32_bf16 v[56:59], v[188:191], v[116:119], v[56:59]
	v_mfma_f32_16x16x32_bf16 v[112:115], v[176:179], v[120:123], 0
	v_mfma_f32_16x16x32_bf16 v[36:39], v[188:191], v[124:127], v[36:39]
	v_mfma_f32_16x16x32_bf16 v[116:119], v[176:179], v[160:163], 0
	v_mfma_f32_16x16x32_bf16 v[32:35], v[188:191], v[164:167], v[32:35]
	v_mfma_f32_16x16x32_bf16 v[120:123], v[176:179], v[168:171], 0
	v_mfma_f32_16x16x32_bf16 v[44:47], v[188:191], v[172:175], v[44:47]
	v_mfma_f32_16x16x32_bf16 v[112:115], v[180:183], v[124:127], v[112:115]
	v_mfma_f32_16x16x32_bf16 v[116:119], v[180:183], v[164:167], v[116:119]
	v_mfma_f32_16x16x32_bf16 v[120:123], v[180:183], v[172:175], v[120:123]
	s_setprio 0
	s_barrier
	s_nop 1
	ds_read_b128 v[124:127], v243 offset:16384
	ds_read_b128 v[128:131], v243 offset:17408
	ds_read_b128 v[132:135], v243 offset:18432
	ds_read_b128 v[140:143], v243 offset:19456
	ds_read_b128 v[160:163], v243 offset:20480
	ds_read_b128 v[164:167], v243 offset:21504
	ds_read_b128 v[168:171], v243 offset:22528
	ds_read_b128 v[172:175], v243 offset:23552
	s_add_i32 s36, s59, s7
	v_lshl_add_u64 v[196:197], s[40:41], 0, v[214:215]
	s_mov_b32 m0, s36
	s_nop 0
	global_load_lds_dwordx4 v[196:197], off
	v_lshl_add_u64 v[198:199], s[40:41], 0, v[210:211]
	s_add_i32 m0, s36, 0x2000
	s_nop 0
	global_load_lds_dwordx4 v[198:199], off
	s_mov_b32 m0, s45
	v_lshl_add_u64 v[200:201], s[42:43], 0, v[216:217]
	global_load_lds_dwordx4 v[200:201], off
	v_lshl_add_u64 v[202:203], s[42:43], 0, v[212:213]
	s_mov_b32 m0, s46
	s_nop 0
	global_load_lds_dwordx4 v[202:203], off
	s_add_u32 s36, s40, 0x40000
	s_addc_u32 s37, s41, 0
	s_add_i32 s73, s62, s7
	v_lshl_add_u64 v[254:255], s[36:37], 0, v[214:215]
	s_mov_b32 m0, s73
	s_nop 0
	global_load_lds_dwordx4 v[254:255], off
	v_lshl_add_u64 v[254:255], s[36:37], 0, v[210:211]
	s_add_i32 m0, s73, 0x2000
	s_nop 0
	global_load_lds_dwordx4 v[254:255], off
	s_waitcnt vmcnt(6)
	s_waitcnt lgkmcnt(0)
	s_barrier
; #define PG8_STAGE(bufoff, gbase, voff) do { _Pragma("unroll") for (int _i = 0; _i < 2; ++_i) \
;         __builtin_amdgcn_global_load_lds((const unsigned*)((const char*)(gbase) + (voff)[_i]), (LAS unsigned*)(lds + (bufoff) + ldsw + _i * 8192), 16, 0, 0); } while (0)
; #define PG8_LDA(dst, b, h) do { _Pragma("unroll") for (int m = 0; m < 4; ++m) _Pragma("unroll") for (int k = 0; k < 2; ++k) dst[m][k] = *(const LAS bf16x8*)(lds + PG8_SA(b, h) + aoff + m * 2048 + k * 1024); } while (0)
; #define PG8_LDB(dst, b, h) do { _Pragma("unroll") for (int n = 0; n < 2; ++n) _Pragma("unroll") for (int k = 0; k < 2; ++k) dst[n][k] = *(const LAS bf16x8*)(lds + PG8_SB(b, h) + boff + n * 2048 + k * 1024); } while (0)
; #define PG8_MMA(ai, bj, At, Bt) do { __builtin_amdgcn_s_setprio(1); _Pragma("unroll") for (int m = 0; m < 4; ++m) _Pragma("unroll") for (int n = 0; n < 2; ++n) _Pragma("unroll") for (int k = 0; k < 2; ++k) \
;         acc[ai][bj][m][n] = __builtin_amdgcn_mfma_f32_16x16x32_bf16(Bt[n][k], At[m][k], acc[ai][bj][m][n], 0, 0, 0); __builtin_amdgcn_s_setprio(0); } while (0)
; #define PG8_WAIT_V(n) asm volatile("s_waitcnt vmcnt(" #n ")" ::: "memory")
; #define PG8_WAIT_L(n) asm volatile("s_waitcnt lgkmcnt(" #n ")" ::: "memory")
; #define PG8_BAR __builtin_amdgcn_s_barrier()
; #define PG8_SCHED __builtin_amdgcn_sched_barrier(0)
; template <class Epi>
; __device__ __forceinline__ void gemm_phase(LAS unsigned char* lds, const Gemm g, const StaticOrder& S, const Epi& E) {
;     ...
;             PG8_BAR; PG8_WAIT_L(0); PG8_MMA(1, 0, At, B0); PG8_BAR; PG8_SCHED;
;             PG8_STAGE(PG8_SB(0, 1), b2 + hstepB, voffB);
;             PG8_WAIT_V(6); PG8_BAR; PG8_MMA(1, 1, At, B1); PG8_BAR;
;             PG8_LDB(B0, 1, 0); PG8_SCHED; PG8_LDA(At, 1, 0); PG8_STAGE(PG8_SA(0, 1), a2 + hstepA, voffA);
;             PG8_WAIT_L(8); PG8_BAR; PG8_WAIT_L(0); PG8_MMA(0, 0, At, B0); PG8_BAR; PG8_SCHED;
;             PG8_LDB(B1, 1, 1); PG8_STAGE(PG8_SB(1, 0), b3, voffB);
;             PG8_BAR; PG8_WAIT_L(0); PG8_MMA(0, 1, At, B1); PG8_BAR;
	s_setprio 1
	v_mfma_f32_16x16x32_bf16 v[92:95], v[96:99], v[124:127], 0
	v_mfma_f32_16x16x32_bf16 v[28:31], v[104:107], v[124:127], 0
	v_mfma_f32_16x16x32_bf16 v[80:83], v[96:99], v[132:135], 0
	v_mfma_f32_16x16x32_bf16 v[16:19], v[104:107], v[132:135], 0
	v_mfma_f32_16x16x32_bf16 v[76:79], v[96:99], v[160:163], 0
	v_mfma_f32_16x16x32_bf16 v[12:15], v[104:107], v[160:163], 0
	v_mfma_f32_16x16x32_bf16 v[84:87], v[96:99], v[168:171], 0
	v_mfma_f32_16x16x32_bf16 v[20:23], v[104:107], v[168:171], 0
	v_mfma_f32_16x16x32_bf16 v[92:95], v[100:103], v[128:131], v[92:95]
	v_mfma_f32_16x16x32_bf16 v[28:31], v[108:111], v[128:131], v[28:31]
	v_mfma_f32_16x16x32_bf16 v[80:83], v[100:103], v[140:143], v[80:83]
	v_mfma_f32_16x16x32_bf16 v[16:19], v[108:111], v[140:143], v[16:19]
	v_mfma_f32_16x16x32_bf16 v[76:79], v[100:103], v[164:167], v[76:79]
	v_mfma_f32_16x16x32_bf16 v[12:15], v[108:111], v[164:167], v[12:15]
	v_mfma_f32_16x16x32_bf16 v[84:87], v[100:103], v[172:175], v[84:87]
	v_mfma_f32_16x16x32_bf16 v[20:23], v[108:111], v[172:175], v[20:23]
	v_mfma_f32_16x16x32_bf16 v[88:91], v[176:179], v[124:127], 0
	v_mfma_f32_16x16x32_bf16 v[24:27], v[184:187], v[124:127], 0
	v_mfma_f32_16x16x32_bf16 v[68:71], v[176:179], v[132:135], 0
	v_mfma_f32_16x16x32_bf16 v[4:7], v[184:187], v[132:135], 0
	v_mfma_f32_16x16x32_bf16 v[64:67], v[176:179], v[160:163], 0
	v_mfma_f32_16x16x32_bf16 v[0:3], v[184:187], v[160:163], 0
	v_mfma_f32_16x16x32_bf16 v[72:75], v[176:179], v[168:171], 0
	v_mfma_f32_16x16x32_bf16 v[8:11], v[184:187], v[168:171], 0
	v_mfma_f32_16x16x32_bf16 v[88:91], v[180:183], v[128:131], v[88:91]
	v_mfma_f32_16x16x32_bf16 v[24:27], v[188:191], v[128:131], v[24:27]
	v_mfma_f32_16x16x32_bf16 v[68:71], v[180:183], v[140:143], v[68:71]
	v_mfma_f32_16x16x32_bf16 v[4:7], v[188:191], v[140:143], v[4:7]
	v_mfma_f32_16x16x32_bf16 v[64:67], v[180:183], v[164:167], v[64:67]
	v_mfma_f32_16x16x32_bf16 v[0:3], v[188:191], v[164:167], v[0:3]
	v_mfma_f32_16x16x32_bf16 v[72:75], v[180:183], v[172:175], v[72:75]
	v_mfma_f32_16x16x32_bf16 v[8:11], v[188:191], v[172:175], v[8:11]
	s_setprio 0
	s_add_i32 s73, 0, 0x18000
	v_add_u32_e32 v108, s73, v234
	s_barrier
	ds_read_b128 v[96:99], v108
	ds_read_b128 v[100:103], v108 offset:1024
	ds_read_b128 v[104:107], v108 offset:2048
	ds_read_b128 v[108:111], v108 offset:3072
	s_add_u32 s36, s42, 0x40000
	s_addc_u32 s37, s43, 0
	s_mov_b32 m0, s47
	v_lshl_add_u64 v[132:133], s[36:37], 0, v[216:217]
	ds_read_b128 v[124:127], v243 offset:32768
	ds_read_b128 v[128:131], v243 offset:33792
	ds_read_b128 v[140:143], v243 offset:34816
	ds_read_b128 v[160:163], v243 offset:35840
	ds_read_b128 v[164:167], v243 offset:36864
	ds_read_b128 v[168:171], v243 offset:37888
	ds_read_b128 v[172:175], v243 offset:38912
	ds_read_b128 v[176:179], v243 offset:39936
	global_load_lds_dwordx4 v[132:133], off
	v_lshl_add_u64 v[132:133], s[36:37], 0, v[212:213]
	s_mov_b32 m0, s48
	s_nop 0
	global_load_lds_dwordx4 v[132:133], off
	s_add_i32 s42, 0, 0x1c000
	v_add_u32_e32 v132, s42, v234
	ds_read_b128 v[180:183], v132
	ds_read_b128 v[184:187], v132 offset:1024
	ds_read_b128 v[188:191], v132 offset:2048
	ds_read_b128 v[192:195], v132 offset:3072
	s_waitcnt lgkmcnt(0)
	s_barrier
	s_setprio 1
	v_mfma_f32_16x16x32_bf16 v[132:135], v[96:99], v[124:127], v[156:159]
	v_mfma_f32_16x16x32_bf16 v[156:159], v[100:103], v[128:131], v[132:135]
	v_mfma_f32_16x16x32_bf16 v[132:135], v[96:99], v[140:143], v[144:147]
	v_mfma_f32_16x16x32_bf16 v[144:147], v[100:103], v[160:163], v[132:135]
	v_mfma_f32_16x16x32_bf16 v[132:135], v[96:99], v[164:167], v[136:139]
	v_mfma_f32_16x16x32_bf16 v[60:63], v[104:107], v[124:127], v[60:63]
	v_mfma_f32_16x16x32_bf16 v[48:51], v[104:107], v[140:143], v[48:51]
	v_mfma_f32_16x16x32_bf16 v[136:139], v[100:103], v[168:171], v[132:135]
	v_mfma_f32_16x16x32_bf16 v[40:43], v[104:107], v[164:167], v[40:43]
	v_mfma_f32_16x16x32_bf16 v[132:135], v[96:99], v[172:175], v[148:151]
	v_mfma_f32_16x16x32_bf16 v[52:55], v[104:107], v[172:175], v[52:55]
	v_mfma_f32_16x16x32_bf16 v[60:63], v[108:111], v[128:131], v[60:63]
	v_mfma_f32_16x16x32_bf16 v[48:51], v[108:111], v[160:163], v[48:51]
	v_mfma_f32_16x16x32_bf16 v[40:43], v[108:111], v[168:171], v[40:43]
	v_mfma_f32_16x16x32_bf16 v[148:151], v[100:103], v[176:179], v[132:135]
	v_mfma_f32_16x16x32_bf16 v[52:55], v[108:111], v[176:179], v[52:55]
	v_mfma_f32_16x16x32_bf16 v[132:135], v[180:183], v[124:127], v[152:155]
	v_mfma_f32_16x16x32_bf16 v[112:115], v[180:183], v[140:143], v[112:115]
	v_mfma_f32_16x16x32_bf16 v[152:155], v[184:187], v[128:131], v[132:135]
	v_mfma_f32_16x16x32_bf16 v[56:59], v[188:191], v[124:127], v[56:59]
	v_mfma_f32_16x16x32_bf16 v[132:135], v[184:187], v[160:163], v[112:115]
	v_mfma_f32_16x16x32_bf16 v[112:115], v[180:183], v[164:167], v[116:119]
	v_mfma_f32_16x16x32_bf16 v[56:59], v[192:195], v[128:131], v[56:59]
	v_mfma_f32_16x16x32_bf16 v[36:39], v[188:191], v[140:143], v[36:39]
	v_mfma_f32_16x16x32_bf16 v[128:131], v[184:187], v[168:171], v[112:115]
	v_mfma_f32_16x16x32_bf16 v[32:35], v[188:191], v[164:167], v[32:35]
	v_mfma_f32_16x16x32_bf16 v[112:115], v[180:183], v[172:175], v[120:123]
	v_mfma_f32_16x16x32_bf16 v[44:47], v[188:191], v[172:175], v[44:47]
	v_mfma_f32_16x16x32_bf16 v[36:39], v[192:195], v[160:163], v[36:39]
	v_mfma_f32_16x16x32_bf16 v[32:35], v[192:195], v[168:171], v[32:35]
	v_mfma_f32_16x16x32_bf16 v[140:143], v[184:187], v[176:179], v[112:115]
	v_mfma_f32_16x16x32_bf16 v[44:47], v[192:195], v[176:179], v[44:47]
	s_setprio 0
	s_barrier
; #define PG8_STAGE(bufoff, gbase, voff) do { _Pragma("unroll") for (int _i = 0; _i < 2; ++_i) \
;         __builtin_amdgcn_global_load_lds((const unsigned*)((const char*)(gbase) + (voff)[_i]), (LAS unsigned*)(lds + (bufoff) + ldsw + _i * 8192), 16, 0, 0); } while (0)
; #define PG8_LDA(dst, b, h) do { _Pragma("unroll") for (int m = 0; m < 4; ++m) _Pragma("unroll") for (int k = 0; k < 2; ++k) dst[m][k] = *(const LAS bf16x8*)(lds + PG8_SA(b, h) + aoff + m * 2048 + k * 1024); } while (0)
; #define PG8_MMA(ai, bj, At, Bt) do { __builtin_amdgcn_s_setprio(1); _Pragma("unroll") for (int m = 0; m < 4; ++m) _Pragma("unroll") for (int n = 0; n < 2; ++n) _Pragma("unroll") for (int k = 0; k < 2; ++k) \
;         acc[ai][bj][m][n] = __builtin_amdgcn_mfma_f32_16x16x32_bf16(Bt[n][k], At[m][k], acc[ai][bj][m][n], 0, 0, 0); __builtin_amdgcn_s_setprio(0); } while (0)
; #define PG8_WAIT_V(n) asm volatile("s_waitcnt vmcnt(" #n ")" ::: "memory")
; #define PG8_WAIT_L(n) asm volatile("s_waitcnt lgkmcnt(" #n ")" ::: "memory")
; #define PG8_BAR __builtin_amdgcn_s_barrier()
; #define PG8_SCHED __builtin_amdgcn_sched_barrier(0)
; template <class Epi>
; __device__ __forceinline__ void gemm_phase(LAS unsigned char* lds, const Gemm g, const StaticOrder& S, const Epi& E) {
;     ...
;             PG8_LDA(At, 1, 1); PG8_STAGE(PG8_SA(1, 0), a3, voffA);
;             PG8_BAR; PG8_WAIT_L(0); PG8_MMA(1, 0, At, B0); PG8_BAR; PG8_SCHED;
;             PG8_STAGE(PG8_SB(1, 1), b3 + hstepB, voffB);
;             PG8_WAIT_V(6); PG8_BAR; PG8_MMA(1, 1, At, B1); PG8_BAR;
	s_nop 1
	ds_read_b128 v[112:115], v243 offset:49152
	ds_read_b128 v[116:119], v243 offset:50176
	ds_read_b128 v[120:123], v243 offset:51200
	ds_read_b128 v[124:127], v243 offset:52224
	ds_read_b128 v[160:163], v243 offset:53248
	ds_read_b128 v[164:167], v243 offset:54272
	ds_read_b128 v[168:171], v243 offset:55296
	ds_read_b128 v[172:175], v243 offset:56320
	s_add_i32 s36, s73, s7
	v_lshl_add_u64 v[254:255], v[196:197], 0, s[16:17]
	s_mov_b32 m0, s36
	s_nop 0
	global_load_lds_dwordx4 v[254:255], off
	v_lshl_add_u64 v[254:255], v[198:199], 0, s[16:17]
	s_add_i32 m0, s36, 0x2000
	s_nop 0
	global_load_lds_dwordx4 v[254:255], off
	s_mov_b32 m0, s57
	v_lshl_add_u64 v[254:255], v[200:201], 0, s[16:17]
	global_load_lds_dwordx4 v[254:255], off
	v_lshl_add_u64 v[254:255], v[202:203], 0, s[16:17]
	s_mov_b32 m0, s58
	s_nop 0
	global_load_lds_dwordx4 v[254:255], off
	s_add_u32 s36, s40, 0x40080
	s_addc_u32 s37, s41, 0
	s_add_i32 s40, s42, s7
	v_lshl_add_u64 v[254:255], s[36:37], 0, v[214:215]
	s_mov_b32 m0, s40
	s_nop 0
	global_load_lds_dwordx4 v[254:255], off
	v_lshl_add_u64 v[254:255], s[36:37], 0, v[210:211]
	s_add_i32 m0, s40, 0x2000
	s_nop 0
	global_load_lds_dwordx4 v[254:255], off
	s_waitcnt vmcnt(6)
	s_waitcnt lgkmcnt(0)
	s_barrier
	s_setprio 1
	v_mfma_f32_16x16x32_bf16 v[92:95], v[96:99], v[112:115], v[92:95]
	v_mfma_f32_16x16x32_bf16 v[28:31], v[104:107], v[112:115], v[28:31]
	v_mfma_f32_16x16x32_bf16 v[80:83], v[96:99], v[120:123], v[80:83]
	v_mfma_f32_16x16x32_bf16 v[16:19], v[104:107], v[120:123], v[16:19]
	v_mfma_f32_16x16x32_bf16 v[76:79], v[96:99], v[160:163], v[76:79]
	v_mfma_f32_16x16x32_bf16 v[12:15], v[104:107], v[160:163], v[12:15]
	v_mfma_f32_16x16x32_bf16 v[84:87], v[96:99], v[168:171], v[84:87]
	v_mfma_f32_16x16x32_bf16 v[20:23], v[104:107], v[168:171], v[20:23]
	v_mfma_f32_16x16x32_bf16 v[92:95], v[100:103], v[116:119], v[92:95]
	v_mfma_f32_16x16x32_bf16 v[28:31], v[108:111], v[116:119], v[28:31]
	v_mfma_f32_16x16x32_bf16 v[80:83], v[100:103], v[124:127], v[80:83]
	v_mfma_f32_16x16x32_bf16 v[16:19], v[108:111], v[124:127], v[16:19]
	v_mfma_f32_16x16x32_bf16 v[76:79], v[100:103], v[164:167], v[76:79]
	v_mfma_f32_16x16x32_bf16 v[12:15], v[108:111], v[164:167], v[12:15]
	v_mfma_f32_16x16x32_bf16 v[84:87], v[100:103], v[172:175], v[84:87]
	v_mfma_f32_16x16x32_bf16 v[20:23], v[108:111], v[172:175], v[20:23]
	v_mfma_f32_16x16x32_bf16 v[88:91], v[180:183], v[112:115], v[88:91]
	v_mfma_f32_16x16x32_bf16 v[24:27], v[188:191], v[112:115], v[24:27]
	v_mfma_f32_16x16x32_bf16 v[68:71], v[180:183], v[120:123], v[68:71]
	v_mfma_f32_16x16x32_bf16 v[4:7], v[188:191], v[120:123], v[4:7]
	v_mfma_f32_16x16x32_bf16 v[64:67], v[180:183], v[160:163], v[64:67]
	v_mfma_f32_16x16x32_bf16 v[0:3], v[188:191], v[160:163], v[0:3]
	v_mfma_f32_16x16x32_bf16 v[72:75], v[180:183], v[168:171], v[72:75]
	v_mfma_f32_16x16x32_bf16 v[8:11], v[188:191], v[168:171], v[8:11]
	v_mfma_f32_16x16x32_bf16 v[88:91], v[184:187], v[116:119], v[88:91]
	v_mfma_f32_16x16x32_bf16 v[24:27], v[192:195], v[116:119], v[24:27]
	v_mfma_f32_16x16x32_bf16 v[68:71], v[184:187], v[124:127], v[68:71]
	v_mfma_f32_16x16x32_bf16 v[4:7], v[192:195], v[124:127], v[4:7]
	v_mfma_f32_16x16x32_bf16 v[64:67], v[184:187], v[164:167], v[64:67]
	v_mfma_f32_16x16x32_bf16 v[0:3], v[192:195], v[164:167], v[0:3]
	v_mfma_f32_16x16x32_bf16 v[72:75], v[184:187], v[172:175], v[72:75]
	v_mfma_f32_16x16x32_bf16 v[8:11], v[192:195], v[172:175], v[8:11]
	s_setprio 0
	s_add_i32 s72, s72, 2
	s_add_u32 s70, s70, 0x100
	s_addc_u32 s71, s71, 0
	s_cmp_gt_u32 s72, 13
	s_mov_b64 s[36:37], s[38:39]
	s_barrier

; #define PG8_STAGE(bufoff, gbase, voff) do { _Pragma("unroll") for (int _i = 0; _i < 2; ++_i) \
;         __builtin_amdgcn_global_load_lds((const unsigned*)((const char*)(gbase) + (voff)[_i]), (LAS unsigned*)(lds + (bufoff) + ldsw + _i * 8192), 16, 0, 0); } while (0)
; #define PG8_LDA(dst, b, h) do { _Pragma("unroll") for (int m = 0; m < 4; ++m) _Pragma("unroll") for (int k = 0; k < 2; ++k) dst[m][k] = *(const LAS bf16x8*)(lds + PG8_SA(b, h) + aoff + m * 2048 + k * 1024); } while (0)
; #define PG8_LDB(dst, b, h) do { _Pragma("unroll") for (int n = 0; n < 2; ++n) _Pragma("unroll") for (int k = 0; k < 2; ++k) dst[n][k] = *(const LAS bf16x8*)(lds + PG8_SB(b, h) + boff + n * 2048 + k * 1024); } while (0)
; #define PG8_MMA(ai, bj, At, Bt) do { __builtin_amdgcn_s_setprio(1); _Pragma("unroll") for (int m = 0; m < 4; ++m) _Pragma("unroll") for (int n = 0; n < 2; ++n) _Pragma("unroll") for (int k = 0; k < 2; ++k) \
;         acc[ai][bj][m][n] = __builtin_amdgcn_mfma_f32_16x16x32_bf16(Bt[n][k], At[m][k], acc[ai][bj][m][n], 0, 0, 0); __builtin_amdgcn_s_setprio(0); } while (0)
; #define PG8_WAIT_L(n) asm volatile("s_waitcnt lgkmcnt(" #n ")" ::: "memory")
; #define PG8_BAR __builtin_amdgcn_s_barrier()
; #define PG8_SCHED __builtin_amdgcn_sched_barrier(0)
; template <class Epi>
; __device__ __forceinline__ void gemm_phase(LAS unsigned char* lds, const Gemm g, const StaticOrder& S, const Epi& E) {
;     ...
;         for (int t = 0; t < nt; t += 2) {
;             const bool last = (t == nt - 2);
;             const char* a1 = cA + (size_t)(t + 1) * kstep;
;             const char* a2 = last ? nA : cA + (size_t)(t + 2) * kstep; const char* b2 = last ? nB : cB + (size_t)(t + 2) * kstep;
;             const char* a3 = a2 + kstep; const char* b3 = b2 + kstep;
;             PG8_LDB(B0, 0, 0); PG8_SCHED; PG8_LDA(At, 0, 0); PG8_STAGE(PG8_SA(1, 1), a1 + hstepA, voffA);
;             PG8_WAIT_L(8); PG8_BAR; PG8_WAIT_L(0); PG8_MMA(0, 0, At, B0); PG8_BAR; PG8_SCHED;
;             PG8_LDB(B1, 0, 1); PG8_STAGE(PG8_SB(0, 0), b2, voffB);
;             PG8_BAR; PG8_WAIT_L(0); PG8_MMA(0, 1, At, B1); PG8_BAR;
;             PG8_LDA(At, 0, 1); PG8_STAGE(PG8_SA(0, 0), a2, voffA);
;             PG8_BAR; PG8_WAIT_L(0); PG8_MMA(1, 0, At, B0); PG8_BAR; PG8_SCHED;
;             PG8_STAGE(PG8_SB(0, 1), b2 + hstepB, voffB);
.LBB0_2041:
	s_add_u32 s44, s20, 0x100
	s_addc_u32 s45, s21, 0
	s_mov_b32 s46, -2
	ds_read_b128 v[140:143], v149
	ds_read_b128 v[152:155], v149 offset:1024
	ds_read_b128 v[156:159], v149 offset:2048
	ds_read_b128 v[160:163], v149 offset:3072
	s_add_u32 s20, s18, 0x100
	s_addc_u32 s21, s19, 0
	s_cmp_eq_u32 s46, 40
	s_cselect_b32 s25, s5, s21
	s_cselect_b32 s24, s4, s20
	s_cselect_b32 s23, s7, s45
	s_cselect_b32 s22, s6, s44
	v_lshl_add_u64 v[144:145], s[18:19], 0, v[132:133]
	s_add_i32 m0, s30, 0xc000
	ds_read_b128 v[164:167], v150
	ds_read_b128 v[168:171], v150 offset:1024
	ds_read_b128 v[172:175], v150 offset:2048
	ds_read_b128 v[176:179], v150 offset:3072
	ds_read_b128 v[180:183], v150 offset:4096
	ds_read_b128 v[184:187], v150 offset:5120
	ds_read_b128 v[188:191], v150 offset:6144
	ds_read_b128 v[192:195], v150 offset:7168
	global_load_lds_dwordx4 v[144:145], off
	v_lshl_add_u64 v[144:145], s[18:19], 0, v[134:135]
	s_add_i32 m0, s30, 0xe000
	s_nop 0
	global_load_lds_dwordx4 v[144:145], off
	ds_read_b128 v[196:199], v151
	ds_read_b128 v[200:203], v151 offset:1024
	ds_read_b128 v[204:207], v151 offset:2048
	ds_read_b128 v[208:211], v151 offset:3072
	s_waitcnt lgkmcnt(0)
	s_barrier
	s_setprio 1
	v_mfma_f32_16x16x32_bf16 v[124:127], v[140:143], v[164:167], 0
	v_mfma_f32_16x16x32_bf16 v[120:123], v[156:159], v[164:167], 0
	v_mfma_f32_16x16x32_bf16 v[112:115], v[140:143], v[172:175], 0
	v_mfma_f32_16x16x32_bf16 v[104:107], v[156:159], v[172:175], 0
	v_mfma_f32_16x16x32_bf16 v[92:95], v[140:143], v[180:183], 0
	v_mfma_f32_16x16x32_bf16 v[88:91], v[156:159], v[180:183], 0
	v_mfma_f32_16x16x32_bf16 v[80:83], v[140:143], v[188:191], 0
	v_mfma_f32_16x16x32_bf16 v[72:75], v[156:159], v[188:191], 0
	v_mfma_f32_16x16x32_bf16 v[124:127], v[152:155], v[168:171], v[124:127]
	v_mfma_f32_16x16x32_bf16 v[120:123], v[160:163], v[168:171], v[120:123]
	v_mfma_f32_16x16x32_bf16 v[112:115], v[152:155], v[176:179], v[112:115]
	v_mfma_f32_16x16x32_bf16 v[104:107], v[160:163], v[176:179], v[104:107]
	v_mfma_f32_16x16x32_bf16 v[92:95], v[152:155], v[184:187], v[92:95]
	v_mfma_f32_16x16x32_bf16 v[88:91], v[160:163], v[184:187], v[88:91]
	v_mfma_f32_16x16x32_bf16 v[80:83], v[152:155], v[192:195], v[80:83]
	v_mfma_f32_16x16x32_bf16 v[72:75], v[160:163], v[192:195], v[72:75]
	v_mfma_f32_16x16x32_bf16 v[116:119], v[196:199], v[164:167], 0
	v_mfma_f32_16x16x32_bf16 v[108:111], v[204:207], v[164:167], 0
	v_mfma_f32_16x16x32_bf16 v[100:103], v[196:199], v[172:175], 0
	v_mfma_f32_16x16x32_bf16 v[96:99], v[204:207], v[172:175], 0
	v_mfma_f32_16x16x32_bf16 v[84:87], v[196:199], v[180:183], 0
	v_mfma_f32_16x16x32_bf16 v[76:79], v[204:207], v[180:183], 0
	v_mfma_f32_16x16x32_bf16 v[68:71], v[196:199], v[188:191], 0
	v_mfma_f32_16x16x32_bf16 v[64:67], v[204:207], v[188:191], 0
	v_mfma_f32_16x16x32_bf16 v[116:119], v[200:203], v[168:171], v[116:119]
	v_mfma_f32_16x16x32_bf16 v[108:111], v[208:211], v[168:171], v[108:111]
	v_mfma_f32_16x16x32_bf16 v[100:103], v[200:203], v[176:179], v[100:103]
	v_mfma_f32_16x16x32_bf16 v[96:99], v[208:211], v[176:179], v[96:99]
	v_mfma_f32_16x16x32_bf16 v[84:87], v[200:203], v[184:187], v[84:87]
	v_mfma_f32_16x16x32_bf16 v[76:79], v[208:211], v[184:187], v[76:79]
	v_mfma_f32_16x16x32_bf16 v[68:71], v[200:203], v[192:195], v[68:71]
	v_mfma_f32_16x16x32_bf16 v[64:67], v[208:211], v[192:195], v[64:67]
	s_setprio 0
	s_barrier
	s_nop 1
	ds_read_b128 v[164:167], v150 offset:16384
	ds_read_b128 v[168:171], v150 offset:17408
	ds_read_b128 v[172:175], v150 offset:18432
	ds_read_b128 v[176:179], v150 offset:19456
	ds_read_b128 v[180:183], v150 offset:20480
	ds_read_b128 v[184:187], v150 offset:21504
	ds_read_b128 v[188:191], v150 offset:22528
	ds_read_b128 v[192:195], v150 offset:23552
	s_add_i32 s18, s38, s29
	v_lshl_add_u64 v[144:145], s[22:23], 0, v[128:129]
	s_mov_b32 m0, s18
	s_nop 0
	global_load_lds_dwordx4 v[144:145], off
	v_lshl_add_u64 v[212:213], s[22:23], 0, v[130:131]
	s_add_i32 m0, s18, 0x2000
	s_nop 0
	global_load_lds_dwordx4 v[212:213], off
	s_mov_b32 m0, s30
	v_lshl_add_u64 v[214:215], s[24:25], 0, v[128:129]
	global_load_lds_dwordx4 v[214:215], off
	v_lshl_add_u64 v[216:217], s[24:25], 0, v[130:131]
	s_mov_b32 m0, s31
	s_nop 0
	global_load_lds_dwordx4 v[216:217], off
	s_add_u32 s18, s22, 0xb0000
	s_addc_u32 s19, s23, 0
	s_add_i32 s47, s39, s29
	v_lshl_add_u64 v[254:255], s[18:19], 0, v[128:129]
	s_mov_b32 m0, s47
	s_nop 0
	global_load_lds_dwordx4 v[254:255], off
	v_lshl_add_u64 v[254:255], s[18:19], 0, v[130:131]
	s_add_i32 m0, s47, 0x2000
	s_nop 0
	global_load_lds_dwordx4 v[254:255], off
	s_waitcnt vmcnt(6)
	s_waitcnt lgkmcnt(0)
	s_barrier
; #define PG8_STAGE(bufoff, gbase, voff) do { _Pragma("unroll") for (int _i = 0; _i < 2; ++_i) \
;         __builtin_amdgcn_global_load_lds((const unsigned*)((const char*)(gbase) + (voff)[_i]), (LAS unsigned*)(lds + (bufoff) + ldsw + _i * 8192), 16, 0, 0); } while (0)
; #define PG8_LDA(dst, b, h) do { _Pragma("unroll") for (int m = 0; m < 4; ++m) _Pragma("unroll") for (int k = 0; k < 2; ++k) dst[m][k] = *(const LAS bf16x8*)(lds + PG8_SA(b, h) + aoff + m * 2048 + k * 1024); } while (0)
; #define PG8_LDB(dst, b, h) do { _Pragma("unroll") for (int n = 0; n < 2; ++n) _Pragma("unroll") for (int k = 0; k < 2; ++k) dst[n][k] = *(const LAS bf16x8*)(lds + PG8_SB(b, h) + boff + n * 2048 + k * 1024); } while (0)
; #define PG8_MMA(ai, bj, At, Bt) do { __builtin_amdgcn_s_setprio(1); _Pragma("unroll") for (int m = 0; m < 4; ++m) _Pragma("unroll") for (int n = 0; n < 2; ++n) _Pragma("unroll") for (int k = 0; k < 2; ++k) \
;         acc[ai][bj][m][n] = __builtin_amdgcn_mfma_f32_16x16x32_bf16(Bt[n][k], At[m][k], acc[ai][bj][m][n], 0, 0, 0); __builtin_amdgcn_s_setprio(0); } while (0)
; #define PG8_WAIT_V(n) asm volatile("s_waitcnt vmcnt(" #n ")" ::: "memory")
; #define PG8_WAIT_L(n) asm volatile("s_waitcnt lgkmcnt(" #n ")" ::: "memory")
; #define PG8_BAR __builtin_amdgcn_s_barrier()
; #define PG8_SCHED __builtin_amdgcn_sched_barrier(0)
; template <class Epi>
; __device__ __forceinline__ void gemm_phase(LAS unsigned char* lds, const Gemm g, const StaticOrder& S, const Epi& E) {
;     ...
;             PG8_BAR; PG8_WAIT_L(0); PG8_MMA(1, 0, At, B0); PG8_BAR; PG8_SCHED;
;             PG8_STAGE(PG8_SB(0, 1), b2 + hstepB, voffB);
;             PG8_WAIT_V(6); PG8_BAR; PG8_MMA(1, 1, At, B1); PG8_BAR;
;             PG8_LDB(B0, 1, 0); PG8_SCHED; PG8_LDA(At, 1, 0); PG8_STAGE(PG8_SA(0, 1), a2 + hstepA, voffA);
;             PG8_WAIT_L(8); PG8_BAR; PG8_WAIT_L(0); PG8_MMA(0, 0, At, B0); PG8_BAR; PG8_SCHED;
;             PG8_LDB(B1, 1, 1); PG8_STAGE(PG8_SB(1, 0), b3, voffB);
;             PG8_BAR; PG8_WAIT_L(0); PG8_MMA(0, 1, At, B1); PG8_BAR;
	s_setprio 1
	v_mfma_f32_16x16x32_bf16 v[60:63], v[140:143], v[164:167], 0
	v_mfma_f32_16x16x32_bf16 v[56:59], v[156:159], v[164:167], 0
	v_mfma_f32_16x16x32_bf16 v[48:51], v[140:143], v[172:175], 0
	v_mfma_f32_16x16x32_bf16 v[40:43], v[156:159], v[172:175], 0
	v_mfma_f32_16x16x32_bf16 v[28:31], v[140:143], v[180:183], 0
	v_mfma_f32_16x16x32_bf16 v[24:27], v[156:159], v[180:183], 0
	v_mfma_f32_16x16x32_bf16 v[16:19], v[140:143], v[188:191], 0
	v_mfma_f32_16x16x32_bf16 v[8:11], v[156:159], v[188:191], 0
	v_mfma_f32_16x16x32_bf16 v[60:63], v[152:155], v[168:171], v[60:63]
	v_mfma_f32_16x16x32_bf16 v[56:59], v[160:163], v[168:171], v[56:59]
	v_mfma_f32_16x16x32_bf16 v[48:51], v[152:155], v[176:179], v[48:51]
	v_mfma_f32_16x16x32_bf16 v[40:43], v[160:163], v[176:179], v[40:43]
	v_mfma_f32_16x16x32_bf16 v[28:31], v[152:155], v[184:187], v[28:31]
	v_mfma_f32_16x16x32_bf16 v[24:27], v[160:163], v[184:187], v[24:27]
	v_mfma_f32_16x16x32_bf16 v[16:19], v[152:155], v[192:195], v[16:19]
	v_mfma_f32_16x16x32_bf16 v[8:11], v[160:163], v[192:195], v[8:11]
	v_mfma_f32_16x16x32_bf16 v[52:55], v[196:199], v[164:167], 0
	v_mfma_f32_16x16x32_bf16 v[44:47], v[204:207], v[164:167], 0
	v_mfma_f32_16x16x32_bf16 v[36:39], v[196:199], v[172:175], 0
	v_mfma_f32_16x16x32_bf16 v[32:35], v[204:207], v[172:175], 0
	v_mfma_f32_16x16x32_bf16 v[20:23], v[196:199], v[180:183], 0
	v_mfma_f32_16x16x32_bf16 v[12:15], v[204:207], v[180:183], 0
	v_mfma_f32_16x16x32_bf16 v[4:7], v[196:199], v[188:191], 0
	v_mfma_f32_16x16x32_bf16 v[0:3], v[204:207], v[188:191], 0
	v_mfma_f32_16x16x32_bf16 v[52:55], v[200:203], v[168:171], v[52:55]
	v_mfma_f32_16x16x32_bf16 v[44:47], v[208:211], v[168:171], v[44:47]
	v_mfma_f32_16x16x32_bf16 v[36:39], v[200:203], v[176:179], v[36:39]
	v_mfma_f32_16x16x32_bf16 v[32:35], v[208:211], v[176:179], v[32:35]
	v_mfma_f32_16x16x32_bf16 v[20:23], v[200:203], v[184:187], v[20:23]
	v_mfma_f32_16x16x32_bf16 v[12:15], v[208:211], v[184:187], v[12:15]
	v_mfma_f32_16x16x32_bf16 v[4:7], v[200:203], v[192:195], v[4:7]
	v_mfma_f32_16x16x32_bf16 v[0:3], v[208:211], v[192:195], v[0:3]
	s_setprio 0
	s_add_i32 s47, 0, 0x18000
	v_add_u32_e32 v160, s47, v147
	s_barrier
	ds_read_b128 v[140:143], v160
	ds_read_b128 v[152:155], v160 offset:1024
	ds_read_b128 v[156:159], v160 offset:2048
	ds_read_b128 v[160:163], v160 offset:3072
	s_add_u32 s18, s24, 0xb0000
	s_addc_u32 s19, s25, 0
	s_mov_b32 m0, s33
	v_lshl_add_u64 v[196:197], s[18:19], 0, v[128:129]
	ds_read_b128 v[164:167], v150 offset:32768
	ds_read_b128 v[168:171], v150 offset:33792
	ds_read_b128 v[172:175], v150 offset:34816
	ds_read_b128 v[176:179], v150 offset:35840
	ds_read_b128 v[180:183], v150 offset:36864
	ds_read_b128 v[184:187], v150 offset:37888
	ds_read_b128 v[188:191], v150 offset:38912
	ds_read_b128 v[192:195], v150 offset:39936
	global_load_lds_dwordx4 v[196:197], off
	v_lshl_add_u64 v[196:197], s[18:19], 0, v[130:131]
	s_mov_b32 m0, s34
	s_nop 0
	global_load_lds_dwordx4 v[196:197], off
	s_add_i32 s24, 0, 0x1c000
	v_add_u32_e32 v208, s24, v147
	ds_read_b128 v[196:199], v208
	ds_read_b128 v[200:203], v208 offset:1024
	ds_read_b128 v[204:207], v208 offset:2048
	ds_read_b128 v[208:211], v208 offset:3072
	s_waitcnt lgkmcnt(0)
	s_barrier
	s_setprio 1
	v_mfma_f32_16x16x32_bf16 v[124:127], v[140:143], v[164:167], v[124:127]
	v_mfma_f32_16x16x32_bf16 v[120:123], v[156:159], v[164:167], v[120:123]
	v_mfma_f32_16x16x32_bf16 v[112:115], v[140:143], v[172:175], v[112:115]
	v_mfma_f32_16x16x32_bf16 v[104:107], v[156:159], v[172:175], v[104:107]
	v_mfma_f32_16x16x32_bf16 v[92:95], v[140:143], v[180:183], v[92:95]
	v_mfma_f32_16x16x32_bf16 v[88:91], v[156:159], v[180:183], v[88:91]
	v_mfma_f32_16x16x32_bf16 v[80:83], v[140:143], v[188:191], v[80:83]
	v_mfma_f32_16x16x32_bf16 v[72:75], v[156:159], v[188:191], v[72:75]
	v_mfma_f32_16x16x32_bf16 v[124:127], v[152:155], v[168:171], v[124:127]
	v_mfma_f32_16x16x32_bf16 v[120:123], v[160:163], v[168:171], v[120:123]
	v_mfma_f32_16x16x32_bf16 v[112:115], v[152:155], v[176:179], v[112:115]
	v_mfma_f32_16x16x32_bf16 v[104:107], v[160:163], v[176:179], v[104:107]
	v_mfma_f32_16x16x32_bf16 v[92:95], v[152:155], v[184:187], v[92:95]
	v_mfma_f32_16x16x32_bf16 v[88:91], v[160:163], v[184:187], v[88:91]
	v_mfma_f32_16x16x32_bf16 v[80:83], v[152:155], v[192:195], v[80:83]
	v_mfma_f32_16x16x32_bf16 v[72:75], v[160:163], v[192:195], v[72:75]
	v_mfma_f32_16x16x32_bf16 v[116:119], v[196:199], v[164:167], v[116:119]
	v_mfma_f32_16x16x32_bf16 v[108:111], v[204:207], v[164:167], v[108:111]
	v_mfma_f32_16x16x32_bf16 v[100:103], v[196:199], v[172:175], v[100:103]
	v_mfma_f32_16x16x32_bf16 v[96:99], v[204:207], v[172:175], v[96:99]
	v_mfma_f32_16x16x32_bf16 v[84:87], v[196:199], v[180:183], v[84:87]
	v_mfma_f32_16x16x32_bf16 v[76:79], v[204:207], v[180:183], v[76:79]
	v_mfma_f32_16x16x32_bf16 v[68:71], v[196:199], v[188:191], v[68:71]
	v_mfma_f32_16x16x32_bf16 v[64:67], v[204:207], v[188:191], v[64:67]
	v_mfma_f32_16x16x32_bf16 v[116:119], v[200:203], v[168:171], v[116:119]
	v_mfma_f32_16x16x32_bf16 v[108:111], v[208:211], v[168:171], v[108:111]
	v_mfma_f32_16x16x32_bf16 v[100:103], v[200:203], v[176:179], v[100:103]
	v_mfma_f32_16x16x32_bf16 v[96:99], v[208:211], v[176:179], v[96:99]
	v_mfma_f32_16x16x32_bf16 v[84:87], v[200:203], v[184:187], v[84:87]
	v_mfma_f32_16x16x32_bf16 v[76:79], v[208:211], v[184:187], v[76:79]
	v_mfma_f32_16x16x32_bf16 v[68:71], v[200:203], v[192:195], v[68:71]
	v_mfma_f32_16x16x32_bf16 v[64:67], v[208:211], v[192:195], v[64:67]
	s_setprio 0
	s_barrier
; #define PG8_STAGE(bufoff, gbase, voff) do { _Pragma("unroll") for (int _i = 0; _i < 2; ++_i) \
;         __builtin_amdgcn_global_load_lds((const unsigned*)((const char*)(gbase) + (voff)[_i]), (LAS unsigned*)(lds + (bufoff) + ldsw + _i * 8192), 16, 0, 0); } while (0)
; #define PG8_LDA(dst, b, h) do { _Pragma("unroll") for (int m = 0; m < 4; ++m) _Pragma("unroll") for (int k = 0; k < 2; ++k) dst[m][k] = *(const LAS bf16x8*)(lds + PG8_SA(b, h) + aoff + m * 2048 + k * 1024); } while (0)
; #define PG8_MMA(ai, bj, At, Bt) do { __builtin_amdgcn_s_setprio(1); _Pragma("unroll") for (int m = 0; m < 4; ++m) _Pragma("unroll") for (int n = 0; n < 2; ++n) _Pragma("unroll") for (int k = 0; k < 2; ++k) \
;         acc[ai][bj][m][n] = __builtin_amdgcn_mfma_f32_16x16x32_bf16(Bt[n][k], At[m][k], acc[ai][bj][m][n], 0, 0, 0); __builtin_amdgcn_s_setprio(0); } while (0)
; #define PG8_WAIT_V(n) asm volatile("s_waitcnt vmcnt(" #n ")" ::: "memory")
; #define PG8_WAIT_L(n) asm volatile("s_waitcnt lgkmcnt(" #n ")" ::: "memory")
; #define PG8_BAR __builtin_amdgcn_s_barrier()
; #define PG8_SCHED __builtin_amdgcn_sched_barrier(0)
; template <class Epi>
; __device__ __forceinline__ void gemm_phase(LAS unsigned char* lds, const Gemm g, const StaticOrder& S, const Epi& E) {
;     ...
;             PG8_LDA(At, 1, 1); PG8_STAGE(PG8_SA(1, 0), a3, voffA);
;             PG8_BAR; PG8_WAIT_L(0); PG8_MMA(1, 0, At, B0); PG8_BAR; PG8_SCHED;
;             PG8_STAGE(PG8_SB(1, 1), b3 + hstepB, voffB);
;             PG8_WAIT_V(6); PG8_BAR; PG8_MMA(1, 1, At, B1); PG8_BAR;
	s_nop 1
	ds_read_b128 v[164:167], v150 offset:49152
	ds_read_b128 v[168:171], v150 offset:50176
	ds_read_b128 v[172:175], v150 offset:51200
	ds_read_b128 v[176:179], v150 offset:52224
	ds_read_b128 v[180:183], v150 offset:53248
	ds_read_b128 v[184:187], v150 offset:54272
	ds_read_b128 v[188:191], v150 offset:55296
	ds_read_b128 v[192:195], v150 offset:56320
	s_add_i32 s18, s47, s29
	v_lshl_add_u64 v[254:255], v[144:145], 0, s[10:11]
	s_mov_b32 m0, s18
	s_nop 0
	global_load_lds_dwordx4 v[254:255], off
	v_lshl_add_u64 v[254:255], v[212:213], 0, s[10:11]
	s_add_i32 m0, s18, 0x2000
	s_nop 0
	global_load_lds_dwordx4 v[254:255], off
	s_mov_b32 m0, s36
	v_lshl_add_u64 v[254:255], v[214:215], 0, s[10:11]
	global_load_lds_dwordx4 v[254:255], off
	v_lshl_add_u64 v[144:145], v[216:217], 0, s[10:11]
	s_mov_b32 m0, s37
	s_nop 0
	global_load_lds_dwordx4 v[144:145], off
	s_add_u32 s18, s22, 0xb0080
	s_addc_u32 s19, s23, 0
	s_add_i32 s22, s24, s29
	v_lshl_add_u64 v[254:255], s[18:19], 0, v[128:129]
	s_mov_b32 m0, s22
	s_nop 0
	global_load_lds_dwordx4 v[254:255], off
	v_lshl_add_u64 v[254:255], s[18:19], 0, v[130:131]
	s_add_i32 m0, s22, 0x2000
	s_nop 0
	global_load_lds_dwordx4 v[254:255], off
	s_waitcnt vmcnt(6)
	s_waitcnt lgkmcnt(0)
	s_barrier
	s_setprio 1
	v_mfma_f32_16x16x32_bf16 v[60:63], v[140:143], v[164:167], v[60:63]
	v_mfma_f32_16x16x32_bf16 v[56:59], v[156:159], v[164:167], v[56:59]
	v_mfma_f32_16x16x32_bf16 v[48:51], v[140:143], v[172:175], v[48:51]
	v_mfma_f32_16x16x32_bf16 v[40:43], v[156:159], v[172:175], v[40:43]
	v_mfma_f32_16x16x32_bf16 v[28:31], v[140:143], v[180:183], v[28:31]
	v_mfma_f32_16x16x32_bf16 v[24:27], v[156:159], v[180:183], v[24:27]
	v_mfma_f32_16x16x32_bf16 v[16:19], v[140:143], v[188:191], v[16:19]
	v_mfma_f32_16x16x32_bf16 v[8:11], v[156:159], v[188:191], v[8:11]
	v_mfma_f32_16x16x32_bf16 v[60:63], v[152:155], v[168:171], v[60:63]
	v_mfma_f32_16x16x32_bf16 v[56:59], v[160:163], v[168:171], v[56:59]
	v_mfma_f32_16x16x32_bf16 v[48:51], v[152:155], v[176:179], v[48:51]
	v_mfma_f32_16x16x32_bf16 v[40:43], v[160:163], v[176:179], v[40:43]
	v_mfma_f32_16x16x32_bf16 v[28:31], v[152:155], v[184:187], v[28:31]
	v_mfma_f32_16x16x32_bf16 v[24:27], v[160:163], v[184:187], v[24:27]
	v_mfma_f32_16x16x32_bf16 v[16:19], v[152:155], v[192:195], v[16:19]
	v_mfma_f32_16x16x32_bf16 v[8:11], v[160:163], v[192:195], v[8:11]
	v_mfma_f32_16x16x32_bf16 v[52:55], v[196:199], v[164:167], v[52:55]
	v_mfma_f32_16x16x32_bf16 v[44:47], v[204:207], v[164:167], v[44:47]
	v_mfma_f32_16x16x32_bf16 v[36:39], v[196:199], v[172:175], v[36:39]
	v_mfma_f32_16x16x32_bf16 v[32:35], v[204:207], v[172:175], v[32:35]
	v_mfma_f32_16x16x32_bf16 v[20:23], v[196:199], v[180:183], v[20:23]
	v_mfma_f32_16x16x32_bf16 v[12:15], v[204:207], v[180:183], v[12:15]
	v_mfma_f32_16x16x32_bf16 v[4:7], v[196:199], v[188:191], v[4:7]
	v_mfma_f32_16x16x32_bf16 v[0:3], v[204:207], v[188:191], v[0:3]
	v_mfma_f32_16x16x32_bf16 v[52:55], v[200:203], v[168:171], v[52:55]
	v_mfma_f32_16x16x32_bf16 v[44:47], v[208:211], v[168:171], v[44:47]
	v_mfma_f32_16x16x32_bf16 v[36:39], v[200:203], v[176:179], v[36:39]
	v_mfma_f32_16x16x32_bf16 v[32:35], v[208:211], v[176:179], v[32:35]
	v_mfma_f32_16x16x32_bf16 v[20:23], v[200:203], v[184:187], v[20:23]
	v_mfma_f32_16x16x32_bf16 v[12:15], v[208:211], v[184:187], v[12:15]
	v_mfma_f32_16x16x32_bf16 v[4:7], v[200:203], v[192:195], v[4:7]
	v_mfma_f32_16x16x32_bf16 v[0:3], v[208:211], v[192:195], v[0:3]
	s_setprio 0
	s_add_i32 s46, s46, 2
	s_add_u32 s44, s44, 0x100
	s_addc_u32 s45, s45, 0
	s_cmp_gt_u32 s46, 41
	s_mov_b64 s[18:19], s[20:21]
	s_barrier
